# v36 + GEMM K-loop back-edge rotation (7.11): counter/pointer SALU moved in front of the closing barrier in 12 K-loops
# speedup vs baseline: 1.0058x; 1.0058x over previous
; #define PG8_STAGE(bufoff, gbase, voff) do { _Pragma("unroll") for (int _i = 0; _i < 2; ++_i) \
;         __builtin_amdgcn_global_load_lds((const unsigned*)((const char*)(gbase) + (voff)[_i]), (LAS unsigned*)(lds + (bufoff) + ldsw + _i * 8192), 16, 0, 0); } while (0)
; #define PG8_LDA(dst, b, h) do { _Pragma("unroll") for (int m = 0; m < 4; ++m) _Pragma("unroll") for (int k = 0; k < 2; ++k) dst[m][k] = *(const LAS bf16x8*)(lds + PG8_SA(b, h) + aoff + m * 2048 + k * 1024); } while (0)
; #define PG8_LDB(dst, b, h) do { _Pragma("unroll") for (int n = 0; n < 2; ++n) _Pragma("unroll") for (int k = 0; k < 2; ++k) dst[n][k] = *(const LAS bf16x8*)(lds + PG8_SB(b, h) + boff + n * 2048 + k * 1024); } while (0)
; #define PG8_MMA(ai, bj, At, Bt) do { __builtin_amdgcn_s_setprio(1); _Pragma("unroll") for (int m = 0; m < 4; ++m) _Pragma("unroll") for (int n = 0; n < 2; ++n) _Pragma("unroll") for (int k = 0; k < 2; ++k) \
;         acc[ai][bj][m][n] = __builtin_amdgcn_mfma_f32_16x16x32_bf16(Bt[n][k], At[m][k], acc[ai][bj][m][n], 0, 0, 0); __builtin_amdgcn_s_setprio(0); } while (0)
; #define PG8_WAIT_V(n) asm volatile("s_waitcnt vmcnt(" #n ")" ::: "memory")
; #define PG8_WAIT_L(n) asm volatile("s_waitcnt lgkmcnt(" #n ")" ::: "memory")
; #define PG8_BAR __builtin_amdgcn_s_barrier()
; #define PG8_SCHED __builtin_amdgcn_sched_barrier(0)
; template <class Epi, class Sched>
; DI void gemm_phase(LAS unsigned char* lds, const Gemm g, const Sched& S, const Epi& E) {
;     ...
;     for (int t = 0; t < nt; t += 2) {
;       const bool last = (t == nt - 2);
;       const char* a1 = cA + (size_t)(t + 1) * kstep;
;       const char* a2 = last ? nA : cA + (size_t)(t + 2) * kstep; const char* b2 = last ? nB : cB + (size_t)(t + 2) * kstep;
;       const char* a3 = a2 + kstep; const char* b3 = b2 + kstep;
;       PG8_LDB(B0, 0, 0); PG8_LDB(B1, 0, 1); PG8_SCHED; PG8_LDA(At, 0, 0); PG8_STAGE(PG8_SA(1, 1), a1 + hstepA, voffA);
;       PG8_WAIT_V(8); PG8_WAIT_L(0); PG8_BAR; PG8_MMA(0, 0, At, B0); PG8_MMA(0, 1, At, B1); PG8_BAR; PG8_SCHED;
;       PG8_LDA(At, 0, 1); PG8_STAGE(PG8_SB(0, 0), b2, voffB); PG8_STAGE(PG8_SB(0, 1), b2 + hstepB, voffB); PG8_STAGE(PG8_SA(0, 0), a2, voffA);
;       PG8_WAIT_V(8); PG8_WAIT_L(0); PG8_BAR; PG8_MMA(1, 0, At, B0); PG8_MMA(1, 1, At, B1); PG8_BAR; PG8_SCHED;
.LBB0_146:
	s_waitcnt lgkmcnt(0)
	ds_read_b128 v[128:131], v183
	ds_read_b128 v[132:135], v183 offset:1024
	ds_read_b128 v[136:139], v183 offset:2048
	ds_read_b128 v[140:143], v183 offset:3072
	ds_read_b128 v[162:165], v184
	ds_read_b128 v[166:169], v184 offset:1024
	ds_read_b128 v[170:173], v184 offset:2048
	ds_read_b128 v[174:177], v184 offset:3072
	s_add_u32 s38, s58, 0xfffc0080
	s_addc_u32 s39, s59, -1
	s_cmp_eq_u32 s65, 12
	s_cselect_b32 s63, s7, s39
	s_cselect_b32 s62, s16, s38
	s_cselect_b32 s61, s17, s64
	s_cselect_b32 s60, s27, s29
	v_lshl_add_u64 v[216:217], s[58:59], 0, v[156:157]
	s_add_i32 m0, s37, 0xc000
	ds_read_b128 v[178:181], v185
	ds_read_b128 v[188:191], v185 offset:1024
	ds_read_b128 v[192:195], v185 offset:2048
	ds_read_b128 v[196:199], v185 offset:3072
	ds_read_b128 v[200:203], v185 offset:4096
	ds_read_b128 v[204:207], v185 offset:5120
	ds_read_b128 v[208:211], v185 offset:6144
	ds_read_b128 v[212:215], v185 offset:7168
	global_load_lds_dwordx4 v[216:217], off
	v_lshl_add_u64 v[216:217], s[58:59], 0, v[154:155]
	s_add_i32 m0, s37, 0xe000
	s_nop 0
	global_load_lds_dwordx4 v[216:217], off
	s_waitcnt vmcnt(8)
	s_waitcnt lgkmcnt(0)
	s_barrier
	s_setprio 1
	s_waitcnt lgkmcnt(0)
	v_mfma_f32_16x16x32_bf16 v[124:127], v[128:131], v[178:181], v[124:127]
	v_mfma_f32_16x16x32_bf16 v[120:123], v[136:139], v[178:181], v[120:123]
	v_mfma_f32_16x16x32_bf16 v[108:111], v[128:131], v[192:195], v[108:111]
	v_mfma_f32_16x16x32_bf16 v[104:107], v[136:139], v[192:195], v[104:107]
	v_mfma_f32_16x16x32_bf16 v[92:95], v[128:131], v[200:203], v[92:95]
	v_mfma_f32_16x16x32_bf16 v[88:91], v[136:139], v[200:203], v[88:91]
	v_mfma_f32_16x16x32_bf16 v[76:79], v[128:131], v[208:211], v[76:79]
	v_mfma_f32_16x16x32_bf16 v[72:75], v[136:139], v[208:211], v[72:75]
	v_mfma_f32_16x16x32_bf16 v[124:127], v[132:135], v[188:191], v[124:127]
	v_mfma_f32_16x16x32_bf16 v[120:123], v[140:143], v[188:191], v[120:123]
	v_mfma_f32_16x16x32_bf16 v[108:111], v[132:135], v[196:199], v[108:111]
	v_mfma_f32_16x16x32_bf16 v[104:107], v[140:143], v[196:199], v[104:107]
	v_mfma_f32_16x16x32_bf16 v[92:95], v[132:135], v[204:207], v[92:95]
	v_mfma_f32_16x16x32_bf16 v[88:91], v[140:143], v[204:207], v[88:91]
	v_mfma_f32_16x16x32_bf16 v[76:79], v[132:135], v[212:215], v[76:79]
	v_mfma_f32_16x16x32_bf16 v[72:75], v[140:143], v[212:215], v[72:75]
	s_setprio 0
	s_setprio 1
	v_mfma_f32_16x16x32_bf16 v[116:119], v[162:165], v[178:181], v[116:119]
	v_mfma_f32_16x16x32_bf16 v[112:115], v[170:173], v[178:181], v[112:115]
	v_mfma_f32_16x16x32_bf16 v[100:103], v[162:165], v[192:195], v[100:103]
	v_mfma_f32_16x16x32_bf16 v[96:99], v[170:173], v[192:195], v[96:99]
	v_mfma_f32_16x16x32_bf16 v[84:87], v[162:165], v[200:203], v[84:87]
	v_mfma_f32_16x16x32_bf16 v[80:83], v[170:173], v[200:203], v[80:83]
	v_mfma_f32_16x16x32_bf16 v[68:71], v[162:165], v[208:211], v[68:71]
	v_mfma_f32_16x16x32_bf16 v[64:67], v[170:173], v[208:211], v[64:67]
	v_mfma_f32_16x16x32_bf16 v[116:119], v[166:169], v[188:191], v[116:119]
	v_mfma_f32_16x16x32_bf16 v[112:115], v[174:177], v[188:191], v[112:115]
	v_mfma_f32_16x16x32_bf16 v[100:103], v[166:169], v[196:199], v[100:103]
	v_mfma_f32_16x16x32_bf16 v[96:99], v[174:177], v[196:199], v[96:99]
	v_mfma_f32_16x16x32_bf16 v[84:87], v[166:169], v[204:207], v[84:87]
	v_mfma_f32_16x16x32_bf16 v[80:83], v[174:177], v[204:207], v[80:83]
	v_mfma_f32_16x16x32_bf16 v[68:71], v[166:169], v[212:215], v[68:71]
	v_mfma_f32_16x16x32_bf16 v[64:67], v[174:177], v[212:215], v[64:67]
	s_setprio 0
	s_barrier
	s_add_i32 s38, s91, s76
	v_lshl_add_u64 v[216:217], s[60:61], 0, v[146:147]
	s_mov_b32 m0, s38
	ds_read_b128 v[178:181], v185 offset:16384
	ds_read_b128 v[188:191], v185 offset:17408
	ds_read_b128 v[192:195], v185 offset:18432
	ds_read_b128 v[196:199], v185 offset:19456
	ds_read_b128 v[200:203], v185 offset:20480
	ds_read_b128 v[204:207], v185 offset:21504
	ds_read_b128 v[208:211], v185 offset:22528
	ds_read_b128 v[212:215], v185 offset:23552
	global_load_lds_dwordx4 v[216:217], off
	s_add_i32 m0, s38, 0x2000
	s_add_u32 s66, s60, 0x40000
	v_lshl_add_u64 v[218:219], s[60:61], 0, v[150:151]
	s_addc_u32 s67, s61, 0
	s_add_i32 s38, s92, s76
	global_load_lds_dwordx4 v[218:219], off
	v_lshl_add_u64 v[220:221], s[66:67], 0, v[146:147]
	s_mov_b32 m0, s38
	v_lshl_add_u64 v[222:223], s[62:63], 0, v[148:149]
	global_load_lds_dwordx4 v[220:221], off
	v_lshl_add_u64 v[220:221], s[66:67], 0, v[150:151]
	s_add_i32 m0, s38, 0x2000
	s_nop 0
	global_load_lds_dwordx4 v[220:221], off
	v_lshl_add_u64 v[220:221], s[62:63], 0, v[144:145]
	s_mov_b32 m0, s37
	s_nop 0
	global_load_lds_dwordx4 v[220:221], off
	s_mov_b32 m0, s77
	s_nop 0
	global_load_lds_dwordx4 v[222:223], off
	s_waitcnt vmcnt(8)
	s_waitcnt lgkmcnt(0)
	s_barrier
; #define PG8_STAGE(bufoff, gbase, voff) do { _Pragma("unroll") for (int _i = 0; _i < 2; ++_i) \
;         __builtin_amdgcn_global_load_lds((const unsigned*)((const char*)(gbase) + (voff)[_i]), (LAS unsigned*)(lds + (bufoff) + ldsw + _i * 8192), 16, 0, 0); } while (0)
; #define PG8_LDA(dst, b, h) do { _Pragma("unroll") for (int m = 0; m < 4; ++m) _Pragma("unroll") for (int k = 0; k < 2; ++k) dst[m][k] = *(const LAS bf16x8*)(lds + PG8_SA(b, h) + aoff + m * 2048 + k * 1024); } while (0)
; #define PG8_LDB(dst, b, h) do { _Pragma("unroll") for (int n = 0; n < 2; ++n) _Pragma("unroll") for (int k = 0; k < 2; ++k) dst[n][k] = *(const LAS bf16x8*)(lds + PG8_SB(b, h) + boff + n * 2048 + k * 1024); } while (0)
; #define PG8_MMA(ai, bj, At, Bt) do { __builtin_amdgcn_s_setprio(1); _Pragma("unroll") for (int m = 0; m < 4; ++m) _Pragma("unroll") for (int n = 0; n < 2; ++n) _Pragma("unroll") for (int k = 0; k < 2; ++k) \
;         acc[ai][bj][m][n] = __builtin_amdgcn_mfma_f32_16x16x32_bf16(Bt[n][k], At[m][k], acc[ai][bj][m][n], 0, 0, 0); __builtin_amdgcn_s_setprio(0); } while (0)
; #define PG8_WAIT_V(n) asm volatile("s_waitcnt vmcnt(" #n ")" ::: "memory")
; #define PG8_WAIT_L(n) asm volatile("s_waitcnt lgkmcnt(" #n ")" ::: "memory")
; #define PG8_BAR __builtin_amdgcn_s_barrier()
; #define PG8_SCHED __builtin_amdgcn_sched_barrier(0)
; template <class Epi, class Sched>
; DI void gemm_phase(LAS unsigned char* lds, const Gemm g, const Sched& S, const Epi& E) {
;     ...
;       PG8_WAIT_V(8); PG8_WAIT_L(0); PG8_BAR; PG8_MMA(1, 0, At, B0); PG8_MMA(1, 1, At, B1); PG8_BAR; PG8_SCHED;
;       PG8_LDB(B0, 1, 0); PG8_LDB(B1, 1, 1); PG8_SCHED; PG8_LDA(At, 1, 0); PG8_STAGE(PG8_SA(0, 1), a2 + hstepA, voffA);
;       PG8_WAIT_V(8); PG8_WAIT_L(0); PG8_BAR; PG8_MMA(0, 0, At, B0); PG8_MMA(0, 1, At, B1); PG8_BAR; PG8_SCHED;
	s_setprio 1
	s_waitcnt lgkmcnt(0)
	v_mfma_f32_16x16x32_bf16 v[60:63], v[128:131], v[178:181], v[60:63]
	v_mfma_f32_16x16x32_bf16 v[56:59], v[136:139], v[178:181], v[56:59]
	v_mfma_f32_16x16x32_bf16 v[44:47], v[128:131], v[192:195], v[44:47]
	v_mfma_f32_16x16x32_bf16 v[40:43], v[136:139], v[192:195], v[40:43]
	v_mfma_f32_16x16x32_bf16 v[28:31], v[128:131], v[200:203], v[28:31]
	v_mfma_f32_16x16x32_bf16 v[24:27], v[136:139], v[200:203], v[24:27]
	v_mfma_f32_16x16x32_bf16 v[12:15], v[128:131], v[208:211], v[12:15]
	v_mfma_f32_16x16x32_bf16 v[8:11], v[136:139], v[208:211], v[8:11]
	v_mfma_f32_16x16x32_bf16 v[60:63], v[132:135], v[188:191], v[60:63]
	v_mfma_f32_16x16x32_bf16 v[56:59], v[140:143], v[188:191], v[56:59]
	v_mfma_f32_16x16x32_bf16 v[44:47], v[132:135], v[196:199], v[44:47]
	v_mfma_f32_16x16x32_bf16 v[40:43], v[140:143], v[196:199], v[40:43]
	v_mfma_f32_16x16x32_bf16 v[28:31], v[132:135], v[204:207], v[28:31]
	v_mfma_f32_16x16x32_bf16 v[24:27], v[140:143], v[204:207], v[24:27]
	v_mfma_f32_16x16x32_bf16 v[12:15], v[132:135], v[212:215], v[12:15]
	v_mfma_f32_16x16x32_bf16 v[8:11], v[140:143], v[212:215], v[8:11]
	s_setprio 0
	s_setprio 1
	v_mfma_f32_16x16x32_bf16 v[52:55], v[162:165], v[178:181], v[52:55]
	v_mfma_f32_16x16x32_bf16 v[48:51], v[170:173], v[178:181], v[48:51]
	v_mfma_f32_16x16x32_bf16 v[36:39], v[162:165], v[192:195], v[36:39]
	v_mfma_f32_16x16x32_bf16 v[32:35], v[170:173], v[192:195], v[32:35]
	v_mfma_f32_16x16x32_bf16 v[20:23], v[162:165], v[200:203], v[20:23]
	v_mfma_f32_16x16x32_bf16 v[16:19], v[170:173], v[200:203], v[16:19]
	v_mfma_f32_16x16x32_bf16 v[4:7], v[162:165], v[208:211], v[4:7]
	v_mfma_f32_16x16x32_bf16 v[0:3], v[170:173], v[208:211], v[0:3]
	v_mfma_f32_16x16x32_bf16 v[52:55], v[166:169], v[188:191], v[52:55]
	v_mfma_f32_16x16x32_bf16 v[48:51], v[174:177], v[188:191], v[48:51]
	v_mfma_f32_16x16x32_bf16 v[36:39], v[166:169], v[196:199], v[36:39]
	v_mfma_f32_16x16x32_bf16 v[32:35], v[174:177], v[196:199], v[32:35]
	v_mfma_f32_16x16x32_bf16 v[20:23], v[166:169], v[204:207], v[20:23]
	v_mfma_f32_16x16x32_bf16 v[16:19], v[174:177], v[204:207], v[16:19]
	v_mfma_f32_16x16x32_bf16 v[4:7], v[166:169], v[212:215], v[4:7]
	v_mfma_f32_16x16x32_bf16 v[0:3], v[174:177], v[212:215], v[0:3]
	s_setprio 0
	s_barrier
	s_add_i32 s38, 0, 0x18000
	s_add_i32 s39, 0, 0x1c000
	v_add_u32_e32 v140, s38, v182
	v_add_u32_e32 v152, s39, v182
	ds_read_b128 v[128:131], v140
	ds_read_b128 v[132:135], v140 offset:1024
	ds_read_b128 v[136:139], v140 offset:2048
	ds_read_b128 v[140:143], v140 offset:3072
	ds_read_b128 v[162:165], v152
	ds_read_b128 v[166:169], v152 offset:1024
	ds_read_b128 v[170:173], v152 offset:2048
	ds_read_b128 v[174:177], v152 offset:3072
	s_add_u32 s62, s62, 0x40000
	s_addc_u32 s63, s63, 0
	s_mov_b32 m0, s80
	v_lshl_add_u64 v[226:227], s[62:63], 0, v[144:145]
	ds_read_b128 v[178:181], v185 offset:32768
	ds_read_b128 v[188:191], v185 offset:33792
	ds_read_b128 v[192:195], v185 offset:34816
	ds_read_b128 v[196:199], v185 offset:35840
	ds_read_b128 v[200:203], v185 offset:36864
	ds_read_b128 v[204:207], v185 offset:37888
	ds_read_b128 v[208:211], v185 offset:38912
	ds_read_b128 v[212:215], v185 offset:39936
	global_load_lds_dwordx4 v[226:227], off
	v_lshl_add_u64 v[226:227], s[62:63], 0, v[148:149]
	s_mov_b32 m0, s81
	s_nop 0
	global_load_lds_dwordx4 v[226:227], off
	s_waitcnt vmcnt(8)
	s_waitcnt lgkmcnt(0)
	s_barrier
	s_setprio 1
	s_waitcnt lgkmcnt(0)
	v_mfma_f32_16x16x32_bf16 v[124:127], v[128:131], v[178:181], v[124:127]
	v_mfma_f32_16x16x32_bf16 v[120:123], v[136:139], v[178:181], v[120:123]
	v_mfma_f32_16x16x32_bf16 v[108:111], v[128:131], v[192:195], v[108:111]
	v_mfma_f32_16x16x32_bf16 v[104:107], v[136:139], v[192:195], v[104:107]
	v_mfma_f32_16x16x32_bf16 v[92:95], v[128:131], v[200:203], v[92:95]
	v_mfma_f32_16x16x32_bf16 v[88:91], v[136:139], v[200:203], v[88:91]
	v_mfma_f32_16x16x32_bf16 v[76:79], v[128:131], v[208:211], v[76:79]
	v_mfma_f32_16x16x32_bf16 v[72:75], v[136:139], v[208:211], v[72:75]
	v_mfma_f32_16x16x32_bf16 v[124:127], v[132:135], v[188:191], v[124:127]
	v_mfma_f32_16x16x32_bf16 v[120:123], v[140:143], v[188:191], v[120:123]
	v_mfma_f32_16x16x32_bf16 v[108:111], v[132:135], v[196:199], v[108:111]
	v_mfma_f32_16x16x32_bf16 v[104:107], v[140:143], v[196:199], v[104:107]
	v_mfma_f32_16x16x32_bf16 v[92:95], v[132:135], v[204:207], v[92:95]
	v_mfma_f32_16x16x32_bf16 v[88:91], v[140:143], v[204:207], v[88:91]
	v_mfma_f32_16x16x32_bf16 v[76:79], v[132:135], v[212:215], v[76:79]
	v_mfma_f32_16x16x32_bf16 v[72:75], v[140:143], v[212:215], v[72:75]
	s_setprio 0
	s_setprio 1
	v_mfma_f32_16x16x32_bf16 v[116:119], v[162:165], v[178:181], v[116:119]
	v_mfma_f32_16x16x32_bf16 v[112:115], v[170:173], v[178:181], v[112:115]
	v_mfma_f32_16x16x32_bf16 v[100:103], v[162:165], v[192:195], v[100:103]
	v_mfma_f32_16x16x32_bf16 v[96:99], v[170:173], v[192:195], v[96:99]
	v_mfma_f32_16x16x32_bf16 v[84:87], v[162:165], v[200:203], v[84:87]
	v_mfma_f32_16x16x32_bf16 v[80:83], v[170:173], v[200:203], v[80:83]
	v_mfma_f32_16x16x32_bf16 v[68:71], v[162:165], v[208:211], v[68:71]
	v_mfma_f32_16x16x32_bf16 v[64:67], v[170:173], v[208:211], v[64:67]
	v_mfma_f32_16x16x32_bf16 v[116:119], v[166:169], v[188:191], v[116:119]
	v_mfma_f32_16x16x32_bf16 v[112:115], v[174:177], v[188:191], v[112:115]
	v_mfma_f32_16x16x32_bf16 v[100:103], v[166:169], v[196:199], v[100:103]
	v_mfma_f32_16x16x32_bf16 v[96:99], v[174:177], v[196:199], v[96:99]
	v_mfma_f32_16x16x32_bf16 v[84:87], v[166:169], v[204:207], v[84:87]
	v_mfma_f32_16x16x32_bf16 v[80:83], v[174:177], v[204:207], v[80:83]
	v_mfma_f32_16x16x32_bf16 v[68:71], v[166:169], v[212:215], v[68:71]
	v_mfma_f32_16x16x32_bf16 v[64:67], v[174:177], v[212:215], v[64:67]
	s_setprio 0
	s_barrier
; #define PG8_STAGE(bufoff, gbase, voff) do { _Pragma("unroll") for (int _i = 0; _i < 2; ++_i) \
;         __builtin_amdgcn_global_load_lds((const unsigned*)((const char*)(gbase) + (voff)[_i]), (LAS unsigned*)(lds + (bufoff) + ldsw + _i * 8192), 16, 0, 0); } while (0)
; #define PG8_LDA(dst, b, h) do { _Pragma("unroll") for (int m = 0; m < 4; ++m) _Pragma("unroll") for (int k = 0; k < 2; ++k) dst[m][k] = *(const LAS bf16x8*)(lds + PG8_SA(b, h) + aoff + m * 2048 + k * 1024); } while (0)
; #define PG8_MMA(ai, bj, At, Bt) do { __builtin_amdgcn_s_setprio(1); _Pragma("unroll") for (int m = 0; m < 4; ++m) _Pragma("unroll") for (int n = 0; n < 2; ++n) _Pragma("unroll") for (int k = 0; k < 2; ++k) \
;         acc[ai][bj][m][n] = __builtin_amdgcn_mfma_f32_16x16x32_bf16(Bt[n][k], At[m][k], acc[ai][bj][m][n], 0, 0, 0); __builtin_amdgcn_s_setprio(0); } while (0)
; #define PG8_WAIT_V(n) asm volatile("s_waitcnt vmcnt(" #n ")" ::: "memory")
; #define PG8_WAIT_L(n) asm volatile("s_waitcnt lgkmcnt(" #n ")" ::: "memory")
; #define PG8_BAR __builtin_amdgcn_s_barrier()
; #define PG8_SCHED __builtin_amdgcn_sched_barrier(0)
; template <class Epi, class Sched>
; DI void gemm_phase(LAS unsigned char* lds, const Gemm g, const Sched& S, const Epi& E) {
;     ...
;       PG8_LDA(At, 1, 1); PG8_STAGE(PG8_SB(1, 0), b3, voffB); PG8_STAGE(PG8_SB(1, 1), b3 + hstepB, voffB); PG8_STAGE(PG8_SA(1, 0), a3, voffA);
;       PG8_WAIT_V(8); PG8_WAIT_L(0); PG8_BAR; PG8_MMA(1, 0, At, B0); PG8_MMA(1, 1, At, B1); PG8_BAR; PG8_SCHED;
;     }
;     if (wr == 0) PG8_BAR;
	s_add_i32 s38, s38, s76
	v_lshl_add_u64 v[216:217], v[216:217], 0, s[10:11]
	s_mov_b32 m0, s38
	ds_read_b128 v[178:181], v185 offset:49152
	ds_read_b128 v[188:191], v185 offset:50176
	ds_read_b128 v[192:195], v185 offset:51200
	ds_read_b128 v[196:199], v185 offset:52224
	ds_read_b128 v[200:203], v185 offset:53248
	ds_read_b128 v[204:207], v185 offset:54272
	ds_read_b128 v[208:211], v185 offset:55296
	ds_read_b128 v[212:215], v185 offset:56320
	global_load_lds_dwordx4 v[216:217], off
	s_add_i32 m0, s38, 0x2000
	s_add_u32 s60, s60, 0x40080
	v_lshl_add_u64 v[216:217], v[218:219], 0, s[10:11]
	s_addc_u32 s61, s61, 0
	s_add_i32 s38, s39, s76
	global_load_lds_dwordx4 v[216:217], off
	v_lshl_add_u64 v[216:217], s[60:61], 0, v[146:147]
	s_mov_b32 m0, s38
	s_nop 0
	global_load_lds_dwordx4 v[216:217], off
	v_lshl_add_u64 v[216:217], s[60:61], 0, v[150:151]
	s_add_i32 m0, s38, 0x2000
	s_nop 0
	global_load_lds_dwordx4 v[216:217], off
	v_lshl_add_u64 v[216:217], v[220:221], 0, s[10:11]
	s_mov_b32 m0, s85
	s_nop 0
	global_load_lds_dwordx4 v[216:217], off
	v_lshl_add_u64 v[216:217], v[222:223], 0, s[10:11]
	s_mov_b32 m0, s86
	s_nop 0
	global_load_lds_dwordx4 v[216:217], off
	s_waitcnt vmcnt(8)
	s_waitcnt lgkmcnt(0)
	s_barrier
	s_setprio 1
	s_waitcnt lgkmcnt(0)
	v_mfma_f32_16x16x32_bf16 v[60:63], v[128:131], v[178:181], v[60:63]
	v_mfma_f32_16x16x32_bf16 v[56:59], v[136:139], v[178:181], v[56:59]
	v_mfma_f32_16x16x32_bf16 v[44:47], v[128:131], v[192:195], v[44:47]
	v_mfma_f32_16x16x32_bf16 v[40:43], v[136:139], v[192:195], v[40:43]
	v_mfma_f32_16x16x32_bf16 v[28:31], v[128:131], v[200:203], v[28:31]
	v_mfma_f32_16x16x32_bf16 v[24:27], v[136:139], v[200:203], v[24:27]
	v_mfma_f32_16x16x32_bf16 v[12:15], v[128:131], v[208:211], v[12:15]
	v_mfma_f32_16x16x32_bf16 v[8:11], v[136:139], v[208:211], v[8:11]
	v_mfma_f32_16x16x32_bf16 v[60:63], v[132:135], v[188:191], v[60:63]
	v_mfma_f32_16x16x32_bf16 v[56:59], v[140:143], v[188:191], v[56:59]
	v_mfma_f32_16x16x32_bf16 v[44:47], v[132:135], v[196:199], v[44:47]
	v_mfma_f32_16x16x32_bf16 v[40:43], v[140:143], v[196:199], v[40:43]
	v_mfma_f32_16x16x32_bf16 v[28:31], v[132:135], v[204:207], v[28:31]
	v_mfma_f32_16x16x32_bf16 v[24:27], v[140:143], v[204:207], v[24:27]
	v_mfma_f32_16x16x32_bf16 v[12:15], v[132:135], v[212:215], v[12:15]
	v_mfma_f32_16x16x32_bf16 v[8:11], v[140:143], v[212:215], v[8:11]
	s_setprio 0
	s_setprio 1
	v_mfma_f32_16x16x32_bf16 v[52:55], v[162:165], v[178:181], v[52:55]
	v_mfma_f32_16x16x32_bf16 v[48:51], v[170:173], v[178:181], v[48:51]
	v_mfma_f32_16x16x32_bf16 v[36:39], v[162:165], v[192:195], v[36:39]
	v_mfma_f32_16x16x32_bf16 v[32:35], v[170:173], v[192:195], v[32:35]
	v_mfma_f32_16x16x32_bf16 v[20:23], v[162:165], v[200:203], v[20:23]
	v_mfma_f32_16x16x32_bf16 v[16:19], v[170:173], v[200:203], v[16:19]
	v_mfma_f32_16x16x32_bf16 v[4:7], v[162:165], v[208:211], v[4:7]
	v_mfma_f32_16x16x32_bf16 v[0:3], v[170:173], v[208:211], v[0:3]
	v_mfma_f32_16x16x32_bf16 v[52:55], v[166:169], v[188:191], v[52:55]
	v_mfma_f32_16x16x32_bf16 v[48:51], v[174:177], v[188:191], v[48:51]
	v_mfma_f32_16x16x32_bf16 v[36:39], v[166:169], v[196:199], v[36:39]
	v_mfma_f32_16x16x32_bf16 v[32:35], v[174:177], v[196:199], v[32:35]
	v_mfma_f32_16x16x32_bf16 v[20:23], v[166:169], v[204:207], v[20:23]
	v_mfma_f32_16x16x32_bf16 v[16:19], v[174:177], v[204:207], v[16:19]
	v_mfma_f32_16x16x32_bf16 v[4:7], v[166:169], v[212:215], v[4:7]
	v_mfma_f32_16x16x32_bf16 v[0:3], v[174:177], v[212:215], v[0:3]
	s_setprio 0
	s_add_i32 s65, s65, 2
	s_add_u32 s29, s29, 0x100
	s_addc_u32 s64, s64, 0
	s_add_u32 s58, s58, 0x100
	s_addc_u32 s59, s59, 0
	s_cmp_gt_u32 s65, 13
	s_barrier
	s_cbranch_scc0 .LBB0_146
	s_and_b64 vcc, exec, s[12:13]
	s_cbranch_vccz .LBB0_149
	s_barrier

; #define PG8_STAGE(bufoff, gbase, voff) do { _Pragma("unroll") for (int _i = 0; _i < 2; ++_i) \
;         __builtin_amdgcn_global_load_lds((const unsigned*)((const char*)(gbase) + (voff)[_i]), (LAS unsigned*)(lds + (bufoff) + ldsw + _i * 8192), 16, 0, 0); } while (0)
; #define PG8_LDA(dst, b, h) do { _Pragma("unroll") for (int m = 0; m < 4; ++m) _Pragma("unroll") for (int k = 0; k < 2; ++k) dst[m][k] = *(const LAS bf16x8*)(lds + PG8_SA(b, h) + aoff + m * 2048 + k * 1024); } while (0)
; #define PG8_LDB(dst, b, h) do { _Pragma("unroll") for (int n = 0; n < 2; ++n) _Pragma("unroll") for (int k = 0; k < 2; ++k) dst[n][k] = *(const LAS bf16x8*)(lds + PG8_SB(b, h) + boff + n * 2048 + k * 1024); } while (0)
; #define PG8_MMA(ai, bj, At, Bt) do { __builtin_amdgcn_s_setprio(1); _Pragma("unroll") for (int m = 0; m < 4; ++m) _Pragma("unroll") for (int n = 0; n < 2; ++n) _Pragma("unroll") for (int k = 0; k < 2; ++k) \
;         acc[ai][bj][m][n] = __builtin_amdgcn_mfma_f32_16x16x32_bf16(Bt[n][k], At[m][k], acc[ai][bj][m][n], 0, 0, 0); __builtin_amdgcn_s_setprio(0); } while (0)
; #define PG8_WAIT_V(n) asm volatile("s_waitcnt vmcnt(" #n ")" ::: "memory")
; #define PG8_WAIT_L(n) asm volatile("s_waitcnt lgkmcnt(" #n ")" ::: "memory")
; #define PG8_BAR __builtin_amdgcn_s_barrier()
; #define PG8_SCHED __builtin_amdgcn_sched_barrier(0)
; template <class Epi, class Sched>
; DI void gemm_phase(LAS unsigned char* lds, const Gemm g, const Sched& S, const Epi& E) {
;     ...
;     for (int t = 0; t < nt; t += 2) {
;       const bool last = (t == nt - 2);
;       const char* a1 = cA + (size_t)(t + 1) * kstep;
;       const char* a2 = last ? nA : cA + (size_t)(t + 2) * kstep; const char* b2 = last ? nB : cB + (size_t)(t + 2) * kstep;
;       const char* a3 = a2 + kstep; const char* b3 = b2 + kstep;
;       PG8_LDB(B0, 0, 0); PG8_LDB(B1, 0, 1); PG8_SCHED; PG8_LDA(At, 0, 0); PG8_STAGE(PG8_SA(1, 1), a1 + hstepA, voffA);
;       PG8_WAIT_V(8); PG8_WAIT_L(0); PG8_BAR; PG8_MMA(0, 0, At, B0); PG8_MMA(0, 1, At, B1); PG8_BAR; PG8_SCHED;
;       PG8_LDA(At, 0, 1); PG8_STAGE(PG8_SB(0, 0), b2, voffB); PG8_STAGE(PG8_SB(0, 1), b2 + hstepB, voffB); PG8_STAGE(PG8_SA(0, 0), a2, voffA);
;       PG8_WAIT_V(8); PG8_WAIT_L(0); PG8_BAR; PG8_MMA(1, 0, At, B0); PG8_MMA(1, 1, At, B1); PG8_BAR; PG8_SCHED;
.LBB0_703:
	ds_read_b128 v[146:149], v153
	ds_read_b128 v[166:169], v153 offset:1024
	ds_read_b128 v[170:173], v153 offset:2048
	ds_read_b128 v[174:177], v153 offset:3072
	ds_read_b128 v[178:181], v154
	ds_read_b128 v[182:185], v154 offset:1024
	ds_read_b128 v[186:189], v154 offset:2048
	ds_read_b128 v[190:193], v154 offset:3072
	s_add_u32 s10, s8, 0xfffc0080
	s_addc_u32 s11, s9, -1
	s_cmp_eq_u32 s87, 12
	s_cselect_b32 s35, s7, s11
	s_cselect_b32 s34, s14, s10
	s_cselect_b32 s11, s25, s86
	s_cselect_b32 s10, s27, s85
	v_lshl_add_u64 v[128:129], s[8:9], 0, v[140:141]
	s_add_i32 m0, s13, 0xc000
	ds_read_b128 v[194:197], v155
	ds_read_b128 v[198:201], v155 offset:1024
	ds_read_b128 v[202:205], v155 offset:2048
	ds_read_b128 v[206:209], v155 offset:3072
	ds_read_b128 v[210:213], v155 offset:4096
	ds_read_b128 v[214:217], v155 offset:5120
	ds_read_b128 v[218:221], v155 offset:6144
	ds_read_b128 v[226:229], v155 offset:7168
	global_load_lds_dwordx4 v[128:129], off
	v_lshl_add_u64 v[128:129], s[8:9], 0, v[138:139]
	s_add_i32 m0, s13, 0xe000
	s_nop 0
	global_load_lds_dwordx4 v[128:129], off
	s_waitcnt vmcnt(8)
	s_waitcnt lgkmcnt(0)
	s_barrier
	s_setprio 1
	s_waitcnt lgkmcnt(0)
	v_mfma_f32_16x16x32_bf16 v[124:127], v[146:149], v[194:197], v[124:127]
	v_mfma_f32_16x16x32_bf16 v[120:123], v[170:173], v[194:197], v[120:123]
	v_mfma_f32_16x16x32_bf16 v[104:107], v[146:149], v[202:205], v[104:107]
	v_mfma_f32_16x16x32_bf16 v[108:111], v[170:173], v[202:205], v[108:111]
	v_mfma_f32_16x16x32_bf16 v[88:91], v[146:149], v[210:213], v[88:91]
	v_mfma_f32_16x16x32_bf16 v[92:95], v[170:173], v[210:213], v[92:95]
	v_mfma_f32_16x16x32_bf16 v[72:75], v[146:149], v[218:221], v[72:75]
	v_mfma_f32_16x16x32_bf16 v[76:79], v[170:173], v[218:221], v[76:79]
	v_mfma_f32_16x16x32_bf16 v[124:127], v[166:169], v[198:201], v[124:127]
	v_mfma_f32_16x16x32_bf16 v[120:123], v[174:177], v[198:201], v[120:123]
	v_mfma_f32_16x16x32_bf16 v[104:107], v[166:169], v[206:209], v[104:107]
	v_mfma_f32_16x16x32_bf16 v[108:111], v[174:177], v[206:209], v[108:111]
	v_mfma_f32_16x16x32_bf16 v[88:91], v[166:169], v[214:217], v[88:91]
	v_mfma_f32_16x16x32_bf16 v[92:95], v[174:177], v[214:217], v[92:95]
	v_mfma_f32_16x16x32_bf16 v[72:75], v[166:169], v[226:229], v[72:75]
	v_mfma_f32_16x16x32_bf16 v[76:79], v[174:177], v[226:229], v[76:79]
	s_setprio 0
	s_setprio 1
	v_mfma_f32_16x16x32_bf16 v[116:119], v[178:181], v[194:197], v[116:119]
	v_mfma_f32_16x16x32_bf16 v[112:115], v[186:189], v[194:197], v[112:115]
	v_mfma_f32_16x16x32_bf16 v[100:103], v[178:181], v[202:205], v[100:103]
	v_mfma_f32_16x16x32_bf16 v[96:99], v[186:189], v[202:205], v[96:99]
	v_mfma_f32_16x16x32_bf16 v[84:87], v[178:181], v[210:213], v[84:87]
	v_mfma_f32_16x16x32_bf16 v[80:83], v[186:189], v[210:213], v[80:83]
	v_mfma_f32_16x16x32_bf16 v[68:71], v[178:181], v[218:221], v[68:71]
	v_mfma_f32_16x16x32_bf16 v[64:67], v[186:189], v[218:221], v[64:67]
	v_mfma_f32_16x16x32_bf16 v[116:119], v[182:185], v[198:201], v[116:119]
	v_mfma_f32_16x16x32_bf16 v[112:115], v[190:193], v[198:201], v[112:115]
	v_mfma_f32_16x16x32_bf16 v[100:103], v[182:185], v[206:209], v[100:103]
	v_mfma_f32_16x16x32_bf16 v[96:99], v[190:193], v[206:209], v[96:99]
	v_mfma_f32_16x16x32_bf16 v[84:87], v[182:185], v[214:217], v[84:87]
	v_mfma_f32_16x16x32_bf16 v[80:83], v[190:193], v[214:217], v[80:83]
	v_mfma_f32_16x16x32_bf16 v[68:71], v[182:185], v[226:229], v[68:71]
	v_mfma_f32_16x16x32_bf16 v[64:67], v[190:193], v[226:229], v[64:67]
	s_setprio 0
	s_barrier
	s_add_i32 s38, s70, s36
	v_lshl_add_u64 v[128:129], s[10:11], 0, v[132:133]
	s_mov_b32 m0, s38
	ds_read_b128 v[194:197], v155 offset:16384
	ds_read_b128 v[198:201], v155 offset:17408
	ds_read_b128 v[202:205], v155 offset:18432
	ds_read_b128 v[206:209], v155 offset:19456
	ds_read_b128 v[210:213], v155 offset:20480
	ds_read_b128 v[214:217], v155 offset:21504
	ds_read_b128 v[218:221], v155 offset:22528
	ds_read_b128 v[226:229], v155 offset:23552
	global_load_lds_dwordx4 v[128:129], off
	s_add_i32 m0, s38, 0x2000
	s_add_u32 s88, s10, 0x40000
	v_lshl_add_u64 v[150:151], s[10:11], 0, v[136:137]
	s_addc_u32 s89, s11, 0
	s_add_i32 s38, s71, s36
	global_load_lds_dwordx4 v[150:151], off
	v_lshl_add_u64 v[160:161], s[88:89], 0, v[132:133]
	s_mov_b32 m0, s38
	v_lshl_add_u64 v[222:223], s[34:35], 0, v[134:135]
	global_load_lds_dwordx4 v[160:161], off
	v_lshl_add_u64 v[160:161], s[88:89], 0, v[136:137]
	s_add_i32 m0, s38, 0x2000
	s_nop 0
	global_load_lds_dwordx4 v[160:161], off
	v_lshl_add_u64 v[160:161], s[34:35], 0, v[130:131]
	s_mov_b32 m0, s13
	s_nop 0
	global_load_lds_dwordx4 v[160:161], off
	s_mov_b32 m0, s37
	s_nop 0
	global_load_lds_dwordx4 v[222:223], off
	s_waitcnt vmcnt(8)
	s_waitcnt lgkmcnt(0)
	s_barrier
; #define PG8_STAGE(bufoff, gbase, voff) do { _Pragma("unroll") for (int _i = 0; _i < 2; ++_i) \
;         __builtin_amdgcn_global_load_lds((const unsigned*)((const char*)(gbase) + (voff)[_i]), (LAS unsigned*)(lds + (bufoff) + ldsw + _i * 8192), 16, 0, 0); } while (0)
; #define PG8_LDA(dst, b, h) do { _Pragma("unroll") for (int m = 0; m < 4; ++m) _Pragma("unroll") for (int k = 0; k < 2; ++k) dst[m][k] = *(const LAS bf16x8*)(lds + PG8_SA(b, h) + aoff + m * 2048 + k * 1024); } while (0)
; #define PG8_LDB(dst, b, h) do { _Pragma("unroll") for (int n = 0; n < 2; ++n) _Pragma("unroll") for (int k = 0; k < 2; ++k) dst[n][k] = *(const LAS bf16x8*)(lds + PG8_SB(b, h) + boff + n * 2048 + k * 1024); } while (0)
; #define PG8_MMA(ai, bj, At, Bt) do { __builtin_amdgcn_s_setprio(1); _Pragma("unroll") for (int m = 0; m < 4; ++m) _Pragma("unroll") for (int n = 0; n < 2; ++n) _Pragma("unroll") for (int k = 0; k < 2; ++k) \
;         acc[ai][bj][m][n] = __builtin_amdgcn_mfma_f32_16x16x32_bf16(Bt[n][k], At[m][k], acc[ai][bj][m][n], 0, 0, 0); __builtin_amdgcn_s_setprio(0); } while (0)
; #define PG8_WAIT_V(n) asm volatile("s_waitcnt vmcnt(" #n ")" ::: "memory")
; #define PG8_WAIT_L(n) asm volatile("s_waitcnt lgkmcnt(" #n ")" ::: "memory")
; #define PG8_BAR __builtin_amdgcn_s_barrier()
; #define PG8_SCHED __builtin_amdgcn_sched_barrier(0)
; template <class Epi, class Sched>
; DI void gemm_phase(LAS unsigned char* lds, const Gemm g, const Sched& S, const Epi& E) {
;     ...
;       PG8_WAIT_V(8); PG8_WAIT_L(0); PG8_BAR; PG8_MMA(1, 0, At, B0); PG8_MMA(1, 1, At, B1); PG8_BAR; PG8_SCHED;
;       PG8_LDB(B0, 1, 0); PG8_LDB(B1, 1, 1); PG8_SCHED; PG8_LDA(At, 1, 0); PG8_STAGE(PG8_SA(0, 1), a2 + hstepA, voffA);
;       PG8_WAIT_V(8); PG8_WAIT_L(0); PG8_BAR; PG8_MMA(0, 0, At, B0); PG8_MMA(0, 1, At, B1); PG8_BAR; PG8_SCHED;
	s_setprio 1
	s_waitcnt lgkmcnt(0)
	v_mfma_f32_16x16x32_bf16 v[56:59], v[146:149], v[194:197], v[56:59]
	v_mfma_f32_16x16x32_bf16 v[60:63], v[170:173], v[194:197], v[60:63]
	v_mfma_f32_16x16x32_bf16 v[40:43], v[146:149], v[202:205], v[40:43]
	v_mfma_f32_16x16x32_bf16 v[44:47], v[170:173], v[202:205], v[44:47]
	v_mfma_f32_16x16x32_bf16 v[24:27], v[146:149], v[210:213], v[24:27]
	v_mfma_f32_16x16x32_bf16 v[28:31], v[170:173], v[210:213], v[28:31]
	v_mfma_f32_16x16x32_bf16 v[8:11], v[146:149], v[218:221], v[8:11]
	v_mfma_f32_16x16x32_bf16 v[12:15], v[170:173], v[218:221], v[12:15]
	v_mfma_f32_16x16x32_bf16 v[56:59], v[166:169], v[198:201], v[56:59]
	v_mfma_f32_16x16x32_bf16 v[60:63], v[174:177], v[198:201], v[60:63]
	v_mfma_f32_16x16x32_bf16 v[40:43], v[166:169], v[206:209], v[40:43]
	v_mfma_f32_16x16x32_bf16 v[44:47], v[174:177], v[206:209], v[44:47]
	v_mfma_f32_16x16x32_bf16 v[24:27], v[166:169], v[214:217], v[24:27]
	v_mfma_f32_16x16x32_bf16 v[28:31], v[174:177], v[214:217], v[28:31]
	v_mfma_f32_16x16x32_bf16 v[8:11], v[166:169], v[226:229], v[8:11]
	v_mfma_f32_16x16x32_bf16 v[12:15], v[174:177], v[226:229], v[12:15]
	s_setprio 0
	s_setprio 1
	v_mfma_f32_16x16x32_bf16 v[52:55], v[178:181], v[194:197], v[52:55]
	v_mfma_f32_16x16x32_bf16 v[48:51], v[186:189], v[194:197], v[48:51]
	v_mfma_f32_16x16x32_bf16 v[36:39], v[178:181], v[202:205], v[36:39]
	v_mfma_f32_16x16x32_bf16 v[32:35], v[186:189], v[202:205], v[32:35]
	v_mfma_f32_16x16x32_bf16 v[20:23], v[178:181], v[210:213], v[20:23]
	v_mfma_f32_16x16x32_bf16 v[16:19], v[186:189], v[210:213], v[16:19]
	v_mfma_f32_16x16x32_bf16 v[4:7], v[178:181], v[218:221], v[4:7]
	v_mfma_f32_16x16x32_bf16 v[0:3], v[186:189], v[218:221], v[0:3]
	v_mfma_f32_16x16x32_bf16 v[52:55], v[182:185], v[198:201], v[52:55]
	v_mfma_f32_16x16x32_bf16 v[48:51], v[190:193], v[198:201], v[48:51]
	v_mfma_f32_16x16x32_bf16 v[36:39], v[182:185], v[206:209], v[36:39]
	v_mfma_f32_16x16x32_bf16 v[32:35], v[190:193], v[206:209], v[32:35]
	v_mfma_f32_16x16x32_bf16 v[20:23], v[182:185], v[214:217], v[20:23]
	v_mfma_f32_16x16x32_bf16 v[16:19], v[190:193], v[214:217], v[16:19]
	v_mfma_f32_16x16x32_bf16 v[4:7], v[182:185], v[226:229], v[4:7]
	v_mfma_f32_16x16x32_bf16 v[0:3], v[190:193], v[226:229], v[0:3]
	s_setprio 0
	s_barrier
	s_add_i32 s38, 0, 0x18000
	s_add_i32 s39, 0, 0x1c000
	v_add_u32_e32 v174, s38, v152
	v_add_u32_e32 v190, s39, v152
	ds_read_b128 v[146:149], v174
	ds_read_b128 v[166:169], v174 offset:1024
	ds_read_b128 v[170:173], v174 offset:2048
	ds_read_b128 v[174:177], v174 offset:3072
	ds_read_b128 v[178:181], v190
	ds_read_b128 v[182:185], v190 offset:1024
	ds_read_b128 v[186:189], v190 offset:2048
	ds_read_b128 v[190:193], v190 offset:3072
	s_add_u32 s34, s34, 0x40000
	s_addc_u32 s35, s35, 0
	s_mov_b32 m0, s42
	v_lshl_add_u64 v[230:231], s[34:35], 0, v[130:131]
	ds_read_b128 v[194:197], v155 offset:32768
	ds_read_b128 v[198:201], v155 offset:33792
	ds_read_b128 v[202:205], v155 offset:34816
	ds_read_b128 v[206:209], v155 offset:35840
	ds_read_b128 v[210:213], v155 offset:36864
	ds_read_b128 v[214:217], v155 offset:37888
	ds_read_b128 v[218:221], v155 offset:38912
	ds_read_b128 v[226:229], v155 offset:39936
	global_load_lds_dwordx4 v[230:231], off
	v_lshl_add_u64 v[230:231], s[34:35], 0, v[134:135]
	s_mov_b32 m0, s43
	s_nop 0
	global_load_lds_dwordx4 v[230:231], off
	s_waitcnt vmcnt(8)
	s_waitcnt lgkmcnt(0)
	s_barrier
	s_setprio 1
	s_waitcnt lgkmcnt(0)
	v_mfma_f32_16x16x32_bf16 v[124:127], v[146:149], v[194:197], v[124:127]
	v_mfma_f32_16x16x32_bf16 v[120:123], v[170:173], v[194:197], v[120:123]
	v_mfma_f32_16x16x32_bf16 v[104:107], v[146:149], v[202:205], v[104:107]
	v_mfma_f32_16x16x32_bf16 v[108:111], v[170:173], v[202:205], v[108:111]
	v_mfma_f32_16x16x32_bf16 v[88:91], v[146:149], v[210:213], v[88:91]
	v_mfma_f32_16x16x32_bf16 v[92:95], v[170:173], v[210:213], v[92:95]
	v_mfma_f32_16x16x32_bf16 v[72:75], v[146:149], v[218:221], v[72:75]
	v_mfma_f32_16x16x32_bf16 v[76:79], v[170:173], v[218:221], v[76:79]
	v_mfma_f32_16x16x32_bf16 v[124:127], v[166:169], v[198:201], v[124:127]
	v_mfma_f32_16x16x32_bf16 v[120:123], v[174:177], v[198:201], v[120:123]
	v_mfma_f32_16x16x32_bf16 v[104:107], v[166:169], v[206:209], v[104:107]
	v_mfma_f32_16x16x32_bf16 v[108:111], v[174:177], v[206:209], v[108:111]
	v_mfma_f32_16x16x32_bf16 v[88:91], v[166:169], v[214:217], v[88:91]
	v_mfma_f32_16x16x32_bf16 v[92:95], v[174:177], v[214:217], v[92:95]
	v_mfma_f32_16x16x32_bf16 v[72:75], v[166:169], v[226:229], v[72:75]
	v_mfma_f32_16x16x32_bf16 v[76:79], v[174:177], v[226:229], v[76:79]
	s_setprio 0
	s_setprio 1
	v_mfma_f32_16x16x32_bf16 v[116:119], v[178:181], v[194:197], v[116:119]
	v_mfma_f32_16x16x32_bf16 v[112:115], v[186:189], v[194:197], v[112:115]
	v_mfma_f32_16x16x32_bf16 v[100:103], v[178:181], v[202:205], v[100:103]
	v_mfma_f32_16x16x32_bf16 v[96:99], v[186:189], v[202:205], v[96:99]
	v_mfma_f32_16x16x32_bf16 v[84:87], v[178:181], v[210:213], v[84:87]
	v_mfma_f32_16x16x32_bf16 v[80:83], v[186:189], v[210:213], v[80:83]
	v_mfma_f32_16x16x32_bf16 v[68:71], v[178:181], v[218:221], v[68:71]
	v_mfma_f32_16x16x32_bf16 v[64:67], v[186:189], v[218:221], v[64:67]
	v_mfma_f32_16x16x32_bf16 v[116:119], v[182:185], v[198:201], v[116:119]
	v_mfma_f32_16x16x32_bf16 v[112:115], v[190:193], v[198:201], v[112:115]
	v_mfma_f32_16x16x32_bf16 v[100:103], v[182:185], v[206:209], v[100:103]
	v_mfma_f32_16x16x32_bf16 v[96:99], v[190:193], v[206:209], v[96:99]
	v_mfma_f32_16x16x32_bf16 v[84:87], v[182:185], v[214:217], v[84:87]
	v_mfma_f32_16x16x32_bf16 v[80:83], v[190:193], v[214:217], v[80:83]
	v_mfma_f32_16x16x32_bf16 v[68:71], v[182:185], v[226:229], v[68:71]
	v_mfma_f32_16x16x32_bf16 v[64:67], v[190:193], v[226:229], v[64:67]
	s_setprio 0
	s_barrier
; #define PG8_STAGE(bufoff, gbase, voff) do { _Pragma("unroll") for (int _i = 0; _i < 2; ++_i) \
;         __builtin_amdgcn_global_load_lds((const unsigned*)((const char*)(gbase) + (voff)[_i]), (LAS unsigned*)(lds + (bufoff) + ldsw + _i * 8192), 16, 0, 0); } while (0)
; #define PG8_LDA(dst, b, h) do { _Pragma("unroll") for (int m = 0; m < 4; ++m) _Pragma("unroll") for (int k = 0; k < 2; ++k) dst[m][k] = *(const LAS bf16x8*)(lds + PG8_SA(b, h) + aoff + m * 2048 + k * 1024); } while (0)
; #define PG8_MMA(ai, bj, At, Bt) do { __builtin_amdgcn_s_setprio(1); _Pragma("unroll") for (int m = 0; m < 4; ++m) _Pragma("unroll") for (int n = 0; n < 2; ++n) _Pragma("unroll") for (int k = 0; k < 2; ++k) \
;         acc[ai][bj][m][n] = __builtin_amdgcn_mfma_f32_16x16x32_bf16(Bt[n][k], At[m][k], acc[ai][bj][m][n], 0, 0, 0); __builtin_amdgcn_s_setprio(0); } while (0)
; #define PG8_WAIT_V(n) asm volatile("s_waitcnt vmcnt(" #n ")" ::: "memory")
; #define PG8_WAIT_L(n) asm volatile("s_waitcnt lgkmcnt(" #n ")" ::: "memory")
; #define PG8_BAR __builtin_amdgcn_s_barrier()
; #define PG8_SCHED __builtin_amdgcn_sched_barrier(0)
; template <class Epi, class Sched>
; DI void gemm_phase(LAS unsigned char* lds, const Gemm g, const Sched& S, const Epi& E) {
;     ...
;       PG8_LDA(At, 1, 1); PG8_STAGE(PG8_SB(1, 0), b3, voffB); PG8_STAGE(PG8_SB(1, 1), b3 + hstepB, voffB); PG8_STAGE(PG8_SA(1, 0), a3, voffA);
;       PG8_WAIT_V(8); PG8_WAIT_L(0); PG8_BAR; PG8_MMA(1, 0, At, B0); PG8_MMA(1, 1, At, B1); PG8_BAR; PG8_SCHED;
;     }
;     if (wr == 0) PG8_BAR;
	s_add_i32 s34, s38, s36
	v_lshl_add_u64 v[128:129], v[128:129], 0, s[20:21]
	s_mov_b32 m0, s34
	ds_read_b128 v[194:197], v155 offset:49152
	ds_read_b128 v[198:201], v155 offset:50176
	ds_read_b128 v[202:205], v155 offset:51200
	ds_read_b128 v[206:209], v155 offset:52224
	ds_read_b128 v[210:213], v155 offset:53248
	ds_read_b128 v[214:217], v155 offset:54272
	ds_read_b128 v[218:221], v155 offset:55296
	ds_read_b128 v[226:229], v155 offset:56320
	global_load_lds_dwordx4 v[128:129], off
	s_add_i32 m0, s34, 0x2000
	s_add_u32 s10, s10, 0x40080
	v_lshl_add_u64 v[128:129], v[150:151], 0, s[20:21]
	s_addc_u32 s11, s11, 0
	s_add_i32 s34, s39, s36
	global_load_lds_dwordx4 v[128:129], off
	v_lshl_add_u64 v[128:129], s[10:11], 0, v[132:133]
	s_mov_b32 m0, s34
	s_nop 0
	global_load_lds_dwordx4 v[128:129], off
	v_lshl_add_u64 v[128:129], s[10:11], 0, v[136:137]
	s_add_i32 m0, s34, 0x2000
	s_nop 0
	global_load_lds_dwordx4 v[128:129], off
	v_lshl_add_u64 v[128:129], v[160:161], 0, s[20:21]
	s_mov_b32 m0, s65
	s_nop 0
	global_load_lds_dwordx4 v[128:129], off
	v_lshl_add_u64 v[128:129], v[222:223], 0, s[20:21]
	s_mov_b32 m0, s66
	s_nop 0
	global_load_lds_dwordx4 v[128:129], off
	s_waitcnt vmcnt(8)
	s_waitcnt lgkmcnt(0)
	s_barrier
	s_setprio 1
	s_waitcnt lgkmcnt(0)
	v_mfma_f32_16x16x32_bf16 v[56:59], v[146:149], v[194:197], v[56:59]
	v_mfma_f32_16x16x32_bf16 v[60:63], v[170:173], v[194:197], v[60:63]
	v_mfma_f32_16x16x32_bf16 v[40:43], v[146:149], v[202:205], v[40:43]
	v_mfma_f32_16x16x32_bf16 v[44:47], v[170:173], v[202:205], v[44:47]
	v_mfma_f32_16x16x32_bf16 v[24:27], v[146:149], v[210:213], v[24:27]
	v_mfma_f32_16x16x32_bf16 v[28:31], v[170:173], v[210:213], v[28:31]
	v_mfma_f32_16x16x32_bf16 v[8:11], v[146:149], v[218:221], v[8:11]
	v_mfma_f32_16x16x32_bf16 v[12:15], v[170:173], v[218:221], v[12:15]
	v_mfma_f32_16x16x32_bf16 v[56:59], v[166:169], v[198:201], v[56:59]
	v_mfma_f32_16x16x32_bf16 v[60:63], v[174:177], v[198:201], v[60:63]
	v_mfma_f32_16x16x32_bf16 v[40:43], v[166:169], v[206:209], v[40:43]
	v_mfma_f32_16x16x32_bf16 v[44:47], v[174:177], v[206:209], v[44:47]
	v_mfma_f32_16x16x32_bf16 v[24:27], v[166:169], v[214:217], v[24:27]
	v_mfma_f32_16x16x32_bf16 v[28:31], v[174:177], v[214:217], v[28:31]
	v_mfma_f32_16x16x32_bf16 v[8:11], v[166:169], v[226:229], v[8:11]
	v_mfma_f32_16x16x32_bf16 v[12:15], v[174:177], v[226:229], v[12:15]
	s_setprio 0
	s_setprio 1
	v_mfma_f32_16x16x32_bf16 v[52:55], v[178:181], v[194:197], v[52:55]
	v_mfma_f32_16x16x32_bf16 v[48:51], v[186:189], v[194:197], v[48:51]
	v_mfma_f32_16x16x32_bf16 v[36:39], v[178:181], v[202:205], v[36:39]
	v_mfma_f32_16x16x32_bf16 v[32:35], v[186:189], v[202:205], v[32:35]
	v_mfma_f32_16x16x32_bf16 v[20:23], v[178:181], v[210:213], v[20:23]
	v_mfma_f32_16x16x32_bf16 v[16:19], v[186:189], v[210:213], v[16:19]
	v_mfma_f32_16x16x32_bf16 v[4:7], v[178:181], v[218:221], v[4:7]
	v_mfma_f32_16x16x32_bf16 v[0:3], v[186:189], v[218:221], v[0:3]
	v_mfma_f32_16x16x32_bf16 v[52:55], v[182:185], v[198:201], v[52:55]
	v_mfma_f32_16x16x32_bf16 v[48:51], v[190:193], v[198:201], v[48:51]
	v_mfma_f32_16x16x32_bf16 v[36:39], v[182:185], v[206:209], v[36:39]
	v_mfma_f32_16x16x32_bf16 v[32:35], v[190:193], v[206:209], v[32:35]
	v_mfma_f32_16x16x32_bf16 v[20:23], v[182:185], v[214:217], v[20:23]
	v_mfma_f32_16x16x32_bf16 v[16:19], v[190:193], v[214:217], v[16:19]
	v_mfma_f32_16x16x32_bf16 v[4:7], v[182:185], v[226:229], v[4:7]
	v_mfma_f32_16x16x32_bf16 v[0:3], v[190:193], v[226:229], v[0:3]
	s_setprio 0
	s_add_i32 s87, s87, 2
	s_add_u32 s85, s85, 0x100
	s_addc_u32 s86, s86, 0
	s_add_u32 s8, s8, 0x100
	s_addc_u32 s9, s9, 0
	s_cmp_gt_u32 s87, 13
	s_barrier
	s_cbranch_scc0 .LBB0_703
	s_and_b64 vcc, exec, s[22:23]
	s_cbranch_vccz .LBB0_706
	s_barrier

; #define PG8_STAGE(bufoff, gbase, voff) do { _Pragma("unroll") for (int _i = 0; _i < 2; ++_i) \
;         __builtin_amdgcn_global_load_lds((const unsigned*)((const char*)(gbase) + (voff)[_i]), (LAS unsigned*)(lds + (bufoff) + ldsw + _i * 8192), 16, 0, 0); } while (0)
; #define PG8_LDA(dst, b, h) do { _Pragma("unroll") for (int m = 0; m < 4; ++m) _Pragma("unroll") for (int k = 0; k < 2; ++k) dst[m][k] = *(const LAS bf16x8*)(lds + PG8_SA(b, h) + aoff + m * 2048 + k * 1024); } while (0)
; #define PG8_LDB(dst, b, h) do { _Pragma("unroll") for (int n = 0; n < 2; ++n) _Pragma("unroll") for (int k = 0; k < 2; ++k) dst[n][k] = *(const LAS bf16x8*)(lds + PG8_SB(b, h) + boff + n * 2048 + k * 1024); } while (0)
; #define PG8_MMA(ai, bj, At, Bt) do { __builtin_amdgcn_s_setprio(1); _Pragma("unroll") for (int m = 0; m < 4; ++m) _Pragma("unroll") for (int n = 0; n < 2; ++n) _Pragma("unroll") for (int k = 0; k < 2; ++k) \
;         acc[ai][bj][m][n] = __builtin_amdgcn_mfma_f32_16x16x32_bf16(Bt[n][k], At[m][k], acc[ai][bj][m][n], 0, 0, 0); __builtin_amdgcn_s_setprio(0); } while (0)
; #define PG8_WAIT_V(n) asm volatile("s_waitcnt vmcnt(" #n ")" ::: "memory")
; #define PG8_WAIT_L(n) asm volatile("s_waitcnt lgkmcnt(" #n ")" ::: "memory")
; #define PG8_BAR __builtin_amdgcn_s_barrier()
; #define PG8_SCHED __builtin_amdgcn_sched_barrier(0)
; template <class Epi, class Sched>
; DI void gemm_phase(LAS unsigned char* lds, const Gemm g, const Sched& S, const Epi& E) {
;     ...
;     for (int t = 0; t < nt; t += 2) {
;       const bool last = (t == nt - 2);
;       const char* a1 = cA + (size_t)(t + 1) * kstep;
;       const char* a2 = last ? nA : cA + (size_t)(t + 2) * kstep; const char* b2 = last ? nB : cB + (size_t)(t + 2) * kstep;
;       const char* a3 = a2 + kstep; const char* b3 = b2 + kstep;
;       PG8_LDB(B0, 0, 0); PG8_LDB(B1, 0, 1); PG8_SCHED; PG8_LDA(At, 0, 0); PG8_STAGE(PG8_SA(1, 1), a1 + hstepA, voffA);
;       PG8_WAIT_V(8); PG8_WAIT_L(0); PG8_BAR; PG8_MMA(0, 0, At, B0); PG8_MMA(0, 1, At, B1); PG8_BAR; PG8_SCHED;
;       PG8_LDA(At, 0, 1); PG8_STAGE(PG8_SB(0, 0), b2, voffB); PG8_STAGE(PG8_SB(0, 1), b2 + hstepB, voffB); PG8_STAGE(PG8_SA(0, 0), a2, voffA);
;       PG8_WAIT_V(8); PG8_WAIT_L(0); PG8_BAR; PG8_MMA(1, 0, At, B0); PG8_MMA(1, 1, At, B1); PG8_BAR; PG8_SCHED;
.LBB0_896:
	ds_read_b128 v[152:155], v147
	ds_read_b128 v[156:159], v147 offset:1024
	ds_read_b128 v[160:163], v147 offset:2048
	ds_read_b128 v[164:167], v147 offset:3072
	ds_read_b128 v[168:171], v148
	ds_read_b128 v[172:175], v148 offset:1024
	ds_read_b128 v[176:179], v148 offset:2048
	ds_read_b128 v[180:183], v148 offset:3072
	s_add_u32 s28, s26, 0xfffc0080
	s_addc_u32 s29, s27, -1
	s_cmp_eq_u32 s69, 12
	s_cselect_b32 s31, s19, s29
	s_cselect_b32 s30, s65, s28
	s_cselect_b32 s29, s15, s68
	s_cselect_b32 s28, s66, s67
	v_lshl_add_u64 v[144:145], s[26:27], 0, v[138:139]
	s_add_i32 m0, s25, 0xc000
	ds_read_b128 v[184:187], v149
	ds_read_b128 v[188:191], v149 offset:1024
	ds_read_b128 v[192:195], v149 offset:2048
	ds_read_b128 v[196:199], v149 offset:3072
	ds_read_b128 v[200:203], v149 offset:4096
	ds_read_b128 v[204:207], v149 offset:5120
	ds_read_b128 v[208:211], v149 offset:6144
	ds_read_b128 v[212:215], v149 offset:7168
	global_load_lds_dwordx4 v[144:145], off
	v_lshl_add_u64 v[144:145], s[26:27], 0, v[136:137]
	s_add_i32 m0, s25, 0xe000
	s_nop 0
	global_load_lds_dwordx4 v[144:145], off
	s_waitcnt vmcnt(8)
	s_waitcnt lgkmcnt(0)
	s_barrier
	s_setprio 1
	s_waitcnt lgkmcnt(0)
	v_mfma_f32_16x16x32_bf16 v[124:127], v[152:155], v[184:187], v[124:127]
	v_mfma_f32_16x16x32_bf16 v[120:123], v[160:163], v[184:187], v[120:123]
	v_mfma_f32_16x16x32_bf16 v[108:111], v[152:155], v[192:195], v[108:111]
	v_mfma_f32_16x16x32_bf16 v[104:107], v[160:163], v[192:195], v[104:107]
	v_mfma_f32_16x16x32_bf16 v[92:95], v[152:155], v[200:203], v[92:95]
	v_mfma_f32_16x16x32_bf16 v[88:91], v[160:163], v[200:203], v[88:91]
	v_mfma_f32_16x16x32_bf16 v[76:79], v[152:155], v[208:211], v[76:79]
	v_mfma_f32_16x16x32_bf16 v[72:75], v[160:163], v[208:211], v[72:75]
	v_mfma_f32_16x16x32_bf16 v[124:127], v[156:159], v[188:191], v[124:127]
	v_mfma_f32_16x16x32_bf16 v[120:123], v[164:167], v[188:191], v[120:123]
	v_mfma_f32_16x16x32_bf16 v[108:111], v[156:159], v[196:199], v[108:111]
	v_mfma_f32_16x16x32_bf16 v[104:107], v[164:167], v[196:199], v[104:107]
	v_mfma_f32_16x16x32_bf16 v[92:95], v[156:159], v[204:207], v[92:95]
	v_mfma_f32_16x16x32_bf16 v[88:91], v[164:167], v[204:207], v[88:91]
	v_mfma_f32_16x16x32_bf16 v[76:79], v[156:159], v[212:215], v[76:79]
	v_mfma_f32_16x16x32_bf16 v[72:75], v[164:167], v[212:215], v[72:75]
	s_setprio 0
	s_setprio 1
	v_mfma_f32_16x16x32_bf16 v[116:119], v[168:171], v[184:187], v[116:119]
	v_mfma_f32_16x16x32_bf16 v[112:115], v[176:179], v[184:187], v[112:115]
	v_mfma_f32_16x16x32_bf16 v[100:103], v[168:171], v[192:195], v[100:103]
	v_mfma_f32_16x16x32_bf16 v[96:99], v[176:179], v[192:195], v[96:99]
	v_mfma_f32_16x16x32_bf16 v[84:87], v[168:171], v[200:203], v[84:87]
	v_mfma_f32_16x16x32_bf16 v[80:83], v[176:179], v[200:203], v[80:83]
	v_mfma_f32_16x16x32_bf16 v[68:71], v[168:171], v[208:211], v[68:71]
	v_mfma_f32_16x16x32_bf16 v[64:67], v[176:179], v[208:211], v[64:67]
	v_mfma_f32_16x16x32_bf16 v[116:119], v[172:175], v[188:191], v[116:119]
	v_mfma_f32_16x16x32_bf16 v[112:115], v[180:183], v[188:191], v[112:115]
	v_mfma_f32_16x16x32_bf16 v[100:103], v[172:175], v[196:199], v[100:103]
	v_mfma_f32_16x16x32_bf16 v[96:99], v[180:183], v[196:199], v[96:99]
	v_mfma_f32_16x16x32_bf16 v[84:87], v[172:175], v[204:207], v[84:87]
	v_mfma_f32_16x16x32_bf16 v[80:83], v[180:183], v[204:207], v[80:83]
	v_mfma_f32_16x16x32_bf16 v[68:71], v[172:175], v[212:215], v[68:71]
	v_mfma_f32_16x16x32_bf16 v[64:67], v[180:183], v[212:215], v[64:67]
	s_setprio 0
	s_barrier
	s_add_i32 s38, s62, s17
	v_lshl_add_u64 v[144:145], s[28:29], 0, v[132:133]
	s_mov_b32 m0, s38
	ds_read_b128 v[184:187], v149 offset:16384
	ds_read_b128 v[188:191], v149 offset:17408
	ds_read_b128 v[192:195], v149 offset:18432
	ds_read_b128 v[196:199], v149 offset:19456
	ds_read_b128 v[200:203], v149 offset:20480
	ds_read_b128 v[204:207], v149 offset:21504
	ds_read_b128 v[208:211], v149 offset:22528
	ds_read_b128 v[212:215], v149 offset:23552
	global_load_lds_dwordx4 v[144:145], off
	s_add_i32 m0, s38, 0x2000
	s_add_u32 s70, s28, 0x40000
	v_lshl_add_u64 v[216:217], s[28:29], 0, v[128:129]
	s_addc_u32 s71, s29, 0
	s_add_i32 s38, s63, s17
	global_load_lds_dwordx4 v[216:217], off
	v_lshl_add_u64 v[218:219], s[70:71], 0, v[132:133]
	s_mov_b32 m0, s38
	v_lshl_add_u64 v[220:221], s[30:31], 0, v[130:131]
	global_load_lds_dwordx4 v[218:219], off
	v_lshl_add_u64 v[218:219], s[70:71], 0, v[128:129]
	s_add_i32 m0, s38, 0x2000
	s_nop 0
	global_load_lds_dwordx4 v[218:219], off
	v_lshl_add_u64 v[218:219], s[30:31], 0, v[134:135]
	s_mov_b32 m0, s25
	s_nop 0
	global_load_lds_dwordx4 v[218:219], off
	s_mov_b32 m0, s34
	s_nop 0
	global_load_lds_dwordx4 v[220:221], off
	s_waitcnt vmcnt(8)
	s_waitcnt lgkmcnt(0)
	s_barrier
; #define PG8_STAGE(bufoff, gbase, voff) do { _Pragma("unroll") for (int _i = 0; _i < 2; ++_i) \
;         __builtin_amdgcn_global_load_lds((const unsigned*)((const char*)(gbase) + (voff)[_i]), (LAS unsigned*)(lds + (bufoff) + ldsw + _i * 8192), 16, 0, 0); } while (0)
; #define PG8_LDA(dst, b, h) do { _Pragma("unroll") for (int m = 0; m < 4; ++m) _Pragma("unroll") for (int k = 0; k < 2; ++k) dst[m][k] = *(const LAS bf16x8*)(lds + PG8_SA(b, h) + aoff + m * 2048 + k * 1024); } while (0)
; #define PG8_LDB(dst, b, h) do { _Pragma("unroll") for (int n = 0; n < 2; ++n) _Pragma("unroll") for (int k = 0; k < 2; ++k) dst[n][k] = *(const LAS bf16x8*)(lds + PG8_SB(b, h) + boff + n * 2048 + k * 1024); } while (0)
; #define PG8_MMA(ai, bj, At, Bt) do { __builtin_amdgcn_s_setprio(1); _Pragma("unroll") for (int m = 0; m < 4; ++m) _Pragma("unroll") for (int n = 0; n < 2; ++n) _Pragma("unroll") for (int k = 0; k < 2; ++k) \
;         acc[ai][bj][m][n] = __builtin_amdgcn_mfma_f32_16x16x32_bf16(Bt[n][k], At[m][k], acc[ai][bj][m][n], 0, 0, 0); __builtin_amdgcn_s_setprio(0); } while (0)
; #define PG8_WAIT_V(n) asm volatile("s_waitcnt vmcnt(" #n ")" ::: "memory")
; #define PG8_WAIT_L(n) asm volatile("s_waitcnt lgkmcnt(" #n ")" ::: "memory")
; #define PG8_BAR __builtin_amdgcn_s_barrier()
; #define PG8_SCHED __builtin_amdgcn_sched_barrier(0)
; template <class Epi, class Sched>
; DI void gemm_phase(LAS unsigned char* lds, const Gemm g, const Sched& S, const Epi& E) {
;     ...
;       PG8_WAIT_V(8); PG8_WAIT_L(0); PG8_BAR; PG8_MMA(1, 0, At, B0); PG8_MMA(1, 1, At, B1); PG8_BAR; PG8_SCHED;
;       PG8_LDB(B0, 1, 0); PG8_LDB(B1, 1, 1); PG8_SCHED; PG8_LDA(At, 1, 0); PG8_STAGE(PG8_SA(0, 1), a2 + hstepA, voffA);
;       PG8_WAIT_V(8); PG8_WAIT_L(0); PG8_BAR; PG8_MMA(0, 0, At, B0); PG8_MMA(0, 1, At, B1); PG8_BAR; PG8_SCHED;
	s_setprio 1
	s_waitcnt lgkmcnt(0)
	v_mfma_f32_16x16x32_bf16 v[60:63], v[152:155], v[184:187], v[60:63]
	v_mfma_f32_16x16x32_bf16 v[56:59], v[160:163], v[184:187], v[56:59]
	v_mfma_f32_16x16x32_bf16 v[44:47], v[152:155], v[192:195], v[44:47]
	v_mfma_f32_16x16x32_bf16 v[40:43], v[160:163], v[192:195], v[40:43]
	v_mfma_f32_16x16x32_bf16 v[28:31], v[152:155], v[200:203], v[28:31]
	v_mfma_f32_16x16x32_bf16 v[24:27], v[160:163], v[200:203], v[24:27]
	v_mfma_f32_16x16x32_bf16 v[12:15], v[152:155], v[208:211], v[12:15]
	v_mfma_f32_16x16x32_bf16 v[8:11], v[160:163], v[208:211], v[8:11]
	v_mfma_f32_16x16x32_bf16 v[60:63], v[156:159], v[188:191], v[60:63]
	v_mfma_f32_16x16x32_bf16 v[56:59], v[164:167], v[188:191], v[56:59]
	v_mfma_f32_16x16x32_bf16 v[44:47], v[156:159], v[196:199], v[44:47]
	v_mfma_f32_16x16x32_bf16 v[40:43], v[164:167], v[196:199], v[40:43]
	v_mfma_f32_16x16x32_bf16 v[28:31], v[156:159], v[204:207], v[28:31]
	v_mfma_f32_16x16x32_bf16 v[24:27], v[164:167], v[204:207], v[24:27]
	v_mfma_f32_16x16x32_bf16 v[12:15], v[156:159], v[212:215], v[12:15]
	v_mfma_f32_16x16x32_bf16 v[8:11], v[164:167], v[212:215], v[8:11]
	s_setprio 0
	s_setprio 1
	v_mfma_f32_16x16x32_bf16 v[52:55], v[168:171], v[184:187], v[52:55]
	v_mfma_f32_16x16x32_bf16 v[48:51], v[176:179], v[184:187], v[48:51]
	v_mfma_f32_16x16x32_bf16 v[36:39], v[168:171], v[192:195], v[36:39]
	v_mfma_f32_16x16x32_bf16 v[32:35], v[176:179], v[192:195], v[32:35]
	v_mfma_f32_16x16x32_bf16 v[20:23], v[168:171], v[200:203], v[20:23]
	v_mfma_f32_16x16x32_bf16 v[16:19], v[176:179], v[200:203], v[16:19]
	v_mfma_f32_16x16x32_bf16 v[4:7], v[168:171], v[208:211], v[4:7]
	v_mfma_f32_16x16x32_bf16 v[0:3], v[176:179], v[208:211], v[0:3]
	v_mfma_f32_16x16x32_bf16 v[52:55], v[172:175], v[188:191], v[52:55]
	v_mfma_f32_16x16x32_bf16 v[48:51], v[180:183], v[188:191], v[48:51]
	v_mfma_f32_16x16x32_bf16 v[36:39], v[172:175], v[196:199], v[36:39]
	v_mfma_f32_16x16x32_bf16 v[32:35], v[180:183], v[196:199], v[32:35]
	v_mfma_f32_16x16x32_bf16 v[20:23], v[172:175], v[204:207], v[20:23]
	v_mfma_f32_16x16x32_bf16 v[16:19], v[180:183], v[204:207], v[16:19]
	v_mfma_f32_16x16x32_bf16 v[4:7], v[172:175], v[212:215], v[4:7]
	v_mfma_f32_16x16x32_bf16 v[0:3], v[180:183], v[212:215], v[0:3]
	s_setprio 0
	s_barrier
	s_add_i32 s38, 0, 0x18000
	v_add_u32_e32 v151, s38, v146
	s_add_i32 s39, 0, 0x1c000
	ds_read_b128 v[152:155], v151
	ds_read_b128 v[156:159], v151 offset:1024
	ds_read_b128 v[160:163], v151 offset:2048
	ds_read_b128 v[164:167], v151 offset:3072
	v_add_u32_e32 v151, s39, v146
	ds_read_b128 v[168:171], v151
	ds_read_b128 v[172:175], v151 offset:1024
	ds_read_b128 v[176:179], v151 offset:2048
	ds_read_b128 v[180:183], v151 offset:3072
	s_add_u32 s30, s30, 0x40000
	s_addc_u32 s31, s31, 0
	s_mov_b32 m0, s35
	v_lshl_add_u64 v[222:223], s[30:31], 0, v[134:135]
	ds_read_b128 v[184:187], v149 offset:32768
	ds_read_b128 v[188:191], v149 offset:33792
	ds_read_b128 v[192:195], v149 offset:34816
	ds_read_b128 v[196:199], v149 offset:35840
	ds_read_b128 v[200:203], v149 offset:36864
	ds_read_b128 v[204:207], v149 offset:37888
	ds_read_b128 v[208:211], v149 offset:38912
	ds_read_b128 v[212:215], v149 offset:39936
	global_load_lds_dwordx4 v[222:223], off
	v_lshl_add_u64 v[222:223], s[30:31], 0, v[130:131]
	s_mov_b32 m0, s36
	s_nop 0
	global_load_lds_dwordx4 v[222:223], off
	s_waitcnt vmcnt(8)
	s_waitcnt lgkmcnt(0)
	s_barrier
	s_setprio 1
	s_waitcnt lgkmcnt(0)
	v_mfma_f32_16x16x32_bf16 v[124:127], v[152:155], v[184:187], v[124:127]
	v_mfma_f32_16x16x32_bf16 v[120:123], v[160:163], v[184:187], v[120:123]
	v_mfma_f32_16x16x32_bf16 v[108:111], v[152:155], v[192:195], v[108:111]
	v_mfma_f32_16x16x32_bf16 v[104:107], v[160:163], v[192:195], v[104:107]
	v_mfma_f32_16x16x32_bf16 v[92:95], v[152:155], v[200:203], v[92:95]
	v_mfma_f32_16x16x32_bf16 v[88:91], v[160:163], v[200:203], v[88:91]
	v_mfma_f32_16x16x32_bf16 v[76:79], v[152:155], v[208:211], v[76:79]
	v_mfma_f32_16x16x32_bf16 v[72:75], v[160:163], v[208:211], v[72:75]
	v_mfma_f32_16x16x32_bf16 v[124:127], v[156:159], v[188:191], v[124:127]
	v_mfma_f32_16x16x32_bf16 v[120:123], v[164:167], v[188:191], v[120:123]
	v_mfma_f32_16x16x32_bf16 v[108:111], v[156:159], v[196:199], v[108:111]
	v_mfma_f32_16x16x32_bf16 v[104:107], v[164:167], v[196:199], v[104:107]
	v_mfma_f32_16x16x32_bf16 v[92:95], v[156:159], v[204:207], v[92:95]
	v_mfma_f32_16x16x32_bf16 v[88:91], v[164:167], v[204:207], v[88:91]
	v_mfma_f32_16x16x32_bf16 v[76:79], v[156:159], v[212:215], v[76:79]
	v_mfma_f32_16x16x32_bf16 v[72:75], v[164:167], v[212:215], v[72:75]
	s_setprio 0
	s_setprio 1
	v_mfma_f32_16x16x32_bf16 v[116:119], v[168:171], v[184:187], v[116:119]
	v_mfma_f32_16x16x32_bf16 v[112:115], v[176:179], v[184:187], v[112:115]
	v_mfma_f32_16x16x32_bf16 v[100:103], v[168:171], v[192:195], v[100:103]
	v_mfma_f32_16x16x32_bf16 v[96:99], v[176:179], v[192:195], v[96:99]
	v_mfma_f32_16x16x32_bf16 v[84:87], v[168:171], v[200:203], v[84:87]
	v_mfma_f32_16x16x32_bf16 v[80:83], v[176:179], v[200:203], v[80:83]
	v_mfma_f32_16x16x32_bf16 v[68:71], v[168:171], v[208:211], v[68:71]
	v_mfma_f32_16x16x32_bf16 v[64:67], v[176:179], v[208:211], v[64:67]
	v_mfma_f32_16x16x32_bf16 v[116:119], v[172:175], v[188:191], v[116:119]
	v_mfma_f32_16x16x32_bf16 v[112:115], v[180:183], v[188:191], v[112:115]
	v_mfma_f32_16x16x32_bf16 v[100:103], v[172:175], v[196:199], v[100:103]
	v_mfma_f32_16x16x32_bf16 v[96:99], v[180:183], v[196:199], v[96:99]
	v_mfma_f32_16x16x32_bf16 v[84:87], v[172:175], v[204:207], v[84:87]
	v_mfma_f32_16x16x32_bf16 v[80:83], v[180:183], v[204:207], v[80:83]
	v_mfma_f32_16x16x32_bf16 v[68:71], v[172:175], v[212:215], v[68:71]
	v_mfma_f32_16x16x32_bf16 v[64:67], v[180:183], v[212:215], v[64:67]
	s_setprio 0
	s_barrier
; #define PG8_STAGE(bufoff, gbase, voff) do { _Pragma("unroll") for (int _i = 0; _i < 2; ++_i) \
;         __builtin_amdgcn_global_load_lds((const unsigned*)((const char*)(gbase) + (voff)[_i]), (LAS unsigned*)(lds + (bufoff) + ldsw + _i * 8192), 16, 0, 0); } while (0)
; #define PG8_LDA(dst, b, h) do { _Pragma("unroll") for (int m = 0; m < 4; ++m) _Pragma("unroll") for (int k = 0; k < 2; ++k) dst[m][k] = *(const LAS bf16x8*)(lds + PG8_SA(b, h) + aoff + m * 2048 + k * 1024); } while (0)
; #define PG8_MMA(ai, bj, At, Bt) do { __builtin_amdgcn_s_setprio(1); _Pragma("unroll") for (int m = 0; m < 4; ++m) _Pragma("unroll") for (int n = 0; n < 2; ++n) _Pragma("unroll") for (int k = 0; k < 2; ++k) \
;         acc[ai][bj][m][n] = __builtin_amdgcn_mfma_f32_16x16x32_bf16(Bt[n][k], At[m][k], acc[ai][bj][m][n], 0, 0, 0); __builtin_amdgcn_s_setprio(0); } while (0)
; #define PG8_WAIT_V(n) asm volatile("s_waitcnt vmcnt(" #n ")" ::: "memory")
; #define PG8_WAIT_L(n) asm volatile("s_waitcnt lgkmcnt(" #n ")" ::: "memory")
; #define PG8_BAR __builtin_amdgcn_s_barrier()
; #define PG8_SCHED __builtin_amdgcn_sched_barrier(0)
; template <class Epi, class Sched>
; DI void gemm_phase(LAS unsigned char* lds, const Gemm g, const Sched& S, const Epi& E) {
;     ...
;       PG8_LDA(At, 1, 1); PG8_STAGE(PG8_SB(1, 0), b3, voffB); PG8_STAGE(PG8_SB(1, 1), b3 + hstepB, voffB); PG8_STAGE(PG8_SA(1, 0), a3, voffA);
;       PG8_WAIT_V(8); PG8_WAIT_L(0); PG8_BAR; PG8_MMA(1, 0, At, B0); PG8_MMA(1, 1, At, B1); PG8_BAR; PG8_SCHED;
;     }
;     if (wr == 0) PG8_BAR;
	s_add_i32 s30, s38, s17
	v_lshl_add_u64 v[144:145], v[144:145], 0, s[8:9]
	s_mov_b32 m0, s30
	ds_read_b128 v[184:187], v149 offset:49152
	ds_read_b128 v[188:191], v149 offset:50176
	ds_read_b128 v[192:195], v149 offset:51200
	ds_read_b128 v[196:199], v149 offset:52224
	ds_read_b128 v[200:203], v149 offset:53248
	ds_read_b128 v[204:207], v149 offset:54272
	ds_read_b128 v[208:211], v149 offset:55296
	ds_read_b128 v[212:215], v149 offset:56320
	global_load_lds_dwordx4 v[144:145], off
	s_add_i32 m0, s30, 0x2000
	s_add_u32 s28, s28, 0x40080
	v_lshl_add_u64 v[144:145], v[216:217], 0, s[8:9]
	s_addc_u32 s29, s29, 0
	s_add_i32 s30, s39, s17
	global_load_lds_dwordx4 v[144:145], off
	v_lshl_add_u64 v[144:145], s[28:29], 0, v[132:133]
	s_mov_b32 m0, s30
	s_nop 0
	global_load_lds_dwordx4 v[144:145], off
	v_lshl_add_u64 v[144:145], s[28:29], 0, v[128:129]
	s_add_i32 m0, s30, 0x2000
	s_nop 0
	global_load_lds_dwordx4 v[144:145], off
	v_lshl_add_u64 v[144:145], v[218:219], 0, s[8:9]
	s_mov_b32 m0, s56
	s_nop 0
	global_load_lds_dwordx4 v[144:145], off
	v_lshl_add_u64 v[144:145], v[220:221], 0, s[8:9]
	s_mov_b32 m0, s57
	s_nop 0
	global_load_lds_dwordx4 v[144:145], off
	s_waitcnt vmcnt(8)
	s_waitcnt lgkmcnt(0)
	s_barrier
	s_setprio 1
	s_waitcnt lgkmcnt(0)
	v_mfma_f32_16x16x32_bf16 v[60:63], v[152:155], v[184:187], v[60:63]
	v_mfma_f32_16x16x32_bf16 v[56:59], v[160:163], v[184:187], v[56:59]
	v_mfma_f32_16x16x32_bf16 v[44:47], v[152:155], v[192:195], v[44:47]
	v_mfma_f32_16x16x32_bf16 v[40:43], v[160:163], v[192:195], v[40:43]
	v_mfma_f32_16x16x32_bf16 v[28:31], v[152:155], v[200:203], v[28:31]
	v_mfma_f32_16x16x32_bf16 v[24:27], v[160:163], v[200:203], v[24:27]
	v_mfma_f32_16x16x32_bf16 v[12:15], v[152:155], v[208:211], v[12:15]
	v_mfma_f32_16x16x32_bf16 v[8:11], v[160:163], v[208:211], v[8:11]
	v_mfma_f32_16x16x32_bf16 v[60:63], v[156:159], v[188:191], v[60:63]
	v_mfma_f32_16x16x32_bf16 v[56:59], v[164:167], v[188:191], v[56:59]
	v_mfma_f32_16x16x32_bf16 v[44:47], v[156:159], v[196:199], v[44:47]
	v_mfma_f32_16x16x32_bf16 v[40:43], v[164:167], v[196:199], v[40:43]
	v_mfma_f32_16x16x32_bf16 v[28:31], v[156:159], v[204:207], v[28:31]
	v_mfma_f32_16x16x32_bf16 v[24:27], v[164:167], v[204:207], v[24:27]
	v_mfma_f32_16x16x32_bf16 v[12:15], v[156:159], v[212:215], v[12:15]
	v_mfma_f32_16x16x32_bf16 v[8:11], v[164:167], v[212:215], v[8:11]
	s_setprio 0
	s_setprio 1
	v_mfma_f32_16x16x32_bf16 v[52:55], v[168:171], v[184:187], v[52:55]
	v_mfma_f32_16x16x32_bf16 v[48:51], v[176:179], v[184:187], v[48:51]
	v_mfma_f32_16x16x32_bf16 v[36:39], v[168:171], v[192:195], v[36:39]
	v_mfma_f32_16x16x32_bf16 v[32:35], v[176:179], v[192:195], v[32:35]
	v_mfma_f32_16x16x32_bf16 v[20:23], v[168:171], v[200:203], v[20:23]
	v_mfma_f32_16x16x32_bf16 v[16:19], v[176:179], v[200:203], v[16:19]
	v_mfma_f32_16x16x32_bf16 v[4:7], v[168:171], v[208:211], v[4:7]
	v_mfma_f32_16x16x32_bf16 v[0:3], v[176:179], v[208:211], v[0:3]
	v_mfma_f32_16x16x32_bf16 v[52:55], v[172:175], v[188:191], v[52:55]
	v_mfma_f32_16x16x32_bf16 v[48:51], v[180:183], v[188:191], v[48:51]
	v_mfma_f32_16x16x32_bf16 v[36:39], v[172:175], v[196:199], v[36:39]
	v_mfma_f32_16x16x32_bf16 v[32:35], v[180:183], v[196:199], v[32:35]
	v_mfma_f32_16x16x32_bf16 v[20:23], v[172:175], v[204:207], v[20:23]
	v_mfma_f32_16x16x32_bf16 v[16:19], v[180:183], v[204:207], v[16:19]
	v_mfma_f32_16x16x32_bf16 v[4:7], v[172:175], v[212:215], v[4:7]
	v_mfma_f32_16x16x32_bf16 v[0:3], v[180:183], v[212:215], v[0:3]
	s_setprio 0
	s_add_i32 s69, s69, 2
	s_add_u32 s67, s67, 0x100
	s_addc_u32 s68, s68, 0
	s_add_u32 s26, s26, 0x100
	s_addc_u32 s27, s27, 0
	s_cmp_gt_u32 s69, 13
	s_barrier
	s_cbranch_scc0 .LBB0_896
	s_and_b64 vcc, exec, s[10:11]
	s_cbranch_vccz .LBB0_899
	s_barrier

; #define PG8_STAGE(bufoff, gbase, voff) do { _Pragma("unroll") for (int _i = 0; _i < 2; ++_i) \
;         __builtin_amdgcn_global_load_lds((const unsigned*)((const char*)(gbase) + (voff)[_i]), (LAS unsigned*)(lds + (bufoff) + ldsw + _i * 8192), 16, 0, 0); } while (0)
; #define PG8_LDA(dst, b, h) do { _Pragma("unroll") for (int m = 0; m < 4; ++m) _Pragma("unroll") for (int k = 0; k < 2; ++k) dst[m][k] = *(const LAS bf16x8*)(lds + PG8_SA(b, h) + aoff + m * 2048 + k * 1024); } while (0)
; #define PG8_LDB(dst, b, h) do { _Pragma("unroll") for (int n = 0; n < 2; ++n) _Pragma("unroll") for (int k = 0; k < 2; ++k) dst[n][k] = *(const LAS bf16x8*)(lds + PG8_SB(b, h) + boff + n * 2048 + k * 1024); } while (0)
; #define PG8_MMA(ai, bj, At, Bt) do { __builtin_amdgcn_s_setprio(1); _Pragma("unroll") for (int m = 0; m < 4; ++m) _Pragma("unroll") for (int n = 0; n < 2; ++n) _Pragma("unroll") for (int k = 0; k < 2; ++k) \
;         acc[ai][bj][m][n] = __builtin_amdgcn_mfma_f32_16x16x32_bf16(Bt[n][k], At[m][k], acc[ai][bj][m][n], 0, 0, 0); __builtin_amdgcn_s_setprio(0); } while (0)
; #define PG8_WAIT_V(n) asm volatile("s_waitcnt vmcnt(" #n ")" ::: "memory")
; #define PG8_WAIT_L(n) asm volatile("s_waitcnt lgkmcnt(" #n ")" ::: "memory")
; #define PG8_BAR __builtin_amdgcn_s_barrier()
; #define PG8_SCHED __builtin_amdgcn_sched_barrier(0)
; template <class Epi, class Sched>
; DI void gemm_phase(LAS unsigned char* lds, const Gemm g, const Sched& S, const Epi& E) {
;     ...
;     for (int t = 0; t < nt; t += 2) {
;       const bool last = (t == nt - 2);
;       const char* a1 = cA + (size_t)(t + 1) * kstep;
;       const char* a2 = last ? nA : cA + (size_t)(t + 2) * kstep; const char* b2 = last ? nB : cB + (size_t)(t + 2) * kstep;
;       const char* a3 = a2 + kstep; const char* b3 = b2 + kstep;
;       PG8_LDB(B0, 0, 0); PG8_LDB(B1, 0, 1); PG8_SCHED; PG8_LDA(At, 0, 0); PG8_STAGE(PG8_SA(1, 1), a1 + hstepA, voffA);
;       PG8_WAIT_V(8); PG8_WAIT_L(0); PG8_BAR; PG8_MMA(0, 0, At, B0); PG8_MMA(0, 1, At, B1); PG8_BAR; PG8_SCHED;
;       PG8_LDA(At, 0, 1); PG8_STAGE(PG8_SB(0, 0), b2, voffB); PG8_STAGE(PG8_SB(0, 1), b2 + hstepB, voffB); PG8_STAGE(PG8_SA(0, 0), a2, voffA);
;       PG8_WAIT_V(8); PG8_WAIT_L(0); PG8_BAR; PG8_MMA(1, 0, At, B0); PG8_MMA(1, 1, At, B1); PG8_BAR; PG8_SCHED;
.LBB0_980:
	ds_read_b128 v[146:149], v159
	ds_read_b128 v[150:153], v159 offset:1024
	ds_read_b128 v[154:157], v159 offset:2048
	ds_read_b128 v[166:169], v159 offset:3072
	ds_read_b128 v[170:173], v160
	ds_read_b128 v[174:177], v160 offset:1024
	ds_read_b128 v[178:181], v160 offset:2048
	ds_read_b128 v[182:185], v160 offset:3072
	s_add_u32 s34, s30, 0xfff00080
	s_addc_u32 s35, s31, -1
	s_cmp_eq_u32 s88, 60
	s_cselect_b32 s37, s7, s35
	s_cselect_b32 s36, s9, s34
	s_cselect_b32 s35, s23, s87
	s_cselect_b32 s34, s25, s86
	v_lshl_add_u64 v[218:219], s[30:31], 0, v[140:141]
	s_add_i32 m0, s43, 0xc000
	ds_read_b128 v[186:189], v161
	ds_read_b128 v[190:193], v161 offset:1024
	ds_read_b128 v[194:197], v161 offset:2048
	ds_read_b128 v[198:201], v161 offset:3072
	ds_read_b128 v[202:205], v161 offset:4096
	ds_read_b128 v[206:209], v161 offset:5120
	ds_read_b128 v[210:213], v161 offset:6144
	ds_read_b128 v[214:217], v161 offset:7168
	global_load_lds_dwordx4 v[218:219], off
	v_lshl_add_u64 v[218:219], s[30:31], 0, v[138:139]
	s_add_i32 m0, s43, 0xe000
	s_nop 0
	global_load_lds_dwordx4 v[218:219], off
	s_waitcnt vmcnt(8)
	s_waitcnt lgkmcnt(0)
	s_barrier
	s_setprio 1
	s_waitcnt lgkmcnt(0)
	v_mfma_f32_16x16x32_bf16 v[124:127], v[146:149], v[186:189], v[124:127]
	v_mfma_f32_16x16x32_bf16 v[120:123], v[154:157], v[186:189], v[120:123]
	v_mfma_f32_16x16x32_bf16 v[108:111], v[146:149], v[194:197], v[108:111]
	v_mfma_f32_16x16x32_bf16 v[104:107], v[154:157], v[194:197], v[104:107]
	v_mfma_f32_16x16x32_bf16 v[92:95], v[146:149], v[202:205], v[92:95]
	v_mfma_f32_16x16x32_bf16 v[88:91], v[154:157], v[202:205], v[88:91]
	v_mfma_f32_16x16x32_bf16 v[76:79], v[146:149], v[210:213], v[76:79]
	v_mfma_f32_16x16x32_bf16 v[72:75], v[154:157], v[210:213], v[72:75]
	v_mfma_f32_16x16x32_bf16 v[124:127], v[150:153], v[190:193], v[124:127]
	v_mfma_f32_16x16x32_bf16 v[120:123], v[166:169], v[190:193], v[120:123]
	v_mfma_f32_16x16x32_bf16 v[108:111], v[150:153], v[198:201], v[108:111]
	v_mfma_f32_16x16x32_bf16 v[104:107], v[166:169], v[198:201], v[104:107]
	v_mfma_f32_16x16x32_bf16 v[92:95], v[150:153], v[206:209], v[92:95]
	v_mfma_f32_16x16x32_bf16 v[88:91], v[166:169], v[206:209], v[88:91]
	v_mfma_f32_16x16x32_bf16 v[76:79], v[150:153], v[214:217], v[76:79]
	v_mfma_f32_16x16x32_bf16 v[72:75], v[166:169], v[214:217], v[72:75]
	s_setprio 0
	s_setprio 1
	v_mfma_f32_16x16x32_bf16 v[116:119], v[170:173], v[186:189], v[116:119]
	v_mfma_f32_16x16x32_bf16 v[112:115], v[178:181], v[186:189], v[112:115]
	v_mfma_f32_16x16x32_bf16 v[100:103], v[170:173], v[194:197], v[100:103]
	v_mfma_f32_16x16x32_bf16 v[96:99], v[178:181], v[194:197], v[96:99]
	v_mfma_f32_16x16x32_bf16 v[84:87], v[170:173], v[202:205], v[84:87]
	v_mfma_f32_16x16x32_bf16 v[80:83], v[178:181], v[202:205], v[80:83]
	v_mfma_f32_16x16x32_bf16 v[68:71], v[170:173], v[210:213], v[68:71]
	v_mfma_f32_16x16x32_bf16 v[64:67], v[178:181], v[210:213], v[64:67]
	v_mfma_f32_16x16x32_bf16 v[116:119], v[174:177], v[190:193], v[116:119]
	v_mfma_f32_16x16x32_bf16 v[112:115], v[182:185], v[190:193], v[112:115]
	v_mfma_f32_16x16x32_bf16 v[100:103], v[174:177], v[198:201], v[100:103]
	v_mfma_f32_16x16x32_bf16 v[96:99], v[182:185], v[198:201], v[96:99]
	v_mfma_f32_16x16x32_bf16 v[84:87], v[174:177], v[206:209], v[84:87]
	v_mfma_f32_16x16x32_bf16 v[80:83], v[182:185], v[206:209], v[80:83]
	v_mfma_f32_16x16x32_bf16 v[68:71], v[174:177], v[214:217], v[68:71]
	v_mfma_f32_16x16x32_bf16 v[64:67], v[182:185], v[214:217], v[64:67]
	s_setprio 0
	s_barrier
	s_add_i32 s38, s69, s42
	v_lshl_add_u64 v[218:219], s[34:35], 0, v[130:131]
	s_mov_b32 m0, s38
	ds_read_b128 v[186:189], v161 offset:16384
	ds_read_b128 v[190:193], v161 offset:17408
	ds_read_b128 v[194:197], v161 offset:18432
	ds_read_b128 v[198:201], v161 offset:19456
	ds_read_b128 v[202:205], v161 offset:20480
	ds_read_b128 v[206:209], v161 offset:21504
	ds_read_b128 v[210:213], v161 offset:22528
	ds_read_b128 v[214:217], v161 offset:23552
	global_load_lds_dwordx4 v[218:219], off
	s_add_i32 m0, s38, 0x2000
	s_add_u32 s90, s34, 0x100000
	v_lshl_add_u64 v[220:221], s[34:35], 0, v[134:135]
	s_addc_u32 s91, s35, 0
	s_add_i32 s38, s70, s42
	global_load_lds_dwordx4 v[220:221], off
	v_lshl_add_u64 v[222:223], s[90:91], 0, v[130:131]
	s_mov_b32 m0, s38
	v_lshl_add_u64 v[226:227], s[36:37], 0, v[132:133]
	global_load_lds_dwordx4 v[222:223], off
	v_lshl_add_u64 v[222:223], s[90:91], 0, v[134:135]
	s_add_i32 m0, s38, 0x2000
	s_nop 0
	global_load_lds_dwordx4 v[222:223], off
	v_lshl_add_u64 v[222:223], s[36:37], 0, v[128:129]
	s_mov_b32 m0, s43
	s_nop 0
	global_load_lds_dwordx4 v[222:223], off
	s_mov_b32 m0, s56
	s_nop 0
	global_load_lds_dwordx4 v[226:227], off
	s_waitcnt vmcnt(8)
	s_waitcnt lgkmcnt(0)
	s_barrier
; #define PG8_STAGE(bufoff, gbase, voff) do { _Pragma("unroll") for (int _i = 0; _i < 2; ++_i) \
;         __builtin_amdgcn_global_load_lds((const unsigned*)((const char*)(gbase) + (voff)[_i]), (LAS unsigned*)(lds + (bufoff) + ldsw + _i * 8192), 16, 0, 0); } while (0)
; #define PG8_LDA(dst, b, h) do { _Pragma("unroll") for (int m = 0; m < 4; ++m) _Pragma("unroll") for (int k = 0; k < 2; ++k) dst[m][k] = *(const LAS bf16x8*)(lds + PG8_SA(b, h) + aoff + m * 2048 + k * 1024); } while (0)
; #define PG8_LDB(dst, b, h) do { _Pragma("unroll") for (int n = 0; n < 2; ++n) _Pragma("unroll") for (int k = 0; k < 2; ++k) dst[n][k] = *(const LAS bf16x8*)(lds + PG8_SB(b, h) + boff + n * 2048 + k * 1024); } while (0)
; #define PG8_MMA(ai, bj, At, Bt) do { __builtin_amdgcn_s_setprio(1); _Pragma("unroll") for (int m = 0; m < 4; ++m) _Pragma("unroll") for (int n = 0; n < 2; ++n) _Pragma("unroll") for (int k = 0; k < 2; ++k) \
;         acc[ai][bj][m][n] = __builtin_amdgcn_mfma_f32_16x16x32_bf16(Bt[n][k], At[m][k], acc[ai][bj][m][n], 0, 0, 0); __builtin_amdgcn_s_setprio(0); } while (0)
; #define PG8_WAIT_V(n) asm volatile("s_waitcnt vmcnt(" #n ")" ::: "memory")
; #define PG8_WAIT_L(n) asm volatile("s_waitcnt lgkmcnt(" #n ")" ::: "memory")
; #define PG8_BAR __builtin_amdgcn_s_barrier()
; #define PG8_SCHED __builtin_amdgcn_sched_barrier(0)
; template <class Epi, class Sched>
; DI void gemm_phase(LAS unsigned char* lds, const Gemm g, const Sched& S, const Epi& E) {
;     ...
;       PG8_WAIT_V(8); PG8_WAIT_L(0); PG8_BAR; PG8_MMA(1, 0, At, B0); PG8_MMA(1, 1, At, B1); PG8_BAR; PG8_SCHED;
;       PG8_LDB(B0, 1, 0); PG8_LDB(B1, 1, 1); PG8_SCHED; PG8_LDA(At, 1, 0); PG8_STAGE(PG8_SA(0, 1), a2 + hstepA, voffA);
;       PG8_WAIT_V(8); PG8_WAIT_L(0); PG8_BAR; PG8_MMA(0, 0, At, B0); PG8_MMA(0, 1, At, B1); PG8_BAR; PG8_SCHED;
	s_setprio 1
	s_waitcnt lgkmcnt(0)
	v_mfma_f32_16x16x32_bf16 v[60:63], v[146:149], v[186:189], v[60:63]
	v_mfma_f32_16x16x32_bf16 v[56:59], v[154:157], v[186:189], v[56:59]
	v_mfma_f32_16x16x32_bf16 v[44:47], v[146:149], v[194:197], v[44:47]
	v_mfma_f32_16x16x32_bf16 v[40:43], v[154:157], v[194:197], v[40:43]
	v_mfma_f32_16x16x32_bf16 v[28:31], v[146:149], v[202:205], v[28:31]
	v_mfma_f32_16x16x32_bf16 v[24:27], v[154:157], v[202:205], v[24:27]
	v_mfma_f32_16x16x32_bf16 v[12:15], v[146:149], v[210:213], v[12:15]
	v_mfma_f32_16x16x32_bf16 v[8:11], v[154:157], v[210:213], v[8:11]
	v_mfma_f32_16x16x32_bf16 v[60:63], v[150:153], v[190:193], v[60:63]
	v_mfma_f32_16x16x32_bf16 v[56:59], v[166:169], v[190:193], v[56:59]
	v_mfma_f32_16x16x32_bf16 v[44:47], v[150:153], v[198:201], v[44:47]
	v_mfma_f32_16x16x32_bf16 v[40:43], v[166:169], v[198:201], v[40:43]
	v_mfma_f32_16x16x32_bf16 v[28:31], v[150:153], v[206:209], v[28:31]
	v_mfma_f32_16x16x32_bf16 v[24:27], v[166:169], v[206:209], v[24:27]
	v_mfma_f32_16x16x32_bf16 v[12:15], v[150:153], v[214:217], v[12:15]
	v_mfma_f32_16x16x32_bf16 v[8:11], v[166:169], v[214:217], v[8:11]
	s_setprio 0
	s_setprio 1
	v_mfma_f32_16x16x32_bf16 v[52:55], v[170:173], v[186:189], v[52:55]
	v_mfma_f32_16x16x32_bf16 v[48:51], v[178:181], v[186:189], v[48:51]
	v_mfma_f32_16x16x32_bf16 v[36:39], v[170:173], v[194:197], v[36:39]
	v_mfma_f32_16x16x32_bf16 v[32:35], v[178:181], v[194:197], v[32:35]
	v_mfma_f32_16x16x32_bf16 v[20:23], v[170:173], v[202:205], v[20:23]
	v_mfma_f32_16x16x32_bf16 v[16:19], v[178:181], v[202:205], v[16:19]
	v_mfma_f32_16x16x32_bf16 v[4:7], v[170:173], v[210:213], v[4:7]
	v_mfma_f32_16x16x32_bf16 v[0:3], v[178:181], v[210:213], v[0:3]
	v_mfma_f32_16x16x32_bf16 v[52:55], v[174:177], v[190:193], v[52:55]
	v_mfma_f32_16x16x32_bf16 v[48:51], v[182:185], v[190:193], v[48:51]
	v_mfma_f32_16x16x32_bf16 v[36:39], v[174:177], v[198:201], v[36:39]
	v_mfma_f32_16x16x32_bf16 v[32:35], v[182:185], v[198:201], v[32:35]
	v_mfma_f32_16x16x32_bf16 v[20:23], v[174:177], v[206:209], v[20:23]
	v_mfma_f32_16x16x32_bf16 v[16:19], v[182:185], v[206:209], v[16:19]
	v_mfma_f32_16x16x32_bf16 v[4:7], v[174:177], v[214:217], v[4:7]
	v_mfma_f32_16x16x32_bf16 v[0:3], v[182:185], v[214:217], v[0:3]
	s_setprio 0
	s_barrier
	s_add_i32 s38, 0, 0x18000
	v_add_u32_e32 v136, s38, v158
	s_add_i32 s39, 0, 0x1c000
	ds_read_b128 v[146:149], v136
	ds_read_b128 v[150:153], v136 offset:1024
	ds_read_b128 v[154:157], v136 offset:2048
	ds_read_b128 v[166:169], v136 offset:3072
	v_add_u32_e32 v136, s39, v158
	ds_read_b128 v[170:173], v136
	ds_read_b128 v[174:177], v136 offset:1024
	ds_read_b128 v[178:181], v136 offset:2048
	ds_read_b128 v[182:185], v136 offset:3072
	s_add_u32 s36, s36, 0x100000
	s_addc_u32 s37, s37, 0
	s_mov_b32 m0, s57
	v_lshl_add_u64 v[228:229], s[36:37], 0, v[128:129]
	ds_read_b128 v[186:189], v161 offset:32768
	ds_read_b128 v[190:193], v161 offset:33792
	ds_read_b128 v[194:197], v161 offset:34816
	ds_read_b128 v[198:201], v161 offset:35840
	ds_read_b128 v[202:205], v161 offset:36864
	ds_read_b128 v[206:209], v161 offset:37888
	ds_read_b128 v[210:213], v161 offset:38912
	ds_read_b128 v[214:217], v161 offset:39936
	global_load_lds_dwordx4 v[228:229], off
	v_lshl_add_u64 v[228:229], s[36:37], 0, v[132:133]
	s_mov_b32 m0, s60
	s_nop 0
	global_load_lds_dwordx4 v[228:229], off
	s_waitcnt vmcnt(8)
	s_waitcnt lgkmcnt(0)
	s_barrier
	s_setprio 1
	s_waitcnt lgkmcnt(0)
	v_mfma_f32_16x16x32_bf16 v[124:127], v[146:149], v[186:189], v[124:127]
	v_mfma_f32_16x16x32_bf16 v[120:123], v[154:157], v[186:189], v[120:123]
	v_mfma_f32_16x16x32_bf16 v[108:111], v[146:149], v[194:197], v[108:111]
	v_mfma_f32_16x16x32_bf16 v[104:107], v[154:157], v[194:197], v[104:107]
	v_mfma_f32_16x16x32_bf16 v[92:95], v[146:149], v[202:205], v[92:95]
	v_mfma_f32_16x16x32_bf16 v[88:91], v[154:157], v[202:205], v[88:91]
	v_mfma_f32_16x16x32_bf16 v[76:79], v[146:149], v[210:213], v[76:79]
	v_mfma_f32_16x16x32_bf16 v[72:75], v[154:157], v[210:213], v[72:75]
	v_mfma_f32_16x16x32_bf16 v[124:127], v[150:153], v[190:193], v[124:127]
	v_mfma_f32_16x16x32_bf16 v[120:123], v[166:169], v[190:193], v[120:123]
	v_mfma_f32_16x16x32_bf16 v[108:111], v[150:153], v[198:201], v[108:111]
	v_mfma_f32_16x16x32_bf16 v[104:107], v[166:169], v[198:201], v[104:107]
	v_mfma_f32_16x16x32_bf16 v[92:95], v[150:153], v[206:209], v[92:95]
	v_mfma_f32_16x16x32_bf16 v[88:91], v[166:169], v[206:209], v[88:91]
	v_mfma_f32_16x16x32_bf16 v[76:79], v[150:153], v[214:217], v[76:79]
	v_mfma_f32_16x16x32_bf16 v[72:75], v[166:169], v[214:217], v[72:75]
	s_setprio 0
	s_setprio 1
	v_mfma_f32_16x16x32_bf16 v[116:119], v[170:173], v[186:189], v[116:119]
	v_mfma_f32_16x16x32_bf16 v[112:115], v[178:181], v[186:189], v[112:115]
	v_mfma_f32_16x16x32_bf16 v[100:103], v[170:173], v[194:197], v[100:103]
	v_mfma_f32_16x16x32_bf16 v[96:99], v[178:181], v[194:197], v[96:99]
	v_mfma_f32_16x16x32_bf16 v[84:87], v[170:173], v[202:205], v[84:87]
	v_mfma_f32_16x16x32_bf16 v[80:83], v[178:181], v[202:205], v[80:83]
	v_mfma_f32_16x16x32_bf16 v[68:71], v[170:173], v[210:213], v[68:71]
	v_mfma_f32_16x16x32_bf16 v[64:67], v[178:181], v[210:213], v[64:67]
	v_mfma_f32_16x16x32_bf16 v[116:119], v[174:177], v[190:193], v[116:119]
	v_mfma_f32_16x16x32_bf16 v[112:115], v[182:185], v[190:193], v[112:115]
	v_mfma_f32_16x16x32_bf16 v[100:103], v[174:177], v[198:201], v[100:103]
	v_mfma_f32_16x16x32_bf16 v[96:99], v[182:185], v[198:201], v[96:99]
	v_mfma_f32_16x16x32_bf16 v[84:87], v[174:177], v[206:209], v[84:87]
	v_mfma_f32_16x16x32_bf16 v[80:83], v[182:185], v[206:209], v[80:83]
	v_mfma_f32_16x16x32_bf16 v[68:71], v[174:177], v[214:217], v[68:71]
	v_mfma_f32_16x16x32_bf16 v[64:67], v[182:185], v[214:217], v[64:67]
	s_setprio 0
	s_barrier
; #define PG8_STAGE(bufoff, gbase, voff) do { _Pragma("unroll") for (int _i = 0; _i < 2; ++_i) \
;         __builtin_amdgcn_global_load_lds((const unsigned*)((const char*)(gbase) + (voff)[_i]), (LAS unsigned*)(lds + (bufoff) + ldsw + _i * 8192), 16, 0, 0); } while (0)
; #define PG8_LDA(dst, b, h) do { _Pragma("unroll") for (int m = 0; m < 4; ++m) _Pragma("unroll") for (int k = 0; k < 2; ++k) dst[m][k] = *(const LAS bf16x8*)(lds + PG8_SA(b, h) + aoff + m * 2048 + k * 1024); } while (0)
; #define PG8_MMA(ai, bj, At, Bt) do { __builtin_amdgcn_s_setprio(1); _Pragma("unroll") for (int m = 0; m < 4; ++m) _Pragma("unroll") for (int n = 0; n < 2; ++n) _Pragma("unroll") for (int k = 0; k < 2; ++k) \
;         acc[ai][bj][m][n] = __builtin_amdgcn_mfma_f32_16x16x32_bf16(Bt[n][k], At[m][k], acc[ai][bj][m][n], 0, 0, 0); __builtin_amdgcn_s_setprio(0); } while (0)
; #define PG8_WAIT_V(n) asm volatile("s_waitcnt vmcnt(" #n ")" ::: "memory")
; #define PG8_WAIT_L(n) asm volatile("s_waitcnt lgkmcnt(" #n ")" ::: "memory")
; #define PG8_BAR __builtin_amdgcn_s_barrier()
; #define PG8_SCHED __builtin_amdgcn_sched_barrier(0)
; template <class Epi, class Sched>
; DI void gemm_phase(LAS unsigned char* lds, const Gemm g, const Sched& S, const Epi& E) {
;     ...
;       PG8_LDA(At, 1, 1); PG8_STAGE(PG8_SB(1, 0), b3, voffB); PG8_STAGE(PG8_SB(1, 1), b3 + hstepB, voffB); PG8_STAGE(PG8_SA(1, 0), a3, voffA);
;       PG8_WAIT_V(8); PG8_WAIT_L(0); PG8_BAR; PG8_MMA(1, 0, At, B0); PG8_MMA(1, 1, At, B1); PG8_BAR; PG8_SCHED;
;     }
;     if (wr == 0) PG8_BAR;
	s_add_i32 s36, s38, s42
	v_lshl_add_u64 v[218:219], v[218:219], 0, s[12:13]
	s_mov_b32 m0, s36
	ds_read_b128 v[186:189], v161 offset:49152
	ds_read_b128 v[190:193], v161 offset:50176
	ds_read_b128 v[194:197], v161 offset:51200
	ds_read_b128 v[198:201], v161 offset:52224
	ds_read_b128 v[202:205], v161 offset:53248
	ds_read_b128 v[206:209], v161 offset:54272
	ds_read_b128 v[210:213], v161 offset:55296
	ds_read_b128 v[214:217], v161 offset:56320
	global_load_lds_dwordx4 v[218:219], off
	s_add_i32 m0, s36, 0x2000
	s_add_u32 s34, s34, 0x100080
	v_lshl_add_u64 v[218:219], v[220:221], 0, s[12:13]
	s_addc_u32 s35, s35, 0
	s_add_i32 s36, s39, s42
	global_load_lds_dwordx4 v[218:219], off
	v_lshl_add_u64 v[218:219], s[34:35], 0, v[130:131]
	s_mov_b32 m0, s36
	s_nop 0
	global_load_lds_dwordx4 v[218:219], off
	v_lshl_add_u64 v[218:219], s[34:35], 0, v[134:135]
	s_add_i32 m0, s36, 0x2000
	s_nop 0
	global_load_lds_dwordx4 v[218:219], off
	v_lshl_add_u64 v[218:219], v[222:223], 0, s[12:13]
	s_mov_b32 m0, s64
	s_nop 0
	global_load_lds_dwordx4 v[218:219], off
	v_lshl_add_u64 v[218:219], v[226:227], 0, s[12:13]
	s_mov_b32 m0, s65
	s_nop 0
	global_load_lds_dwordx4 v[218:219], off
	s_waitcnt vmcnt(8)
	s_waitcnt lgkmcnt(0)
	s_barrier
	s_setprio 1
	s_waitcnt lgkmcnt(0)
	v_mfma_f32_16x16x32_bf16 v[60:63], v[146:149], v[186:189], v[60:63]
	v_mfma_f32_16x16x32_bf16 v[56:59], v[154:157], v[186:189], v[56:59]
	v_mfma_f32_16x16x32_bf16 v[44:47], v[146:149], v[194:197], v[44:47]
	v_mfma_f32_16x16x32_bf16 v[40:43], v[154:157], v[194:197], v[40:43]
	v_mfma_f32_16x16x32_bf16 v[28:31], v[146:149], v[202:205], v[28:31]
	v_mfma_f32_16x16x32_bf16 v[24:27], v[154:157], v[202:205], v[24:27]
	v_mfma_f32_16x16x32_bf16 v[12:15], v[146:149], v[210:213], v[12:15]
	v_mfma_f32_16x16x32_bf16 v[8:11], v[154:157], v[210:213], v[8:11]
	v_mfma_f32_16x16x32_bf16 v[60:63], v[150:153], v[190:193], v[60:63]
	v_mfma_f32_16x16x32_bf16 v[56:59], v[166:169], v[190:193], v[56:59]
	v_mfma_f32_16x16x32_bf16 v[44:47], v[150:153], v[198:201], v[44:47]
	v_mfma_f32_16x16x32_bf16 v[40:43], v[166:169], v[198:201], v[40:43]
	v_mfma_f32_16x16x32_bf16 v[28:31], v[150:153], v[206:209], v[28:31]
	v_mfma_f32_16x16x32_bf16 v[24:27], v[166:169], v[206:209], v[24:27]
	v_mfma_f32_16x16x32_bf16 v[12:15], v[150:153], v[214:217], v[12:15]
	v_mfma_f32_16x16x32_bf16 v[8:11], v[166:169], v[214:217], v[8:11]
	s_setprio 0
	s_setprio 1
	v_mfma_f32_16x16x32_bf16 v[52:55], v[170:173], v[186:189], v[52:55]
	v_mfma_f32_16x16x32_bf16 v[48:51], v[178:181], v[186:189], v[48:51]
	v_mfma_f32_16x16x32_bf16 v[36:39], v[170:173], v[194:197], v[36:39]
	v_mfma_f32_16x16x32_bf16 v[32:35], v[178:181], v[194:197], v[32:35]
	v_mfma_f32_16x16x32_bf16 v[20:23], v[170:173], v[202:205], v[20:23]
	v_mfma_f32_16x16x32_bf16 v[16:19], v[178:181], v[202:205], v[16:19]
	v_mfma_f32_16x16x32_bf16 v[4:7], v[170:173], v[210:213], v[4:7]
	v_mfma_f32_16x16x32_bf16 v[0:3], v[178:181], v[210:213], v[0:3]
	v_mfma_f32_16x16x32_bf16 v[52:55], v[174:177], v[190:193], v[52:55]
	v_mfma_f32_16x16x32_bf16 v[48:51], v[182:185], v[190:193], v[48:51]
	v_mfma_f32_16x16x32_bf16 v[36:39], v[174:177], v[198:201], v[36:39]
	v_mfma_f32_16x16x32_bf16 v[32:35], v[182:185], v[198:201], v[32:35]
	v_mfma_f32_16x16x32_bf16 v[20:23], v[174:177], v[206:209], v[20:23]
	v_mfma_f32_16x16x32_bf16 v[16:19], v[182:185], v[206:209], v[16:19]
	v_mfma_f32_16x16x32_bf16 v[4:7], v[174:177], v[214:217], v[4:7]
	v_mfma_f32_16x16x32_bf16 v[0:3], v[182:185], v[214:217], v[0:3]
	s_setprio 0
	s_add_i32 s88, s88, 2
	s_add_u32 s86, s86, 0x100
	s_addc_u32 s87, s87, 0
	s_add_u32 s30, s30, 0x100
	s_addc_u32 s31, s31, 0
	s_cmp_gt_u32 s88, 61
	s_barrier
	s_cbranch_scc0 .LBB0_980
	s_and_b64 vcc, exec, s[14:15]
	s_cbranch_vccz .LBB0_983
	s_barrier

; #define PG8_STAGE(bufoff, gbase, voff) do { _Pragma("unroll") for (int _i = 0; _i < 2; ++_i) \
;         __builtin_amdgcn_global_load_lds((const unsigned*)((const char*)(gbase) + (voff)[_i]), (LAS unsigned*)(lds + (bufoff) + ldsw + _i * 8192), 16, 0, 0); } while (0)
; #define PG8_LDA(dst, b, h) do { _Pragma("unroll") for (int m = 0; m < 4; ++m) _Pragma("unroll") for (int k = 0; k < 2; ++k) dst[m][k] = *(const LAS bf16x8*)(lds + PG8_SA(b, h) + aoff + m * 2048 + k * 1024); } while (0)
; #define PG8_LDB(dst, b, h) do { _Pragma("unroll") for (int n = 0; n < 2; ++n) _Pragma("unroll") for (int k = 0; k < 2; ++k) dst[n][k] = *(const LAS bf16x8*)(lds + PG8_SB(b, h) + boff + n * 2048 + k * 1024); } while (0)
; #define PG8_MMA(ai, bj, At, Bt) do { __builtin_amdgcn_s_setprio(1); _Pragma("unroll") for (int m = 0; m < 4; ++m) _Pragma("unroll") for (int n = 0; n < 2; ++n) _Pragma("unroll") for (int k = 0; k < 2; ++k) \
;         acc[ai][bj][m][n] = __builtin_amdgcn_mfma_f32_16x16x32_bf16(Bt[n][k], At[m][k], acc[ai][bj][m][n], 0, 0, 0); __builtin_amdgcn_s_setprio(0); } while (0)
; #define PG8_WAIT_V(n) asm volatile("s_waitcnt vmcnt(" #n ")" ::: "memory")
; #define PG8_WAIT_L(n) asm volatile("s_waitcnt lgkmcnt(" #n ")" ::: "memory")
; #define PG8_BAR __builtin_amdgcn_s_barrier()
; #define PG8_SCHED __builtin_amdgcn_sched_barrier(0)
; template <class Epi, class Sched>
; DI void gemm_phase(LAS unsigned char* lds, const Gemm g, const Sched& S, const Epi& E) {
;     ...
;     for (int t = 0; t < nt; t += 2) {
;       const bool last = (t == nt - 2);
;       const char* a1 = cA + (size_t)(t + 1) * kstep;
;       const char* a2 = last ? nA : cA + (size_t)(t + 2) * kstep; const char* b2 = last ? nB : cB + (size_t)(t + 2) * kstep;
;       const char* a3 = a2 + kstep; const char* b3 = b2 + kstep;
;       PG8_LDB(B0, 0, 0); PG8_LDB(B1, 0, 1); PG8_SCHED; PG8_LDA(At, 0, 0); PG8_STAGE(PG8_SA(1, 1), a1 + hstepA, voffA);
;       PG8_WAIT_V(8); PG8_WAIT_L(0); PG8_BAR; PG8_MMA(0, 0, At, B0); PG8_MMA(0, 1, At, B1); PG8_BAR; PG8_SCHED;
;       PG8_LDA(At, 0, 1); PG8_STAGE(PG8_SB(0, 0), b2, voffB); PG8_STAGE(PG8_SB(0, 1), b2 + hstepB, voffB); PG8_STAGE(PG8_SA(0, 0), a2, voffA);
;       PG8_WAIT_V(8); PG8_WAIT_L(0); PG8_BAR; PG8_MMA(1, 0, At, B0); PG8_MMA(1, 1, At, B1); PG8_BAR; PG8_SCHED;
.LBB0_1680:
	ds_read_b128 v[152:155], v147
	ds_read_b128 v[156:159], v147 offset:1024
	ds_read_b128 v[160:163], v147 offset:2048
	ds_read_b128 v[164:167], v147 offset:3072
	ds_read_b128 v[168:171], v148
	ds_read_b128 v[172:175], v148 offset:1024
	ds_read_b128 v[176:179], v148 offset:2048
	ds_read_b128 v[180:183], v148 offset:3072
	s_add_u32 s26, s24, 0xfffc0080
	s_addc_u32 s27, s25, -1
	s_cmp_eq_u32 s71, 12
	s_cselect_b32 s29, s15, s27
	s_cselect_b32 s28, s67, s26
	s_cselect_b32 s27, s13, s70
	s_cselect_b32 s26, s68, s69
	v_lshl_add_u64 v[144:145], s[24:25], 0, v[138:139]
	s_add_i32 m0, s23, 0xc000
	ds_read_b128 v[184:187], v149
	ds_read_b128 v[188:191], v149 offset:1024
	ds_read_b128 v[192:195], v149 offset:2048
	ds_read_b128 v[196:199], v149 offset:3072
	ds_read_b128 v[200:203], v149 offset:4096
	ds_read_b128 v[204:207], v149 offset:5120
	ds_read_b128 v[208:211], v149 offset:6144
	ds_read_b128 v[212:215], v149 offset:7168
	global_load_lds_dwordx4 v[144:145], off
	v_lshl_add_u64 v[144:145], s[24:25], 0, v[136:137]
	s_add_i32 m0, s23, 0xe000
	s_nop 0
	global_load_lds_dwordx4 v[144:145], off
	s_waitcnt vmcnt(8)
	s_waitcnt lgkmcnt(0)
	s_barrier
	s_setprio 1
	s_waitcnt lgkmcnt(0)
	v_mfma_f32_16x16x32_bf16 v[124:127], v[152:155], v[184:187], v[124:127]
	v_mfma_f32_16x16x32_bf16 v[120:123], v[160:163], v[184:187], v[120:123]
	v_mfma_f32_16x16x32_bf16 v[108:111], v[152:155], v[192:195], v[108:111]
	v_mfma_f32_16x16x32_bf16 v[104:107], v[160:163], v[192:195], v[104:107]
	v_mfma_f32_16x16x32_bf16 v[92:95], v[152:155], v[200:203], v[92:95]
	v_mfma_f32_16x16x32_bf16 v[88:91], v[160:163], v[200:203], v[88:91]
	v_mfma_f32_16x16x32_bf16 v[76:79], v[152:155], v[208:211], v[76:79]
	v_mfma_f32_16x16x32_bf16 v[72:75], v[160:163], v[208:211], v[72:75]
	v_mfma_f32_16x16x32_bf16 v[124:127], v[156:159], v[188:191], v[124:127]
	v_mfma_f32_16x16x32_bf16 v[120:123], v[164:167], v[188:191], v[120:123]
	v_mfma_f32_16x16x32_bf16 v[108:111], v[156:159], v[196:199], v[108:111]
	v_mfma_f32_16x16x32_bf16 v[104:107], v[164:167], v[196:199], v[104:107]
	v_mfma_f32_16x16x32_bf16 v[92:95], v[156:159], v[204:207], v[92:95]
	v_mfma_f32_16x16x32_bf16 v[88:91], v[164:167], v[204:207], v[88:91]
	v_mfma_f32_16x16x32_bf16 v[76:79], v[156:159], v[212:215], v[76:79]
	v_mfma_f32_16x16x32_bf16 v[72:75], v[164:167], v[212:215], v[72:75]
	s_setprio 0
	s_setprio 1
	v_mfma_f32_16x16x32_bf16 v[116:119], v[168:171], v[184:187], v[116:119]
	v_mfma_f32_16x16x32_bf16 v[112:115], v[176:179], v[184:187], v[112:115]
	v_mfma_f32_16x16x32_bf16 v[100:103], v[168:171], v[192:195], v[100:103]
	v_mfma_f32_16x16x32_bf16 v[96:99], v[176:179], v[192:195], v[96:99]
	v_mfma_f32_16x16x32_bf16 v[84:87], v[168:171], v[200:203], v[84:87]
	v_mfma_f32_16x16x32_bf16 v[80:83], v[176:179], v[200:203], v[80:83]
	v_mfma_f32_16x16x32_bf16 v[68:71], v[168:171], v[208:211], v[68:71]
	v_mfma_f32_16x16x32_bf16 v[64:67], v[176:179], v[208:211], v[64:67]
	v_mfma_f32_16x16x32_bf16 v[116:119], v[172:175], v[188:191], v[116:119]
	v_mfma_f32_16x16x32_bf16 v[112:115], v[180:183], v[188:191], v[112:115]
	v_mfma_f32_16x16x32_bf16 v[100:103], v[172:175], v[196:199], v[100:103]
	v_mfma_f32_16x16x32_bf16 v[96:99], v[180:183], v[196:199], v[96:99]
	v_mfma_f32_16x16x32_bf16 v[84:87], v[172:175], v[204:207], v[84:87]
	v_mfma_f32_16x16x32_bf16 v[80:83], v[180:183], v[204:207], v[80:83]
	v_mfma_f32_16x16x32_bf16 v[68:71], v[172:175], v[212:215], v[68:71]
	v_mfma_f32_16x16x32_bf16 v[64:67], v[180:183], v[212:215], v[64:67]
	s_setprio 0
	s_barrier
	s_add_i32 s38, s64, s17
	v_lshl_add_u64 v[144:145], s[26:27], 0, v[132:133]
	s_mov_b32 m0, s38
	ds_read_b128 v[184:187], v149 offset:16384
	ds_read_b128 v[188:191], v149 offset:17408
	ds_read_b128 v[192:195], v149 offset:18432
	ds_read_b128 v[196:199], v149 offset:19456
	ds_read_b128 v[200:203], v149 offset:20480
	ds_read_b128 v[204:207], v149 offset:21504
	ds_read_b128 v[208:211], v149 offset:22528
	ds_read_b128 v[212:215], v149 offset:23552
	global_load_lds_dwordx4 v[144:145], off
	s_add_i32 m0, s38, 0x2000
	s_add_u32 s72, s26, 0x40000
	v_lshl_add_u64 v[216:217], s[26:27], 0, v[128:129]
	s_addc_u32 s73, s27, 0
	s_add_i32 s38, s65, s17
	global_load_lds_dwordx4 v[216:217], off
	v_lshl_add_u64 v[218:219], s[72:73], 0, v[132:133]
	s_mov_b32 m0, s38
	v_lshl_add_u64 v[220:221], s[28:29], 0, v[130:131]
	global_load_lds_dwordx4 v[218:219], off
	v_lshl_add_u64 v[218:219], s[72:73], 0, v[128:129]
	s_add_i32 m0, s38, 0x2000
	s_nop 0
	global_load_lds_dwordx4 v[218:219], off
	v_lshl_add_u64 v[218:219], s[28:29], 0, v[134:135]
	s_mov_b32 m0, s23
	s_nop 0
	global_load_lds_dwordx4 v[218:219], off
	s_mov_b32 m0, s33
	s_nop 0
	global_load_lds_dwordx4 v[220:221], off
	s_waitcnt vmcnt(8)
	s_waitcnt lgkmcnt(0)
	s_barrier
; #define PG8_STAGE(bufoff, gbase, voff) do { _Pragma("unroll") for (int _i = 0; _i < 2; ++_i) \
;         __builtin_amdgcn_global_load_lds((const unsigned*)((const char*)(gbase) + (voff)[_i]), (LAS unsigned*)(lds + (bufoff) + ldsw + _i * 8192), 16, 0, 0); } while (0)
; #define PG8_LDA(dst, b, h) do { _Pragma("unroll") for (int m = 0; m < 4; ++m) _Pragma("unroll") for (int k = 0; k < 2; ++k) dst[m][k] = *(const LAS bf16x8*)(lds + PG8_SA(b, h) + aoff + m * 2048 + k * 1024); } while (0)
; #define PG8_LDB(dst, b, h) do { _Pragma("unroll") for (int n = 0; n < 2; ++n) _Pragma("unroll") for (int k = 0; k < 2; ++k) dst[n][k] = *(const LAS bf16x8*)(lds + PG8_SB(b, h) + boff + n * 2048 + k * 1024); } while (0)
; #define PG8_MMA(ai, bj, At, Bt) do { __builtin_amdgcn_s_setprio(1); _Pragma("unroll") for (int m = 0; m < 4; ++m) _Pragma("unroll") for (int n = 0; n < 2; ++n) _Pragma("unroll") for (int k = 0; k < 2; ++k) \
;         acc[ai][bj][m][n] = __builtin_amdgcn_mfma_f32_16x16x32_bf16(Bt[n][k], At[m][k], acc[ai][bj][m][n], 0, 0, 0); __builtin_amdgcn_s_setprio(0); } while (0)
; #define PG8_WAIT_V(n) asm volatile("s_waitcnt vmcnt(" #n ")" ::: "memory")
; #define PG8_WAIT_L(n) asm volatile("s_waitcnt lgkmcnt(" #n ")" ::: "memory")
; #define PG8_BAR __builtin_amdgcn_s_barrier()
; #define PG8_SCHED __builtin_amdgcn_sched_barrier(0)
; template <class Epi, class Sched>
; DI void gemm_phase(LAS unsigned char* lds, const Gemm g, const Sched& S, const Epi& E) {
;     ...
;       PG8_WAIT_V(8); PG8_WAIT_L(0); PG8_BAR; PG8_MMA(1, 0, At, B0); PG8_MMA(1, 1, At, B1); PG8_BAR; PG8_SCHED;
;       PG8_LDB(B0, 1, 0); PG8_LDB(B1, 1, 1); PG8_SCHED; PG8_LDA(At, 1, 0); PG8_STAGE(PG8_SA(0, 1), a2 + hstepA, voffA);
;       PG8_WAIT_V(8); PG8_WAIT_L(0); PG8_BAR; PG8_MMA(0, 0, At, B0); PG8_MMA(0, 1, At, B1); PG8_BAR; PG8_SCHED;
	s_setprio 1
	s_waitcnt lgkmcnt(0)
	v_mfma_f32_16x16x32_bf16 v[60:63], v[152:155], v[184:187], v[60:63]
	v_mfma_f32_16x16x32_bf16 v[56:59], v[160:163], v[184:187], v[56:59]
	v_mfma_f32_16x16x32_bf16 v[44:47], v[152:155], v[192:195], v[44:47]
	v_mfma_f32_16x16x32_bf16 v[40:43], v[160:163], v[192:195], v[40:43]
	v_mfma_f32_16x16x32_bf16 v[28:31], v[152:155], v[200:203], v[28:31]
	v_mfma_f32_16x16x32_bf16 v[24:27], v[160:163], v[200:203], v[24:27]
	v_mfma_f32_16x16x32_bf16 v[12:15], v[152:155], v[208:211], v[12:15]
	v_mfma_f32_16x16x32_bf16 v[8:11], v[160:163], v[208:211], v[8:11]
	v_mfma_f32_16x16x32_bf16 v[60:63], v[156:159], v[188:191], v[60:63]
	v_mfma_f32_16x16x32_bf16 v[56:59], v[164:167], v[188:191], v[56:59]
	v_mfma_f32_16x16x32_bf16 v[44:47], v[156:159], v[196:199], v[44:47]
	v_mfma_f32_16x16x32_bf16 v[40:43], v[164:167], v[196:199], v[40:43]
	v_mfma_f32_16x16x32_bf16 v[28:31], v[156:159], v[204:207], v[28:31]
	v_mfma_f32_16x16x32_bf16 v[24:27], v[164:167], v[204:207], v[24:27]
	v_mfma_f32_16x16x32_bf16 v[12:15], v[156:159], v[212:215], v[12:15]
	v_mfma_f32_16x16x32_bf16 v[8:11], v[164:167], v[212:215], v[8:11]
	s_setprio 0
	s_setprio 1
	v_mfma_f32_16x16x32_bf16 v[52:55], v[168:171], v[184:187], v[52:55]
	v_mfma_f32_16x16x32_bf16 v[48:51], v[176:179], v[184:187], v[48:51]
	v_mfma_f32_16x16x32_bf16 v[36:39], v[168:171], v[192:195], v[36:39]
	v_mfma_f32_16x16x32_bf16 v[32:35], v[176:179], v[192:195], v[32:35]
	v_mfma_f32_16x16x32_bf16 v[20:23], v[168:171], v[200:203], v[20:23]
	v_mfma_f32_16x16x32_bf16 v[16:19], v[176:179], v[200:203], v[16:19]
	v_mfma_f32_16x16x32_bf16 v[4:7], v[168:171], v[208:211], v[4:7]
	v_mfma_f32_16x16x32_bf16 v[0:3], v[176:179], v[208:211], v[0:3]
	v_mfma_f32_16x16x32_bf16 v[52:55], v[172:175], v[188:191], v[52:55]
	v_mfma_f32_16x16x32_bf16 v[48:51], v[180:183], v[188:191], v[48:51]
	v_mfma_f32_16x16x32_bf16 v[36:39], v[172:175], v[196:199], v[36:39]
	v_mfma_f32_16x16x32_bf16 v[32:35], v[180:183], v[196:199], v[32:35]
	v_mfma_f32_16x16x32_bf16 v[20:23], v[172:175], v[204:207], v[20:23]
	v_mfma_f32_16x16x32_bf16 v[16:19], v[180:183], v[204:207], v[16:19]
	v_mfma_f32_16x16x32_bf16 v[4:7], v[172:175], v[212:215], v[4:7]
	v_mfma_f32_16x16x32_bf16 v[0:3], v[180:183], v[212:215], v[0:3]
	s_setprio 0
	s_barrier
	s_add_i32 s38, 0, 0x18000
	v_add_u32_e32 v151, s38, v146
	s_add_i32 s39, 0, 0x1c000
	ds_read_b128 v[152:155], v151
	ds_read_b128 v[156:159], v151 offset:1024
	ds_read_b128 v[160:163], v151 offset:2048
	ds_read_b128 v[164:167], v151 offset:3072
	v_add_u32_e32 v151, s39, v146
	ds_read_b128 v[168:171], v151
	ds_read_b128 v[172:175], v151 offset:1024
	ds_read_b128 v[176:179], v151 offset:2048
	ds_read_b128 v[180:183], v151 offset:3072
	s_add_u32 s28, s28, 0x40000
	s_addc_u32 s29, s29, 0
	s_mov_b32 m0, s34
	v_lshl_add_u64 v[222:223], s[28:29], 0, v[134:135]
	ds_read_b128 v[184:187], v149 offset:32768
	ds_read_b128 v[188:191], v149 offset:33792
	ds_read_b128 v[192:195], v149 offset:34816
	ds_read_b128 v[196:199], v149 offset:35840
	ds_read_b128 v[200:203], v149 offset:36864
	ds_read_b128 v[204:207], v149 offset:37888
	ds_read_b128 v[208:211], v149 offset:38912
	ds_read_b128 v[212:215], v149 offset:39936
	global_load_lds_dwordx4 v[222:223], off
	v_lshl_add_u64 v[222:223], s[28:29], 0, v[130:131]
	s_mov_b32 m0, s35
	s_nop 0
	global_load_lds_dwordx4 v[222:223], off
	s_waitcnt vmcnt(8)
	s_waitcnt lgkmcnt(0)
	s_barrier
	s_setprio 1
	s_waitcnt lgkmcnt(0)
	v_mfma_f32_16x16x32_bf16 v[124:127], v[152:155], v[184:187], v[124:127]
	v_mfma_f32_16x16x32_bf16 v[120:123], v[160:163], v[184:187], v[120:123]
	v_mfma_f32_16x16x32_bf16 v[108:111], v[152:155], v[192:195], v[108:111]
	v_mfma_f32_16x16x32_bf16 v[104:107], v[160:163], v[192:195], v[104:107]
	v_mfma_f32_16x16x32_bf16 v[92:95], v[152:155], v[200:203], v[92:95]
	v_mfma_f32_16x16x32_bf16 v[88:91], v[160:163], v[200:203], v[88:91]
	v_mfma_f32_16x16x32_bf16 v[76:79], v[152:155], v[208:211], v[76:79]
	v_mfma_f32_16x16x32_bf16 v[72:75], v[160:163], v[208:211], v[72:75]
	v_mfma_f32_16x16x32_bf16 v[124:127], v[156:159], v[188:191], v[124:127]
	v_mfma_f32_16x16x32_bf16 v[120:123], v[164:167], v[188:191], v[120:123]
	v_mfma_f32_16x16x32_bf16 v[108:111], v[156:159], v[196:199], v[108:111]
	v_mfma_f32_16x16x32_bf16 v[104:107], v[164:167], v[196:199], v[104:107]
	v_mfma_f32_16x16x32_bf16 v[92:95], v[156:159], v[204:207], v[92:95]
	v_mfma_f32_16x16x32_bf16 v[88:91], v[164:167], v[204:207], v[88:91]
	v_mfma_f32_16x16x32_bf16 v[76:79], v[156:159], v[212:215], v[76:79]
	v_mfma_f32_16x16x32_bf16 v[72:75], v[164:167], v[212:215], v[72:75]
	s_setprio 0
	s_setprio 1
	v_mfma_f32_16x16x32_bf16 v[116:119], v[168:171], v[184:187], v[116:119]
	v_mfma_f32_16x16x32_bf16 v[112:115], v[176:179], v[184:187], v[112:115]
	v_mfma_f32_16x16x32_bf16 v[100:103], v[168:171], v[192:195], v[100:103]
	v_mfma_f32_16x16x32_bf16 v[96:99], v[176:179], v[192:195], v[96:99]
	v_mfma_f32_16x16x32_bf16 v[84:87], v[168:171], v[200:203], v[84:87]
	v_mfma_f32_16x16x32_bf16 v[80:83], v[176:179], v[200:203], v[80:83]
	v_mfma_f32_16x16x32_bf16 v[68:71], v[168:171], v[208:211], v[68:71]
	v_mfma_f32_16x16x32_bf16 v[64:67], v[176:179], v[208:211], v[64:67]
	v_mfma_f32_16x16x32_bf16 v[116:119], v[172:175], v[188:191], v[116:119]
	v_mfma_f32_16x16x32_bf16 v[112:115], v[180:183], v[188:191], v[112:115]
	v_mfma_f32_16x16x32_bf16 v[100:103], v[172:175], v[196:199], v[100:103]
	v_mfma_f32_16x16x32_bf16 v[96:99], v[180:183], v[196:199], v[96:99]
	v_mfma_f32_16x16x32_bf16 v[84:87], v[172:175], v[204:207], v[84:87]
	v_mfma_f32_16x16x32_bf16 v[80:83], v[180:183], v[204:207], v[80:83]
	v_mfma_f32_16x16x32_bf16 v[68:71], v[172:175], v[212:215], v[68:71]
	v_mfma_f32_16x16x32_bf16 v[64:67], v[180:183], v[212:215], v[64:67]
	s_setprio 0
	s_barrier
; #define PG8_STAGE(bufoff, gbase, voff) do { _Pragma("unroll") for (int _i = 0; _i < 2; ++_i) \
;         __builtin_amdgcn_global_load_lds((const unsigned*)((const char*)(gbase) + (voff)[_i]), (LAS unsigned*)(lds + (bufoff) + ldsw + _i * 8192), 16, 0, 0); } while (0)
; #define PG8_LDA(dst, b, h) do { _Pragma("unroll") for (int m = 0; m < 4; ++m) _Pragma("unroll") for (int k = 0; k < 2; ++k) dst[m][k] = *(const LAS bf16x8*)(lds + PG8_SA(b, h) + aoff + m * 2048 + k * 1024); } while (0)
; #define PG8_MMA(ai, bj, At, Bt) do { __builtin_amdgcn_s_setprio(1); _Pragma("unroll") for (int m = 0; m < 4; ++m) _Pragma("unroll") for (int n = 0; n < 2; ++n) _Pragma("unroll") for (int k = 0; k < 2; ++k) \
;         acc[ai][bj][m][n] = __builtin_amdgcn_mfma_f32_16x16x32_bf16(Bt[n][k], At[m][k], acc[ai][bj][m][n], 0, 0, 0); __builtin_amdgcn_s_setprio(0); } while (0)
; #define PG8_WAIT_V(n) asm volatile("s_waitcnt vmcnt(" #n ")" ::: "memory")
; #define PG8_WAIT_L(n) asm volatile("s_waitcnt lgkmcnt(" #n ")" ::: "memory")
; #define PG8_BAR __builtin_amdgcn_s_barrier()
; #define PG8_SCHED __builtin_amdgcn_sched_barrier(0)
; template <class Epi, class Sched>
; DI void gemm_phase(LAS unsigned char* lds, const Gemm g, const Sched& S, const Epi& E) {
;     ...
;       PG8_LDA(At, 1, 1); PG8_STAGE(PG8_SB(1, 0), b3, voffB); PG8_STAGE(PG8_SB(1, 1), b3 + hstepB, voffB); PG8_STAGE(PG8_SA(1, 0), a3, voffA);
;       PG8_WAIT_V(8); PG8_WAIT_L(0); PG8_BAR; PG8_MMA(1, 0, At, B0); PG8_MMA(1, 1, At, B1); PG8_BAR; PG8_SCHED;
;     }
;     if (wr == 0) PG8_BAR;
	s_add_i32 s28, s38, s17
	v_lshl_add_u64 v[144:145], v[144:145], 0, s[8:9]
	s_mov_b32 m0, s28
	ds_read_b128 v[184:187], v149 offset:49152
	ds_read_b128 v[188:191], v149 offset:50176
	ds_read_b128 v[192:195], v149 offset:51200
	ds_read_b128 v[196:199], v149 offset:52224
	ds_read_b128 v[200:203], v149 offset:53248
	ds_read_b128 v[204:207], v149 offset:54272
	ds_read_b128 v[208:211], v149 offset:55296
	ds_read_b128 v[212:215], v149 offset:56320
	global_load_lds_dwordx4 v[144:145], off
	s_add_i32 m0, s28, 0x2000
	s_add_u32 s26, s26, 0x40080
	v_lshl_add_u64 v[144:145], v[216:217], 0, s[8:9]
	s_addc_u32 s27, s27, 0
	s_add_i32 s28, s39, s17
	global_load_lds_dwordx4 v[144:145], off
	v_lshl_add_u64 v[144:145], s[26:27], 0, v[132:133]
	s_mov_b32 m0, s28
	s_nop 0
	global_load_lds_dwordx4 v[144:145], off
	v_lshl_add_u64 v[144:145], s[26:27], 0, v[128:129]
	s_add_i32 m0, s28, 0x2000
	s_nop 0
	global_load_lds_dwordx4 v[144:145], off
	v_lshl_add_u64 v[144:145], v[218:219], 0, s[8:9]
	s_mov_b32 m0, s42
	s_nop 0
	global_load_lds_dwordx4 v[144:145], off
	v_lshl_add_u64 v[144:145], v[220:221], 0, s[8:9]
	s_mov_b32 m0, s43
	s_nop 0
	global_load_lds_dwordx4 v[144:145], off
	s_waitcnt vmcnt(8)
	s_waitcnt lgkmcnt(0)
	s_barrier
	s_setprio 1
	s_waitcnt lgkmcnt(0)
	v_mfma_f32_16x16x32_bf16 v[60:63], v[152:155], v[184:187], v[60:63]
	v_mfma_f32_16x16x32_bf16 v[56:59], v[160:163], v[184:187], v[56:59]
	v_mfma_f32_16x16x32_bf16 v[44:47], v[152:155], v[192:195], v[44:47]
	v_mfma_f32_16x16x32_bf16 v[40:43], v[160:163], v[192:195], v[40:43]
	v_mfma_f32_16x16x32_bf16 v[28:31], v[152:155], v[200:203], v[28:31]
	v_mfma_f32_16x16x32_bf16 v[24:27], v[160:163], v[200:203], v[24:27]
	v_mfma_f32_16x16x32_bf16 v[12:15], v[152:155], v[208:211], v[12:15]
	v_mfma_f32_16x16x32_bf16 v[8:11], v[160:163], v[208:211], v[8:11]
	v_mfma_f32_16x16x32_bf16 v[60:63], v[156:159], v[188:191], v[60:63]
	v_mfma_f32_16x16x32_bf16 v[56:59], v[164:167], v[188:191], v[56:59]
	v_mfma_f32_16x16x32_bf16 v[44:47], v[156:159], v[196:199], v[44:47]
	v_mfma_f32_16x16x32_bf16 v[40:43], v[164:167], v[196:199], v[40:43]
	v_mfma_f32_16x16x32_bf16 v[28:31], v[156:159], v[204:207], v[28:31]
	v_mfma_f32_16x16x32_bf16 v[24:27], v[164:167], v[204:207], v[24:27]
	v_mfma_f32_16x16x32_bf16 v[12:15], v[156:159], v[212:215], v[12:15]
	v_mfma_f32_16x16x32_bf16 v[8:11], v[164:167], v[212:215], v[8:11]
	s_setprio 0
	s_setprio 1
	v_mfma_f32_16x16x32_bf16 v[52:55], v[168:171], v[184:187], v[52:55]
	v_mfma_f32_16x16x32_bf16 v[48:51], v[176:179], v[184:187], v[48:51]
	v_mfma_f32_16x16x32_bf16 v[36:39], v[168:171], v[192:195], v[36:39]
	v_mfma_f32_16x16x32_bf16 v[32:35], v[176:179], v[192:195], v[32:35]
	v_mfma_f32_16x16x32_bf16 v[20:23], v[168:171], v[200:203], v[20:23]
	v_mfma_f32_16x16x32_bf16 v[16:19], v[176:179], v[200:203], v[16:19]
	v_mfma_f32_16x16x32_bf16 v[4:7], v[168:171], v[208:211], v[4:7]
	v_mfma_f32_16x16x32_bf16 v[0:3], v[176:179], v[208:211], v[0:3]
	v_mfma_f32_16x16x32_bf16 v[52:55], v[172:175], v[188:191], v[52:55]
	v_mfma_f32_16x16x32_bf16 v[48:51], v[180:183], v[188:191], v[48:51]
	v_mfma_f32_16x16x32_bf16 v[36:39], v[172:175], v[196:199], v[36:39]
	v_mfma_f32_16x16x32_bf16 v[32:35], v[180:183], v[196:199], v[32:35]
	v_mfma_f32_16x16x32_bf16 v[20:23], v[172:175], v[204:207], v[20:23]
	v_mfma_f32_16x16x32_bf16 v[16:19], v[180:183], v[204:207], v[16:19]
	v_mfma_f32_16x16x32_bf16 v[4:7], v[172:175], v[212:215], v[4:7]
	v_mfma_f32_16x16x32_bf16 v[0:3], v[180:183], v[212:215], v[0:3]
	s_setprio 0
	s_add_i32 s71, s71, 2
	s_add_u32 s69, s69, 0x100
	s_addc_u32 s70, s70, 0
	s_add_u32 s24, s24, 0x100
	s_addc_u32 s25, s25, 0
	s_cmp_gt_u32 s71, 13
	s_barrier
	s_cbranch_scc0 .LBB0_1680
	s_and_b64 vcc, exec, s[10:11]
	s_cbranch_vccz .LBB0_1683
	s_barrier

; #define PG8_STAGE(bufoff, gbase, voff) do { _Pragma("unroll") for (int _i = 0; _i < 2; ++_i) \
;         __builtin_amdgcn_global_load_lds((const unsigned*)((const char*)(gbase) + (voff)[_i]), (LAS unsigned*)(lds + (bufoff) + ldsw + _i * 8192), 16, 0, 0); } while (0)
; #define PG8_LDA(dst, b, h) do { _Pragma("unroll") for (int m = 0; m < 4; ++m) _Pragma("unroll") for (int k = 0; k < 2; ++k) dst[m][k] = *(const LAS bf16x8*)(lds + PG8_SA(b, h) + aoff + m * 2048 + k * 1024); } while (0)
; #define PG8_LDB(dst, b, h) do { _Pragma("unroll") for (int n = 0; n < 2; ++n) _Pragma("unroll") for (int k = 0; k < 2; ++k) dst[n][k] = *(const LAS bf16x8*)(lds + PG8_SB(b, h) + boff + n * 2048 + k * 1024); } while (0)
; #define PG8_MMA(ai, bj, At, Bt) do { __builtin_amdgcn_s_setprio(1); _Pragma("unroll") for (int m = 0; m < 4; ++m) _Pragma("unroll") for (int n = 0; n < 2; ++n) _Pragma("unroll") for (int k = 0; k < 2; ++k) \
;         acc[ai][bj][m][n] = __builtin_amdgcn_mfma_f32_16x16x32_bf16(Bt[n][k], At[m][k], acc[ai][bj][m][n], 0, 0, 0); __builtin_amdgcn_s_setprio(0); } while (0)
; #define PG8_WAIT_V(n) asm volatile("s_waitcnt vmcnt(" #n ")" ::: "memory")
; #define PG8_WAIT_L(n) asm volatile("s_waitcnt lgkmcnt(" #n ")" ::: "memory")
; #define PG8_BAR __builtin_amdgcn_s_barrier()
; #define PG8_SCHED __builtin_amdgcn_sched_barrier(0)
; template <class Epi, class Sched>
; DI void gemm_phase(LAS unsigned char* lds, const Gemm g, const Sched& S, const Epi& E) {
;     ...
;     for (int t = 0; t < nt; t += 2) {
;       const bool last = (t == nt - 2);
;       const char* a1 = cA + (size_t)(t + 1) * kstep;
;       const char* a2 = last ? nA : cA + (size_t)(t + 2) * kstep; const char* b2 = last ? nB : cB + (size_t)(t + 2) * kstep;
;       const char* a3 = a2 + kstep; const char* b3 = b2 + kstep;
;       PG8_LDB(B0, 0, 0); PG8_LDB(B1, 0, 1); PG8_SCHED; PG8_LDA(At, 0, 0); PG8_STAGE(PG8_SA(1, 1), a1 + hstepA, voffA);
;       PG8_WAIT_V(8); PG8_WAIT_L(0); PG8_BAR; PG8_MMA(0, 0, At, B0); PG8_MMA(0, 1, At, B1); PG8_BAR; PG8_SCHED;
;       PG8_LDA(At, 0, 1); PG8_STAGE(PG8_SB(0, 0), b2, voffB); PG8_STAGE(PG8_SB(0, 1), b2 + hstepB, voffB); PG8_STAGE(PG8_SA(0, 0), a2, voffA);
;       PG8_WAIT_V(8); PG8_WAIT_L(0); PG8_BAR; PG8_MMA(1, 0, At, B0); PG8_MMA(1, 1, At, B1); PG8_BAR; PG8_SCHED;
.LBB0_1856:
	ds_read_b128 v[146:149], v157
	ds_read_b128 v[150:153], v157 offset:1024
	ds_read_b128 v[164:167], v157 offset:2048
	ds_read_b128 v[168:171], v157 offset:3072
	ds_read_b128 v[172:175], v158
	ds_read_b128 v[176:179], v158 offset:1024
	ds_read_b128 v[180:183], v158 offset:2048
	ds_read_b128 v[184:187], v158 offset:3072
	s_add_u32 s10, s8, 0xfff00080
	s_addc_u32 s11, s9, -1
	s_cmp_eq_u32 s92, 60
	s_cselect_b32 s35, s7, s11
	s_cselect_b32 s34, s27, s10
	s_cselect_b32 s11, s25, s91
	s_cselect_b32 s10, s36, s37
	v_lshl_add_u64 v[154:155], s[8:9], 0, v[140:141]
	s_add_i32 m0, s43, 0xc000
	ds_read_b128 v[188:191], v159
	ds_read_b128 v[192:195], v159 offset:1024
	ds_read_b128 v[196:199], v159 offset:2048
	ds_read_b128 v[200:203], v159 offset:3072
	ds_read_b128 v[204:207], v159 offset:4096
	ds_read_b128 v[208:211], v159 offset:5120
	ds_read_b128 v[212:215], v159 offset:6144
	ds_read_b128 v[216:219], v159 offset:7168
	global_load_lds_dwordx4 v[154:155], off
	v_lshl_add_u64 v[154:155], s[8:9], 0, v[138:139]
	s_add_i32 m0, s43, 0xe000
	s_nop 0
	global_load_lds_dwordx4 v[154:155], off
	s_waitcnt vmcnt(8)
	s_waitcnt lgkmcnt(0)
	s_barrier
	s_setprio 1
	s_waitcnt lgkmcnt(0)
	v_mfma_f32_16x16x32_bf16 v[124:127], v[146:149], v[188:191], v[124:127]
	v_mfma_f32_16x16x32_bf16 v[120:123], v[164:167], v[188:191], v[120:123]
	v_mfma_f32_16x16x32_bf16 v[108:111], v[146:149], v[196:199], v[108:111]
	v_mfma_f32_16x16x32_bf16 v[104:107], v[164:167], v[196:199], v[104:107]
	v_mfma_f32_16x16x32_bf16 v[92:95], v[146:149], v[204:207], v[92:95]
	v_mfma_f32_16x16x32_bf16 v[88:91], v[164:167], v[204:207], v[88:91]
	v_mfma_f32_16x16x32_bf16 v[76:79], v[146:149], v[212:215], v[76:79]
	v_mfma_f32_16x16x32_bf16 v[72:75], v[164:167], v[212:215], v[72:75]
	v_mfma_f32_16x16x32_bf16 v[124:127], v[150:153], v[192:195], v[124:127]
	v_mfma_f32_16x16x32_bf16 v[120:123], v[168:171], v[192:195], v[120:123]
	v_mfma_f32_16x16x32_bf16 v[108:111], v[150:153], v[200:203], v[108:111]
	v_mfma_f32_16x16x32_bf16 v[104:107], v[168:171], v[200:203], v[104:107]
	v_mfma_f32_16x16x32_bf16 v[92:95], v[150:153], v[208:211], v[92:95]
	v_mfma_f32_16x16x32_bf16 v[88:91], v[168:171], v[208:211], v[88:91]
	v_mfma_f32_16x16x32_bf16 v[76:79], v[150:153], v[216:219], v[76:79]
	v_mfma_f32_16x16x32_bf16 v[72:75], v[168:171], v[216:219], v[72:75]
	s_setprio 0
	s_setprio 1
	v_mfma_f32_16x16x32_bf16 v[116:119], v[172:175], v[188:191], v[116:119]
	v_mfma_f32_16x16x32_bf16 v[112:115], v[180:183], v[188:191], v[112:115]
	v_mfma_f32_16x16x32_bf16 v[100:103], v[172:175], v[196:199], v[100:103]
	v_mfma_f32_16x16x32_bf16 v[96:99], v[180:183], v[196:199], v[96:99]
	v_mfma_f32_16x16x32_bf16 v[84:87], v[172:175], v[204:207], v[84:87]
	v_mfma_f32_16x16x32_bf16 v[80:83], v[180:183], v[204:207], v[80:83]
	v_mfma_f32_16x16x32_bf16 v[68:71], v[172:175], v[212:215], v[68:71]
	v_mfma_f32_16x16x32_bf16 v[64:67], v[180:183], v[212:215], v[64:67]
	v_mfma_f32_16x16x32_bf16 v[116:119], v[176:179], v[192:195], v[116:119]
	v_mfma_f32_16x16x32_bf16 v[112:115], v[184:187], v[192:195], v[112:115]
	v_mfma_f32_16x16x32_bf16 v[100:103], v[176:179], v[200:203], v[100:103]
	v_mfma_f32_16x16x32_bf16 v[96:99], v[184:187], v[200:203], v[96:99]
	v_mfma_f32_16x16x32_bf16 v[84:87], v[176:179], v[208:211], v[84:87]
	v_mfma_f32_16x16x32_bf16 v[80:83], v[184:187], v[208:211], v[80:83]
	v_mfma_f32_16x16x32_bf16 v[68:71], v[176:179], v[216:219], v[68:71]
	v_mfma_f32_16x16x32_bf16 v[64:67], v[184:187], v[216:219], v[64:67]
	s_setprio 0
	s_barrier
	s_add_i32 s38, s72, s42
	v_lshl_add_u64 v[154:155], s[10:11], 0, v[130:131]
	s_mov_b32 m0, s38
	ds_read_b128 v[188:191], v159 offset:16384
	ds_read_b128 v[192:195], v159 offset:17408
	ds_read_b128 v[196:199], v159 offset:18432
	ds_read_b128 v[200:203], v159 offset:19456
	ds_read_b128 v[204:207], v159 offset:20480
	ds_read_b128 v[208:211], v159 offset:21504
	ds_read_b128 v[212:215], v159 offset:22528
	ds_read_b128 v[216:219], v159 offset:23552
	global_load_lds_dwordx4 v[154:155], off
	s_add_i32 m0, s38, 0x2000
	s_add_u32 s94, s10, 0x100000
	v_lshl_add_u64 v[220:221], s[10:11], 0, v[134:135]
	s_addc_u32 s95, s11, 0
	s_add_i32 s38, s73, s42
	global_load_lds_dwordx4 v[220:221], off
	v_lshl_add_u64 v[222:223], s[94:95], 0, v[130:131]
	s_mov_b32 m0, s38
	v_lshl_add_u64 v[226:227], s[34:35], 0, v[132:133]
	global_load_lds_dwordx4 v[222:223], off
	v_lshl_add_u64 v[222:223], s[94:95], 0, v[134:135]
	s_add_i32 m0, s38, 0x2000
	s_nop 0
	global_load_lds_dwordx4 v[222:223], off
	v_lshl_add_u64 v[222:223], s[34:35], 0, v[128:129]
	s_mov_b32 m0, s43
	s_nop 0
	global_load_lds_dwordx4 v[222:223], off
	s_mov_b32 m0, s62
	s_nop 0
	global_load_lds_dwordx4 v[226:227], off
	s_waitcnt vmcnt(8)
	s_waitcnt lgkmcnt(0)
	s_barrier
; #define PG8_STAGE(bufoff, gbase, voff) do { _Pragma("unroll") for (int _i = 0; _i < 2; ++_i) \
;         __builtin_amdgcn_global_load_lds((const unsigned*)((const char*)(gbase) + (voff)[_i]), (LAS unsigned*)(lds + (bufoff) + ldsw + _i * 8192), 16, 0, 0); } while (0)
; #define PG8_LDA(dst, b, h) do { _Pragma("unroll") for (int m = 0; m < 4; ++m) _Pragma("unroll") for (int k = 0; k < 2; ++k) dst[m][k] = *(const LAS bf16x8*)(lds + PG8_SA(b, h) + aoff + m * 2048 + k * 1024); } while (0)
; #define PG8_LDB(dst, b, h) do { _Pragma("unroll") for (int n = 0; n < 2; ++n) _Pragma("unroll") for (int k = 0; k < 2; ++k) dst[n][k] = *(const LAS bf16x8*)(lds + PG8_SB(b, h) + boff + n * 2048 + k * 1024); } while (0)
; #define PG8_MMA(ai, bj, At, Bt) do { __builtin_amdgcn_s_setprio(1); _Pragma("unroll") for (int m = 0; m < 4; ++m) _Pragma("unroll") for (int n = 0; n < 2; ++n) _Pragma("unroll") for (int k = 0; k < 2; ++k) \
;         acc[ai][bj][m][n] = __builtin_amdgcn_mfma_f32_16x16x32_bf16(Bt[n][k], At[m][k], acc[ai][bj][m][n], 0, 0, 0); __builtin_amdgcn_s_setprio(0); } while (0)
; #define PG8_WAIT_V(n) asm volatile("s_waitcnt vmcnt(" #n ")" ::: "memory")
; #define PG8_WAIT_L(n) asm volatile("s_waitcnt lgkmcnt(" #n ")" ::: "memory")
; #define PG8_BAR __builtin_amdgcn_s_barrier()
; #define PG8_SCHED __builtin_amdgcn_sched_barrier(0)
; template <class Epi, class Sched>
; DI void gemm_phase(LAS unsigned char* lds, const Gemm g, const Sched& S, const Epi& E) {
;     ...
;       PG8_WAIT_V(8); PG8_WAIT_L(0); PG8_BAR; PG8_MMA(1, 0, At, B0); PG8_MMA(1, 1, At, B1); PG8_BAR; PG8_SCHED;
;       PG8_LDB(B0, 1, 0); PG8_LDB(B1, 1, 1); PG8_SCHED; PG8_LDA(At, 1, 0); PG8_STAGE(PG8_SA(0, 1), a2 + hstepA, voffA);
;       PG8_WAIT_V(8); PG8_WAIT_L(0); PG8_BAR; PG8_MMA(0, 0, At, B0); PG8_MMA(0, 1, At, B1); PG8_BAR; PG8_SCHED;
	s_setprio 1
	s_waitcnt lgkmcnt(0)
	v_mfma_f32_16x16x32_bf16 v[60:63], v[146:149], v[188:191], v[60:63]
	v_mfma_f32_16x16x32_bf16 v[56:59], v[164:167], v[188:191], v[56:59]
	v_mfma_f32_16x16x32_bf16 v[44:47], v[146:149], v[196:199], v[44:47]
	v_mfma_f32_16x16x32_bf16 v[40:43], v[164:167], v[196:199], v[40:43]
	v_mfma_f32_16x16x32_bf16 v[28:31], v[146:149], v[204:207], v[28:31]
	v_mfma_f32_16x16x32_bf16 v[24:27], v[164:167], v[204:207], v[24:27]
	v_mfma_f32_16x16x32_bf16 v[12:15], v[146:149], v[212:215], v[12:15]
	v_mfma_f32_16x16x32_bf16 v[8:11], v[164:167], v[212:215], v[8:11]
	v_mfma_f32_16x16x32_bf16 v[60:63], v[150:153], v[192:195], v[60:63]
	v_mfma_f32_16x16x32_bf16 v[56:59], v[168:171], v[192:195], v[56:59]
	v_mfma_f32_16x16x32_bf16 v[44:47], v[150:153], v[200:203], v[44:47]
	v_mfma_f32_16x16x32_bf16 v[40:43], v[168:171], v[200:203], v[40:43]
	v_mfma_f32_16x16x32_bf16 v[28:31], v[150:153], v[208:211], v[28:31]
	v_mfma_f32_16x16x32_bf16 v[24:27], v[168:171], v[208:211], v[24:27]
	v_mfma_f32_16x16x32_bf16 v[12:15], v[150:153], v[216:219], v[12:15]
	v_mfma_f32_16x16x32_bf16 v[8:11], v[168:171], v[216:219], v[8:11]
	s_setprio 0
	s_setprio 1
	v_mfma_f32_16x16x32_bf16 v[52:55], v[172:175], v[188:191], v[52:55]
	v_mfma_f32_16x16x32_bf16 v[48:51], v[180:183], v[188:191], v[48:51]
	v_mfma_f32_16x16x32_bf16 v[36:39], v[172:175], v[196:199], v[36:39]
	v_mfma_f32_16x16x32_bf16 v[32:35], v[180:183], v[196:199], v[32:35]
	v_mfma_f32_16x16x32_bf16 v[20:23], v[172:175], v[204:207], v[20:23]
	v_mfma_f32_16x16x32_bf16 v[16:19], v[180:183], v[204:207], v[16:19]
	v_mfma_f32_16x16x32_bf16 v[4:7], v[172:175], v[212:215], v[4:7]
	v_mfma_f32_16x16x32_bf16 v[0:3], v[180:183], v[212:215], v[0:3]
	v_mfma_f32_16x16x32_bf16 v[52:55], v[176:179], v[192:195], v[52:55]
	v_mfma_f32_16x16x32_bf16 v[48:51], v[184:187], v[192:195], v[48:51]
	v_mfma_f32_16x16x32_bf16 v[36:39], v[176:179], v[200:203], v[36:39]
	v_mfma_f32_16x16x32_bf16 v[32:35], v[184:187], v[200:203], v[32:35]
	v_mfma_f32_16x16x32_bf16 v[20:23], v[176:179], v[208:211], v[20:23]
	v_mfma_f32_16x16x32_bf16 v[16:19], v[184:187], v[208:211], v[16:19]
	v_mfma_f32_16x16x32_bf16 v[4:7], v[176:179], v[216:219], v[4:7]
	v_mfma_f32_16x16x32_bf16 v[0:3], v[184:187], v[216:219], v[0:3]
	s_setprio 0
	s_barrier
	s_add_i32 s38, 0, 0x18000
	v_add_u32_e32 v136, s38, v156
	s_add_i32 s39, 0, 0x1c000
	ds_read_b128 v[146:149], v136
	ds_read_b128 v[150:153], v136 offset:1024
	ds_read_b128 v[164:167], v136 offset:2048
	ds_read_b128 v[168:171], v136 offset:3072
	v_add_u32_e32 v136, s39, v156
	ds_read_b128 v[172:175], v136
	ds_read_b128 v[176:179], v136 offset:1024
	ds_read_b128 v[180:183], v136 offset:2048
	ds_read_b128 v[184:187], v136 offset:3072
	s_add_u32 s34, s34, 0x100000
	s_addc_u32 s35, s35, 0
	s_mov_b32 m0, s63
	v_lshl_add_u64 v[228:229], s[34:35], 0, v[128:129]
	ds_read_b128 v[188:191], v159 offset:32768
	ds_read_b128 v[192:195], v159 offset:33792
	ds_read_b128 v[196:199], v159 offset:34816
	ds_read_b128 v[200:203], v159 offset:35840
	ds_read_b128 v[204:207], v159 offset:36864
	ds_read_b128 v[208:211], v159 offset:37888
	ds_read_b128 v[212:215], v159 offset:38912
	ds_read_b128 v[216:219], v159 offset:39936
	global_load_lds_dwordx4 v[228:229], off
	v_lshl_add_u64 v[228:229], s[34:35], 0, v[132:133]
	s_mov_b32 m0, s64
	s_nop 0
	global_load_lds_dwordx4 v[228:229], off
	s_waitcnt vmcnt(8)
	s_waitcnt lgkmcnt(0)
	s_barrier
	s_setprio 1
	s_waitcnt lgkmcnt(0)
	v_mfma_f32_16x16x32_bf16 v[124:127], v[146:149], v[188:191], v[124:127]
	v_mfma_f32_16x16x32_bf16 v[120:123], v[164:167], v[188:191], v[120:123]
	v_mfma_f32_16x16x32_bf16 v[108:111], v[146:149], v[196:199], v[108:111]
	v_mfma_f32_16x16x32_bf16 v[104:107], v[164:167], v[196:199], v[104:107]
	v_mfma_f32_16x16x32_bf16 v[92:95], v[146:149], v[204:207], v[92:95]
	v_mfma_f32_16x16x32_bf16 v[88:91], v[164:167], v[204:207], v[88:91]
	v_mfma_f32_16x16x32_bf16 v[76:79], v[146:149], v[212:215], v[76:79]
	v_mfma_f32_16x16x32_bf16 v[72:75], v[164:167], v[212:215], v[72:75]
	v_mfma_f32_16x16x32_bf16 v[124:127], v[150:153], v[192:195], v[124:127]
	v_mfma_f32_16x16x32_bf16 v[120:123], v[168:171], v[192:195], v[120:123]
	v_mfma_f32_16x16x32_bf16 v[108:111], v[150:153], v[200:203], v[108:111]
	v_mfma_f32_16x16x32_bf16 v[104:107], v[168:171], v[200:203], v[104:107]
	v_mfma_f32_16x16x32_bf16 v[92:95], v[150:153], v[208:211], v[92:95]
	v_mfma_f32_16x16x32_bf16 v[88:91], v[168:171], v[208:211], v[88:91]
	v_mfma_f32_16x16x32_bf16 v[76:79], v[150:153], v[216:219], v[76:79]
	v_mfma_f32_16x16x32_bf16 v[72:75], v[168:171], v[216:219], v[72:75]
	s_setprio 0
	s_setprio 1
	v_mfma_f32_16x16x32_bf16 v[116:119], v[172:175], v[188:191], v[116:119]
	v_mfma_f32_16x16x32_bf16 v[112:115], v[180:183], v[188:191], v[112:115]
	v_mfma_f32_16x16x32_bf16 v[100:103], v[172:175], v[196:199], v[100:103]
	v_mfma_f32_16x16x32_bf16 v[96:99], v[180:183], v[196:199], v[96:99]
	v_mfma_f32_16x16x32_bf16 v[84:87], v[172:175], v[204:207], v[84:87]
	v_mfma_f32_16x16x32_bf16 v[80:83], v[180:183], v[204:207], v[80:83]
	v_mfma_f32_16x16x32_bf16 v[68:71], v[172:175], v[212:215], v[68:71]
	v_mfma_f32_16x16x32_bf16 v[64:67], v[180:183], v[212:215], v[64:67]
	v_mfma_f32_16x16x32_bf16 v[116:119], v[176:179], v[192:195], v[116:119]
	v_mfma_f32_16x16x32_bf16 v[112:115], v[184:187], v[192:195], v[112:115]
	v_mfma_f32_16x16x32_bf16 v[100:103], v[176:179], v[200:203], v[100:103]
	v_mfma_f32_16x16x32_bf16 v[96:99], v[184:187], v[200:203], v[96:99]
	v_mfma_f32_16x16x32_bf16 v[84:87], v[176:179], v[208:211], v[84:87]
	v_mfma_f32_16x16x32_bf16 v[80:83], v[184:187], v[208:211], v[80:83]
	v_mfma_f32_16x16x32_bf16 v[68:71], v[176:179], v[216:219], v[68:71]
	v_mfma_f32_16x16x32_bf16 v[64:67], v[184:187], v[216:219], v[64:67]
	s_setprio 0
	s_barrier
; #define PG8_STAGE(bufoff, gbase, voff) do { _Pragma("unroll") for (int _i = 0; _i < 2; ++_i) \
;         __builtin_amdgcn_global_load_lds((const unsigned*)((const char*)(gbase) + (voff)[_i]), (LAS unsigned*)(lds + (bufoff) + ldsw + _i * 8192), 16, 0, 0); } while (0)
; #define PG8_LDA(dst, b, h) do { _Pragma("unroll") for (int m = 0; m < 4; ++m) _Pragma("unroll") for (int k = 0; k < 2; ++k) dst[m][k] = *(const LAS bf16x8*)(lds + PG8_SA(b, h) + aoff + m * 2048 + k * 1024); } while (0)
; #define PG8_MMA(ai, bj, At, Bt) do { __builtin_amdgcn_s_setprio(1); _Pragma("unroll") for (int m = 0; m < 4; ++m) _Pragma("unroll") for (int n = 0; n < 2; ++n) _Pragma("unroll") for (int k = 0; k < 2; ++k) \
;         acc[ai][bj][m][n] = __builtin_amdgcn_mfma_f32_16x16x32_bf16(Bt[n][k], At[m][k], acc[ai][bj][m][n], 0, 0, 0); __builtin_amdgcn_s_setprio(0); } while (0)
; #define PG8_WAIT_V(n) asm volatile("s_waitcnt vmcnt(" #n ")" ::: "memory")
; #define PG8_WAIT_L(n) asm volatile("s_waitcnt lgkmcnt(" #n ")" ::: "memory")
; #define PG8_BAR __builtin_amdgcn_s_barrier()
; #define PG8_SCHED __builtin_amdgcn_sched_barrier(0)
; template <class Epi, class Sched>
; DI void gemm_phase(LAS unsigned char* lds, const Gemm g, const Sched& S, const Epi& E) {
;     ...
;     for (int t = 0; t < nt; t += 2) {
;       const bool last = (t == nt - 2);
;       const char* a1 = cA + (size_t)(t + 1) * kstep;
;       const char* a2 = last ? nA : cA + (size_t)(t + 2) * kstep; const char* b2 = last ? nB : cB + (size_t)(t + 2) * kstep;
;     ...
;       PG8_LDA(At, 1, 1); PG8_STAGE(PG8_SB(1, 0), b3, voffB); PG8_STAGE(PG8_SB(1, 1), b3 + hstepB, voffB); PG8_STAGE(PG8_SA(1, 0), a3, voffA);
;       PG8_WAIT_V(8); PG8_WAIT_L(0); PG8_BAR; PG8_MMA(1, 0, At, B0); PG8_MMA(1, 1, At, B1); PG8_BAR; PG8_SCHED;
;     }
	s_add_i32 s34, s38, s42
	v_lshl_add_u64 v[154:155], v[154:155], 0, s[18:19]
	s_mov_b32 m0, s34
	ds_read_b128 v[188:191], v159 offset:49152
	ds_read_b128 v[192:195], v159 offset:50176
	ds_read_b128 v[196:199], v159 offset:51200
	ds_read_b128 v[200:203], v159 offset:52224
	ds_read_b128 v[204:207], v159 offset:53248
	ds_read_b128 v[208:211], v159 offset:54272
	ds_read_b128 v[212:215], v159 offset:55296
	ds_read_b128 v[216:219], v159 offset:56320
	global_load_lds_dwordx4 v[154:155], off
	s_add_i32 m0, s34, 0x2000
	s_add_u32 s10, s10, 0x100080
	v_lshl_add_u64 v[154:155], v[220:221], 0, s[18:19]
	s_addc_u32 s11, s11, 0
	s_add_i32 s34, s39, s42
	global_load_lds_dwordx4 v[154:155], off
	v_lshl_add_u64 v[154:155], s[10:11], 0, v[130:131]
	s_mov_b32 m0, s34
	s_nop 0
	global_load_lds_dwordx4 v[154:155], off
	v_lshl_add_u64 v[154:155], s[10:11], 0, v[134:135]
	s_add_i32 m0, s34, 0x2000
	s_nop 0
	global_load_lds_dwordx4 v[154:155], off
	v_lshl_add_u64 v[154:155], v[222:223], 0, s[18:19]
	s_mov_b32 m0, s68
	s_nop 0
	global_load_lds_dwordx4 v[154:155], off
	v_lshl_add_u64 v[154:155], v[226:227], 0, s[18:19]
	s_mov_b32 m0, s69
	s_nop 0
	global_load_lds_dwordx4 v[154:155], off
	s_waitcnt vmcnt(8)
	s_waitcnt lgkmcnt(0)
	s_barrier
	s_setprio 1
	s_waitcnt lgkmcnt(0)
	v_mfma_f32_16x16x32_bf16 v[60:63], v[146:149], v[188:191], v[60:63]
	v_mfma_f32_16x16x32_bf16 v[56:59], v[164:167], v[188:191], v[56:59]
	v_mfma_f32_16x16x32_bf16 v[44:47], v[146:149], v[196:199], v[44:47]
	v_mfma_f32_16x16x32_bf16 v[40:43], v[164:167], v[196:199], v[40:43]
	v_mfma_f32_16x16x32_bf16 v[28:31], v[146:149], v[204:207], v[28:31]
	v_mfma_f32_16x16x32_bf16 v[24:27], v[164:167], v[204:207], v[24:27]
	v_mfma_f32_16x16x32_bf16 v[12:15], v[146:149], v[212:215], v[12:15]
	v_mfma_f32_16x16x32_bf16 v[8:11], v[164:167], v[212:215], v[8:11]
	v_mfma_f32_16x16x32_bf16 v[60:63], v[150:153], v[192:195], v[60:63]
	v_mfma_f32_16x16x32_bf16 v[56:59], v[168:171], v[192:195], v[56:59]
	v_mfma_f32_16x16x32_bf16 v[44:47], v[150:153], v[200:203], v[44:47]
	v_mfma_f32_16x16x32_bf16 v[40:43], v[168:171], v[200:203], v[40:43]
	v_mfma_f32_16x16x32_bf16 v[28:31], v[150:153], v[208:211], v[28:31]
	v_mfma_f32_16x16x32_bf16 v[24:27], v[168:171], v[208:211], v[24:27]
	v_mfma_f32_16x16x32_bf16 v[12:15], v[150:153], v[216:219], v[12:15]
	v_mfma_f32_16x16x32_bf16 v[8:11], v[168:171], v[216:219], v[8:11]
	s_setprio 0
	s_setprio 1
	v_mfma_f32_16x16x32_bf16 v[52:55], v[172:175], v[188:191], v[52:55]
	v_mfma_f32_16x16x32_bf16 v[48:51], v[180:183], v[188:191], v[48:51]
	v_mfma_f32_16x16x32_bf16 v[36:39], v[172:175], v[196:199], v[36:39]
	v_mfma_f32_16x16x32_bf16 v[32:35], v[180:183], v[196:199], v[32:35]
	v_mfma_f32_16x16x32_bf16 v[20:23], v[172:175], v[204:207], v[20:23]
	v_mfma_f32_16x16x32_bf16 v[16:19], v[180:183], v[204:207], v[16:19]
	v_mfma_f32_16x16x32_bf16 v[4:7], v[172:175], v[212:215], v[4:7]
	v_mfma_f32_16x16x32_bf16 v[0:3], v[180:183], v[212:215], v[0:3]
	v_mfma_f32_16x16x32_bf16 v[52:55], v[176:179], v[192:195], v[52:55]
	v_mfma_f32_16x16x32_bf16 v[48:51], v[184:187], v[192:195], v[48:51]
	v_mfma_f32_16x16x32_bf16 v[36:39], v[176:179], v[200:203], v[36:39]
	v_mfma_f32_16x16x32_bf16 v[32:35], v[184:187], v[200:203], v[32:35]
	v_mfma_f32_16x16x32_bf16 v[20:23], v[176:179], v[208:211], v[20:23]
	v_mfma_f32_16x16x32_bf16 v[16:19], v[184:187], v[208:211], v[16:19]
	v_mfma_f32_16x16x32_bf16 v[4:7], v[176:179], v[216:219], v[4:7]
	v_mfma_f32_16x16x32_bf16 v[0:3], v[184:187], v[216:219], v[0:3]
	s_setprio 0
	s_add_i32 s92, s92, 2
	s_add_u32 s37, s37, 0x100
	s_addc_u32 s91, s91, 0
	s_add_u32 s8, s8, 0x100
	s_addc_u32 s9, s9, 0
	s_cmp_gt_u32 s92, 61
	s_barrier
	s_cbranch_scc0 .LBB0_1856
	s_and_b64 vcc, exec, s[20:21]
	s_cbranch_vccz .LBB0_1859
	s_barrier

; #define PG8_STAGE(bufoff, gbase, voff) do { _Pragma("unroll") for (int _i = 0; _i < 2; ++_i) \
;         __builtin_amdgcn_global_load_lds((const unsigned*)((const char*)(gbase) + (voff)[_i]), (LAS unsigned*)(lds + (bufoff) + ldsw + _i * 8192), 16, 0, 0); } while (0)
; #define PG8_LDA(dst, b, h) do { _Pragma("unroll") for (int m = 0; m < 4; ++m) _Pragma("unroll") for (int k = 0; k < 2; ++k) dst[m][k] = *(const LAS bf16x8*)(lds + PG8_SA(b, h) + aoff + m * 2048 + k * 1024); } while (0)
; #define PG8_LDB(dst, b, h) do { _Pragma("unroll") for (int n = 0; n < 2; ++n) _Pragma("unroll") for (int k = 0; k < 2; ++k) dst[n][k] = *(const LAS bf16x8*)(lds + PG8_SB(b, h) + boff + n * 2048 + k * 1024); } while (0)
; #define PG8_MMA(ai, bj, At, Bt) do { __builtin_amdgcn_s_setprio(1); _Pragma("unroll") for (int m = 0; m < 4; ++m) _Pragma("unroll") for (int n = 0; n < 2; ++n) _Pragma("unroll") for (int k = 0; k < 2; ++k) \
;         acc[ai][bj][m][n] = __builtin_amdgcn_mfma_f32_16x16x32_bf16(Bt[n][k], At[m][k], acc[ai][bj][m][n], 0, 0, 0); __builtin_amdgcn_s_setprio(0); } while (0)
; #define PG8_WAIT_V(n) asm volatile("s_waitcnt vmcnt(" #n ")" ::: "memory")
; #define PG8_WAIT_L(n) asm volatile("s_waitcnt lgkmcnt(" #n ")" ::: "memory")
; #define PG8_BAR __builtin_amdgcn_s_barrier()
; #define PG8_SCHED __builtin_amdgcn_sched_barrier(0)
; template <class Epi, class Sched>
; DI void gemm_phase(LAS unsigned char* lds, const Gemm g, const Sched& S, const Epi& E) {
;     ...
;     for (int t = 0; t < nt; t += 2) {
;       const bool last = (t == nt - 2);
;       const char* a1 = cA + (size_t)(t + 1) * kstep;
;       const char* a2 = last ? nA : cA + (size_t)(t + 2) * kstep; const char* b2 = last ? nB : cB + (size_t)(t + 2) * kstep;
;       const char* a3 = a2 + kstep; const char* b3 = b2 + kstep;
;       PG8_LDB(B0, 0, 0); PG8_LDB(B1, 0, 1); PG8_SCHED; PG8_LDA(At, 0, 0); PG8_STAGE(PG8_SA(1, 1), a1 + hstepA, voffA);
;       PG8_WAIT_V(8); PG8_WAIT_L(0); PG8_BAR; PG8_MMA(0, 0, At, B0); PG8_MMA(0, 1, At, B1); PG8_BAR; PG8_SCHED;
;       PG8_LDA(At, 0, 1); PG8_STAGE(PG8_SB(0, 0), b2, voffB); PG8_STAGE(PG8_SB(0, 1), b2 + hstepB, voffB); PG8_STAGE(PG8_SA(0, 0), a2, voffA);
;       PG8_WAIT_V(8); PG8_WAIT_L(0); PG8_BAR; PG8_MMA(1, 0, At, B0); PG8_MMA(1, 1, At, B1); PG8_BAR; PG8_SCHED;
.LBB0_2157:
	s_waitcnt lgkmcnt(0)
	ds_read_b128 v[128:131], v199
	ds_read_b128 v[132:135], v199 offset:1024
	ds_read_b128 v[136:139], v199 offset:2048
	ds_read_b128 v[140:143], v199 offset:3072
	ds_read_b128 v[162:165], v200
	ds_read_b128 v[166:169], v200 offset:1024
	ds_read_b128 v[170:173], v200 offset:2048
	ds_read_b128 v[174:177], v200 offset:3072
	s_add_u32 s0, s62, 0xfffc0080
	s_addc_u32 s1, s63, -1
	s_cmp_eq_u32 s69, 12
	s_cselect_b32 s67, s7, s1
	s_cselect_b32 s66, s16, s0
	s_cselect_b32 s65, s17, s68
	s_cselect_b32 s64, s31, s35
	v_lshl_add_u64 v[216:217], s[62:63], 0, v[156:157]
	s_add_i32 m0, s61, 0xc000
	ds_read_b128 v[178:181], v201
	ds_read_b128 v[182:185], v201 offset:1024
	ds_read_b128 v[186:189], v201 offset:2048
	ds_read_b128 v[190:193], v201 offset:3072
	ds_read_b128 v[194:197], v201 offset:4096
	ds_read_b128 v[204:207], v201 offset:5120
	ds_read_b128 v[208:211], v201 offset:6144
	ds_read_b128 v[212:215], v201 offset:7168
	global_load_lds_dwordx4 v[216:217], off
	v_lshl_add_u64 v[216:217], s[62:63], 0, v[154:155]
	s_add_i32 m0, s61, 0xe000
	s_nop 0
	global_load_lds_dwordx4 v[216:217], off
	s_waitcnt vmcnt(8)
	s_waitcnt lgkmcnt(0)
	s_barrier
	s_setprio 1
	s_waitcnt lgkmcnt(0)
	v_mfma_f32_16x16x32_bf16 v[124:127], v[128:131], v[178:181], v[124:127]
	v_mfma_f32_16x16x32_bf16 v[120:123], v[136:139], v[178:181], v[120:123]
	v_mfma_f32_16x16x32_bf16 v[108:111], v[128:131], v[186:189], v[108:111]
	v_mfma_f32_16x16x32_bf16 v[104:107], v[136:139], v[186:189], v[104:107]
	v_mfma_f32_16x16x32_bf16 v[92:95], v[128:131], v[194:197], v[92:95]
	v_mfma_f32_16x16x32_bf16 v[88:91], v[136:139], v[194:197], v[88:91]
	v_mfma_f32_16x16x32_bf16 v[76:79], v[128:131], v[208:211], v[76:79]
	v_mfma_f32_16x16x32_bf16 v[72:75], v[136:139], v[208:211], v[72:75]
	v_mfma_f32_16x16x32_bf16 v[124:127], v[132:135], v[182:185], v[124:127]
	v_mfma_f32_16x16x32_bf16 v[120:123], v[140:143], v[182:185], v[120:123]
	v_mfma_f32_16x16x32_bf16 v[108:111], v[132:135], v[190:193], v[108:111]
	v_mfma_f32_16x16x32_bf16 v[104:107], v[140:143], v[190:193], v[104:107]
	v_mfma_f32_16x16x32_bf16 v[92:95], v[132:135], v[204:207], v[92:95]
	v_mfma_f32_16x16x32_bf16 v[88:91], v[140:143], v[204:207], v[88:91]
	v_mfma_f32_16x16x32_bf16 v[76:79], v[132:135], v[212:215], v[76:79]
	v_mfma_f32_16x16x32_bf16 v[72:75], v[140:143], v[212:215], v[72:75]
	s_setprio 0
	s_setprio 1
	v_mfma_f32_16x16x32_bf16 v[116:119], v[162:165], v[178:181], v[116:119]
	v_mfma_f32_16x16x32_bf16 v[112:115], v[170:173], v[178:181], v[112:115]
	v_mfma_f32_16x16x32_bf16 v[100:103], v[162:165], v[186:189], v[100:103]
	v_mfma_f32_16x16x32_bf16 v[96:99], v[170:173], v[186:189], v[96:99]
	v_mfma_f32_16x16x32_bf16 v[84:87], v[162:165], v[194:197], v[84:87]
	v_mfma_f32_16x16x32_bf16 v[80:83], v[170:173], v[194:197], v[80:83]
	v_mfma_f32_16x16x32_bf16 v[68:71], v[162:165], v[208:211], v[68:71]
	v_mfma_f32_16x16x32_bf16 v[64:67], v[170:173], v[208:211], v[64:67]
	v_mfma_f32_16x16x32_bf16 v[116:119], v[166:169], v[182:185], v[116:119]
	v_mfma_f32_16x16x32_bf16 v[112:115], v[174:177], v[182:185], v[112:115]
	v_mfma_f32_16x16x32_bf16 v[100:103], v[166:169], v[190:193], v[100:103]
	v_mfma_f32_16x16x32_bf16 v[96:99], v[174:177], v[190:193], v[96:99]
	v_mfma_f32_16x16x32_bf16 v[84:87], v[166:169], v[204:207], v[84:87]
	v_mfma_f32_16x16x32_bf16 v[80:83], v[174:177], v[204:207], v[80:83]
	v_mfma_f32_16x16x32_bf16 v[68:71], v[166:169], v[212:215], v[68:71]
	v_mfma_f32_16x16x32_bf16 v[64:67], v[174:177], v[212:215], v[64:67]
	s_setprio 0
	s_barrier
	s_add_i32 s0, s96, s83
	v_lshl_add_u64 v[216:217], s[64:65], 0, v[146:147]
	s_mov_b32 m0, s0
	ds_read_b128 v[178:181], v201 offset:16384
	ds_read_b128 v[182:185], v201 offset:17408
	ds_read_b128 v[186:189], v201 offset:18432
	ds_read_b128 v[190:193], v201 offset:19456
	ds_read_b128 v[194:197], v201 offset:20480
	ds_read_b128 v[204:207], v201 offset:21504
	ds_read_b128 v[208:211], v201 offset:22528
	ds_read_b128 v[212:215], v201 offset:23552
	global_load_lds_dwordx4 v[216:217], off
	s_add_i32 m0, s0, 0x2000
	s_add_u32 s38, s64, 0x40000
	v_lshl_add_u64 v[218:219], s[64:65], 0, v[150:151]
	s_addc_u32 s39, s65, 0
	s_add_i32 s0, s97, s83
	global_load_lds_dwordx4 v[218:219], off
	v_lshl_add_u64 v[220:221], s[38:39], 0, v[146:147]
	s_mov_b32 m0, s0
	v_lshl_add_u64 v[222:223], s[66:67], 0, v[148:149]
	global_load_lds_dwordx4 v[220:221], off
	v_lshl_add_u64 v[220:221], s[38:39], 0, v[150:151]
	s_add_i32 m0, s0, 0x2000
	s_nop 0
	global_load_lds_dwordx4 v[220:221], off
	v_lshl_add_u64 v[220:221], s[66:67], 0, v[144:145]
	s_mov_b32 m0, s61
	s_nop 0
	global_load_lds_dwordx4 v[220:221], off
	s_mov_b32 m0, s86
	s_nop 0
	global_load_lds_dwordx4 v[222:223], off
	s_waitcnt vmcnt(8)
	s_waitcnt lgkmcnt(0)
	s_barrier
; #define PG8_STAGE(bufoff, gbase, voff) do { _Pragma("unroll") for (int _i = 0; _i < 2; ++_i) \
;         __builtin_amdgcn_global_load_lds((const unsigned*)((const char*)(gbase) + (voff)[_i]), (LAS unsigned*)(lds + (bufoff) + ldsw + _i * 8192), 16, 0, 0); } while (0)
; #define PG8_LDA(dst, b, h) do { _Pragma("unroll") for (int m = 0; m < 4; ++m) _Pragma("unroll") for (int k = 0; k < 2; ++k) dst[m][k] = *(const LAS bf16x8*)(lds + PG8_SA(b, h) + aoff + m * 2048 + k * 1024); } while (0)
; #define PG8_LDB(dst, b, h) do { _Pragma("unroll") for (int n = 0; n < 2; ++n) _Pragma("unroll") for (int k = 0; k < 2; ++k) dst[n][k] = *(const LAS bf16x8*)(lds + PG8_SB(b, h) + boff + n * 2048 + k * 1024); } while (0)
; #define PG8_MMA(ai, bj, At, Bt) do { __builtin_amdgcn_s_setprio(1); _Pragma("unroll") for (int m = 0; m < 4; ++m) _Pragma("unroll") for (int n = 0; n < 2; ++n) _Pragma("unroll") for (int k = 0; k < 2; ++k) \
;         acc[ai][bj][m][n] = __builtin_amdgcn_mfma_f32_16x16x32_bf16(Bt[n][k], At[m][k], acc[ai][bj][m][n], 0, 0, 0); __builtin_amdgcn_s_setprio(0); } while (0)
; #define PG8_WAIT_V(n) asm volatile("s_waitcnt vmcnt(" #n ")" ::: "memory")
; #define PG8_WAIT_L(n) asm volatile("s_waitcnt lgkmcnt(" #n ")" ::: "memory")
; #define PG8_BAR __builtin_amdgcn_s_barrier()
; #define PG8_SCHED __builtin_amdgcn_sched_barrier(0)
; template <class Epi, class Sched>
; DI void gemm_phase(LAS unsigned char* lds, const Gemm g, const Sched& S, const Epi& E) {
;     ...
;       PG8_WAIT_V(8); PG8_WAIT_L(0); PG8_BAR; PG8_MMA(1, 0, At, B0); PG8_MMA(1, 1, At, B1); PG8_BAR; PG8_SCHED;
;       PG8_LDB(B0, 1, 0); PG8_LDB(B1, 1, 1); PG8_SCHED; PG8_LDA(At, 1, 0); PG8_STAGE(PG8_SA(0, 1), a2 + hstepA, voffA);
;       PG8_WAIT_V(8); PG8_WAIT_L(0); PG8_BAR; PG8_MMA(0, 0, At, B0); PG8_MMA(0, 1, At, B1); PG8_BAR; PG8_SCHED;
	s_setprio 1
	s_waitcnt lgkmcnt(0)
	v_mfma_f32_16x16x32_bf16 v[60:63], v[128:131], v[178:181], v[60:63]
	v_mfma_f32_16x16x32_bf16 v[56:59], v[136:139], v[178:181], v[56:59]
	v_mfma_f32_16x16x32_bf16 v[44:47], v[128:131], v[186:189], v[44:47]
	v_mfma_f32_16x16x32_bf16 v[40:43], v[136:139], v[186:189], v[40:43]
	v_mfma_f32_16x16x32_bf16 v[28:31], v[128:131], v[194:197], v[28:31]
	v_mfma_f32_16x16x32_bf16 v[24:27], v[136:139], v[194:197], v[24:27]
	v_mfma_f32_16x16x32_bf16 v[12:15], v[128:131], v[208:211], v[12:15]
	v_mfma_f32_16x16x32_bf16 v[8:11], v[136:139], v[208:211], v[8:11]
	v_mfma_f32_16x16x32_bf16 v[60:63], v[132:135], v[182:185], v[60:63]
	v_mfma_f32_16x16x32_bf16 v[56:59], v[140:143], v[182:185], v[56:59]
	v_mfma_f32_16x16x32_bf16 v[44:47], v[132:135], v[190:193], v[44:47]
	v_mfma_f32_16x16x32_bf16 v[40:43], v[140:143], v[190:193], v[40:43]
	v_mfma_f32_16x16x32_bf16 v[28:31], v[132:135], v[204:207], v[28:31]
	v_mfma_f32_16x16x32_bf16 v[24:27], v[140:143], v[204:207], v[24:27]
	v_mfma_f32_16x16x32_bf16 v[12:15], v[132:135], v[212:215], v[12:15]
	v_mfma_f32_16x16x32_bf16 v[8:11], v[140:143], v[212:215], v[8:11]
	s_setprio 0
	s_setprio 1
	v_mfma_f32_16x16x32_bf16 v[52:55], v[162:165], v[178:181], v[52:55]
	v_mfma_f32_16x16x32_bf16 v[48:51], v[170:173], v[178:181], v[48:51]
	v_mfma_f32_16x16x32_bf16 v[36:39], v[162:165], v[186:189], v[36:39]
	v_mfma_f32_16x16x32_bf16 v[32:35], v[170:173], v[186:189], v[32:35]
	v_mfma_f32_16x16x32_bf16 v[20:23], v[162:165], v[194:197], v[20:23]
	v_mfma_f32_16x16x32_bf16 v[16:19], v[170:173], v[194:197], v[16:19]
	v_mfma_f32_16x16x32_bf16 v[4:7], v[162:165], v[208:211], v[4:7]
	v_mfma_f32_16x16x32_bf16 v[0:3], v[170:173], v[208:211], v[0:3]
	v_mfma_f32_16x16x32_bf16 v[52:55], v[166:169], v[182:185], v[52:55]
	v_mfma_f32_16x16x32_bf16 v[48:51], v[174:177], v[182:185], v[48:51]
	v_mfma_f32_16x16x32_bf16 v[36:39], v[166:169], v[190:193], v[36:39]
	v_mfma_f32_16x16x32_bf16 v[32:35], v[174:177], v[190:193], v[32:35]
	v_mfma_f32_16x16x32_bf16 v[20:23], v[166:169], v[204:207], v[20:23]
	v_mfma_f32_16x16x32_bf16 v[16:19], v[174:177], v[204:207], v[16:19]
	v_mfma_f32_16x16x32_bf16 v[4:7], v[166:169], v[212:215], v[4:7]
	v_mfma_f32_16x16x32_bf16 v[0:3], v[174:177], v[212:215], v[0:3]
	s_setprio 0
	s_barrier
	s_add_i32 s0, 0, 0x18000
	s_add_i32 s1, 0, 0x1c000
	v_add_u32_e32 v140, s0, v198
	v_add_u32_e32 v152, s1, v198
	ds_read_b128 v[128:131], v140
	ds_read_b128 v[132:135], v140 offset:1024
	ds_read_b128 v[136:139], v140 offset:2048
	ds_read_b128 v[140:143], v140 offset:3072
	ds_read_b128 v[162:165], v152
	ds_read_b128 v[166:169], v152 offset:1024
	ds_read_b128 v[170:173], v152 offset:2048
	ds_read_b128 v[174:177], v152 offset:3072
	s_add_u32 s38, s66, 0x40000
	s_addc_u32 s39, s67, 0
	s_mov_b32 m0, s87
	v_lshl_add_u64 v[226:227], s[38:39], 0, v[144:145]
	ds_read_b128 v[178:181], v201 offset:32768
	ds_read_b128 v[182:185], v201 offset:33792
	ds_read_b128 v[186:189], v201 offset:34816
	ds_read_b128 v[190:193], v201 offset:35840
	ds_read_b128 v[194:197], v201 offset:36864
	ds_read_b128 v[204:207], v201 offset:37888
	ds_read_b128 v[208:211], v201 offset:38912
	ds_read_b128 v[212:215], v201 offset:39936
	global_load_lds_dwordx4 v[226:227], off
	v_lshl_add_u64 v[226:227], s[38:39], 0, v[148:149]
	s_mov_b32 m0, s88
	s_nop 0
	global_load_lds_dwordx4 v[226:227], off
	s_waitcnt vmcnt(8)
	s_waitcnt lgkmcnt(0)
	s_barrier
	s_setprio 1
	s_waitcnt lgkmcnt(0)
	v_mfma_f32_16x16x32_bf16 v[124:127], v[128:131], v[178:181], v[124:127]
	v_mfma_f32_16x16x32_bf16 v[120:123], v[136:139], v[178:181], v[120:123]
	v_mfma_f32_16x16x32_bf16 v[108:111], v[128:131], v[186:189], v[108:111]
	v_mfma_f32_16x16x32_bf16 v[104:107], v[136:139], v[186:189], v[104:107]
	v_mfma_f32_16x16x32_bf16 v[92:95], v[128:131], v[194:197], v[92:95]
	v_mfma_f32_16x16x32_bf16 v[88:91], v[136:139], v[194:197], v[88:91]
	v_mfma_f32_16x16x32_bf16 v[76:79], v[128:131], v[208:211], v[76:79]
	v_mfma_f32_16x16x32_bf16 v[72:75], v[136:139], v[208:211], v[72:75]
	v_mfma_f32_16x16x32_bf16 v[124:127], v[132:135], v[182:185], v[124:127]
	v_mfma_f32_16x16x32_bf16 v[120:123], v[140:143], v[182:185], v[120:123]
	v_mfma_f32_16x16x32_bf16 v[108:111], v[132:135], v[190:193], v[108:111]
	v_mfma_f32_16x16x32_bf16 v[104:107], v[140:143], v[190:193], v[104:107]
	v_mfma_f32_16x16x32_bf16 v[92:95], v[132:135], v[204:207], v[92:95]
	v_mfma_f32_16x16x32_bf16 v[88:91], v[140:143], v[204:207], v[88:91]
	v_mfma_f32_16x16x32_bf16 v[76:79], v[132:135], v[212:215], v[76:79]
	v_mfma_f32_16x16x32_bf16 v[72:75], v[140:143], v[212:215], v[72:75]
	s_setprio 0
	s_setprio 1
	v_mfma_f32_16x16x32_bf16 v[116:119], v[162:165], v[178:181], v[116:119]
	v_mfma_f32_16x16x32_bf16 v[112:115], v[170:173], v[178:181], v[112:115]
	v_mfma_f32_16x16x32_bf16 v[100:103], v[162:165], v[186:189], v[100:103]
	v_mfma_f32_16x16x32_bf16 v[96:99], v[170:173], v[186:189], v[96:99]
	v_mfma_f32_16x16x32_bf16 v[84:87], v[162:165], v[194:197], v[84:87]
	v_mfma_f32_16x16x32_bf16 v[80:83], v[170:173], v[194:197], v[80:83]
	v_mfma_f32_16x16x32_bf16 v[68:71], v[162:165], v[208:211], v[68:71]
	v_mfma_f32_16x16x32_bf16 v[64:67], v[170:173], v[208:211], v[64:67]
	v_mfma_f32_16x16x32_bf16 v[116:119], v[166:169], v[182:185], v[116:119]
	v_mfma_f32_16x16x32_bf16 v[112:115], v[174:177], v[182:185], v[112:115]
	v_mfma_f32_16x16x32_bf16 v[100:103], v[166:169], v[190:193], v[100:103]
	v_mfma_f32_16x16x32_bf16 v[96:99], v[174:177], v[190:193], v[96:99]
	v_mfma_f32_16x16x32_bf16 v[84:87], v[166:169], v[204:207], v[84:87]
	v_mfma_f32_16x16x32_bf16 v[80:83], v[174:177], v[204:207], v[80:83]
	v_mfma_f32_16x16x32_bf16 v[68:71], v[166:169], v[212:215], v[68:71]
	v_mfma_f32_16x16x32_bf16 v[64:67], v[174:177], v[212:215], v[64:67]
	s_setprio 0
	s_barrier
; #define PG8_STAGE(bufoff, gbase, voff) do { _Pragma("unroll") for (int _i = 0; _i < 2; ++_i) \
;         __builtin_amdgcn_global_load_lds((const unsigned*)((const char*)(gbase) + (voff)[_i]), (LAS unsigned*)(lds + (bufoff) + ldsw + _i * 8192), 16, 0, 0); } while (0)
; #define PG8_LDA(dst, b, h) do { _Pragma("unroll") for (int m = 0; m < 4; ++m) _Pragma("unroll") for (int k = 0; k < 2; ++k) dst[m][k] = *(const LAS bf16x8*)(lds + PG8_SA(b, h) + aoff + m * 2048 + k * 1024); } while (0)
; #define PG8_MMA(ai, bj, At, Bt) do { __builtin_amdgcn_s_setprio(1); _Pragma("unroll") for (int m = 0; m < 4; ++m) _Pragma("unroll") for (int n = 0; n < 2; ++n) _Pragma("unroll") for (int k = 0; k < 2; ++k) \
;         acc[ai][bj][m][n] = __builtin_amdgcn_mfma_f32_16x16x32_bf16(Bt[n][k], At[m][k], acc[ai][bj][m][n], 0, 0, 0); __builtin_amdgcn_s_setprio(0); } while (0)
; #define PG8_WAIT_V(n) asm volatile("s_waitcnt vmcnt(" #n ")" ::: "memory")
; #define PG8_WAIT_L(n) asm volatile("s_waitcnt lgkmcnt(" #n ")" ::: "memory")
; #define PG8_BAR __builtin_amdgcn_s_barrier()
; #define PG8_SCHED __builtin_amdgcn_sched_barrier(0)
; template <class Epi, class Sched>
; DI void gemm_phase(LAS unsigned char* lds, const Gemm g, const Sched& S, const Epi& E) {
;     ...
;     for (int t = 0; t < nt; t += 2) {
;       const bool last = (t == nt - 2);
;       const char* a1 = cA + (size_t)(t + 1) * kstep;
;       const char* a2 = last ? nA : cA + (size_t)(t + 2) * kstep; const char* b2 = last ? nB : cB + (size_t)(t + 2) * kstep;
;     ...
;       PG8_LDA(At, 1, 1); PG8_STAGE(PG8_SB(1, 0), b3, voffB); PG8_STAGE(PG8_SB(1, 1), b3 + hstepB, voffB); PG8_STAGE(PG8_SA(1, 0), a3, voffA);
;       PG8_WAIT_V(8); PG8_WAIT_L(0); PG8_BAR; PG8_MMA(1, 0, At, B0); PG8_MMA(1, 1, At, B1); PG8_BAR; PG8_SCHED;
;     }
	s_add_i32 s0, s0, s83
	v_lshl_add_u64 v[216:217], v[216:217], 0, s[10:11]
	s_mov_b32 m0, s0
	ds_read_b128 v[178:181], v201 offset:49152
	ds_read_b128 v[182:185], v201 offset:50176
	ds_read_b128 v[186:189], v201 offset:51200
	ds_read_b128 v[190:193], v201 offset:52224
	ds_read_b128 v[194:197], v201 offset:53248
	ds_read_b128 v[204:207], v201 offset:54272
	ds_read_b128 v[208:211], v201 offset:55296
	ds_read_b128 v[212:215], v201 offset:56320
	global_load_lds_dwordx4 v[216:217], off
	s_add_i32 m0, s0, 0x2000
	s_add_u32 s38, s64, 0x40080
	v_lshl_add_u64 v[216:217], v[218:219], 0, s[10:11]
	s_addc_u32 s39, s65, 0
	s_add_i32 s0, s1, s83
	global_load_lds_dwordx4 v[216:217], off
	v_lshl_add_u64 v[216:217], s[38:39], 0, v[146:147]
	s_mov_b32 m0, s0
	s_nop 0
	global_load_lds_dwordx4 v[216:217], off
	v_lshl_add_u64 v[216:217], s[38:39], 0, v[150:151]
	s_add_i32 m0, s0, 0x2000
	s_nop 0
	global_load_lds_dwordx4 v[216:217], off
	v_lshl_add_u64 v[216:217], v[220:221], 0, s[10:11]
	s_mov_b32 m0, s92
	s_nop 0
	global_load_lds_dwordx4 v[216:217], off
	v_lshl_add_u64 v[216:217], v[222:223], 0, s[10:11]
	s_mov_b32 m0, s93
	s_nop 0
	global_load_lds_dwordx4 v[216:217], off
	s_waitcnt vmcnt(8)
	s_waitcnt lgkmcnt(0)
	s_barrier
	s_setprio 1
	s_waitcnt lgkmcnt(0)
	v_mfma_f32_16x16x32_bf16 v[60:63], v[128:131], v[178:181], v[60:63]
	v_mfma_f32_16x16x32_bf16 v[56:59], v[136:139], v[178:181], v[56:59]
	v_mfma_f32_16x16x32_bf16 v[44:47], v[128:131], v[186:189], v[44:47]
	v_mfma_f32_16x16x32_bf16 v[40:43], v[136:139], v[186:189], v[40:43]
	v_mfma_f32_16x16x32_bf16 v[28:31], v[128:131], v[194:197], v[28:31]
	v_mfma_f32_16x16x32_bf16 v[24:27], v[136:139], v[194:197], v[24:27]
	v_mfma_f32_16x16x32_bf16 v[12:15], v[128:131], v[208:211], v[12:15]
	v_mfma_f32_16x16x32_bf16 v[8:11], v[136:139], v[208:211], v[8:11]
	v_mfma_f32_16x16x32_bf16 v[60:63], v[132:135], v[182:185], v[60:63]
	v_mfma_f32_16x16x32_bf16 v[56:59], v[140:143], v[182:185], v[56:59]
	v_mfma_f32_16x16x32_bf16 v[44:47], v[132:135], v[190:193], v[44:47]
	v_mfma_f32_16x16x32_bf16 v[40:43], v[140:143], v[190:193], v[40:43]
	v_mfma_f32_16x16x32_bf16 v[28:31], v[132:135], v[204:207], v[28:31]
	v_mfma_f32_16x16x32_bf16 v[24:27], v[140:143], v[204:207], v[24:27]
	v_mfma_f32_16x16x32_bf16 v[12:15], v[132:135], v[212:215], v[12:15]
	v_mfma_f32_16x16x32_bf16 v[8:11], v[140:143], v[212:215], v[8:11]
	s_setprio 0
	s_setprio 1
	v_mfma_f32_16x16x32_bf16 v[52:55], v[162:165], v[178:181], v[52:55]
	v_mfma_f32_16x16x32_bf16 v[48:51], v[170:173], v[178:181], v[48:51]
	v_mfma_f32_16x16x32_bf16 v[36:39], v[162:165], v[186:189], v[36:39]
	v_mfma_f32_16x16x32_bf16 v[32:35], v[170:173], v[186:189], v[32:35]
	v_mfma_f32_16x16x32_bf16 v[20:23], v[162:165], v[194:197], v[20:23]
	v_mfma_f32_16x16x32_bf16 v[16:19], v[170:173], v[194:197], v[16:19]
	v_mfma_f32_16x16x32_bf16 v[4:7], v[162:165], v[208:211], v[4:7]
	v_mfma_f32_16x16x32_bf16 v[0:3], v[170:173], v[208:211], v[0:3]
	v_mfma_f32_16x16x32_bf16 v[52:55], v[166:169], v[182:185], v[52:55]
	v_mfma_f32_16x16x32_bf16 v[48:51], v[174:177], v[182:185], v[48:51]
	v_mfma_f32_16x16x32_bf16 v[36:39], v[166:169], v[190:193], v[36:39]
	v_mfma_f32_16x16x32_bf16 v[32:35], v[174:177], v[190:193], v[32:35]
	v_mfma_f32_16x16x32_bf16 v[20:23], v[166:169], v[204:207], v[20:23]
	v_mfma_f32_16x16x32_bf16 v[16:19], v[174:177], v[204:207], v[16:19]
	v_mfma_f32_16x16x32_bf16 v[4:7], v[166:169], v[212:215], v[4:7]
	v_mfma_f32_16x16x32_bf16 v[0:3], v[174:177], v[212:215], v[0:3]
	s_setprio 0
	s_add_i32 s69, s69, 2
	s_add_u32 s35, s35, 0x100
	s_addc_u32 s68, s68, 0
	s_add_u32 s62, s62, 0x100
	s_addc_u32 s63, s63, 0
	s_cmp_gt_u32 s69, 13
	s_barrier
	s_cbranch_scc0 .LBB0_2157
	s_and_b64 vcc, exec, s[18:19]
	s_cbranch_vccz .LBB0_2160
	s_barrier

; #define PG8_STAGE(bufoff, gbase, voff) do { _Pragma("unroll") for (int _i = 0; _i < 2; ++_i) \
;         __builtin_amdgcn_global_load_lds((const unsigned*)((const char*)(gbase) + (voff)[_i]), (LAS unsigned*)(lds + (bufoff) + ldsw + _i * 8192), 16, 0, 0); } while (0)
; #define PG8_LDA(dst, b, h) do { _Pragma("unroll") for (int m = 0; m < 4; ++m) _Pragma("unroll") for (int k = 0; k < 2; ++k) dst[m][k] = *(const LAS bf16x8*)(lds + PG8_SA(b, h) + aoff + m * 2048 + k * 1024); } while (0)
; #define PG8_LDB(dst, b, h) do { _Pragma("unroll") for (int n = 0; n < 2; ++n) _Pragma("unroll") for (int k = 0; k < 2; ++k) dst[n][k] = *(const LAS bf16x8*)(lds + PG8_SB(b, h) + boff + n * 2048 + k * 1024); } while (0)
; #define PG8_MMA(ai, bj, At, Bt) do { __builtin_amdgcn_s_setprio(1); _Pragma("unroll") for (int m = 0; m < 4; ++m) _Pragma("unroll") for (int n = 0; n < 2; ++n) _Pragma("unroll") for (int k = 0; k < 2; ++k) \
;         acc[ai][bj][m][n] = __builtin_amdgcn_mfma_f32_16x16x32_bf16(Bt[n][k], At[m][k], acc[ai][bj][m][n], 0, 0, 0); __builtin_amdgcn_s_setprio(0); } while (0)
; #define PG8_WAIT_V(n) asm volatile("s_waitcnt vmcnt(" #n ")" ::: "memory")
; #define PG8_WAIT_L(n) asm volatile("s_waitcnt lgkmcnt(" #n ")" ::: "memory")
; #define PG8_BAR __builtin_amdgcn_s_barrier()
; #define PG8_SCHED __builtin_amdgcn_sched_barrier(0)
; template <class Epi, class Sched>
; DI void gemm_phase(LAS unsigned char* lds, const Gemm g, const Sched& S, const Epi& E) {
;     ...
;     for (int t = 0; t < nt; t += 2) {
;       const bool last = (t == nt - 2);
;       const char* a1 = cA + (size_t)(t + 1) * kstep;
;       const char* a2 = last ? nA : cA + (size_t)(t + 2) * kstep; const char* b2 = last ? nB : cB + (size_t)(t + 2) * kstep;
;       const char* a3 = a2 + kstep; const char* b3 = b2 + kstep;
;       PG8_LDB(B0, 0, 0); PG8_LDB(B1, 0, 1); PG8_SCHED; PG8_LDA(At, 0, 0); PG8_STAGE(PG8_SA(1, 1), a1 + hstepA, voffA);
;       PG8_WAIT_V(8); PG8_WAIT_L(0); PG8_BAR; PG8_MMA(0, 0, At, B0); PG8_MMA(0, 1, At, B1); PG8_BAR; PG8_SCHED;
;       PG8_LDA(At, 0, 1); PG8_STAGE(PG8_SB(0, 0), b2, voffB); PG8_STAGE(PG8_SB(0, 1), b2 + hstepB, voffB); PG8_STAGE(PG8_SA(0, 0), a2, voffA);
;       PG8_WAIT_V(8); PG8_WAIT_L(0); PG8_BAR; PG8_MMA(1, 0, At, B0); PG8_MMA(1, 1, At, B1); PG8_BAR; PG8_SCHED;
.LBB0_2714:
	ds_read_b128 v[128:131], v167
	ds_read_b128 v[132:135], v167 offset:1024
	ds_read_b128 v[154:157], v167 offset:2048
	ds_read_b128 v[158:161], v167 offset:3072
	ds_read_b128 v[162:165], v168
	ds_read_b128 v[180:183], v168 offset:1024
	ds_read_b128 v[184:187], v168 offset:2048
	ds_read_b128 v[188:191], v168 offset:3072
	s_add_u32 s0, s8, 0xfffc0080
	s_addc_u32 s1, s9, -1
	s_cmp_eq_u32 s92, 12
	s_cselect_b32 s61, s7, s1
	s_cselect_b32 s60, s14, s0
	s_cselect_b32 s11, s29, s91
	s_cselect_b32 s10, s31, s90
	v_lshl_add_u64 v[174:175], s[8:9], 0, v[148:149]
	s_add_i32 m0, s13, 0xc000
	ds_read_b128 v[192:195], v169
	ds_read_b128 v[196:199], v169 offset:1024
	ds_read_b128 v[200:203], v169 offset:2048
	ds_read_b128 v[204:207], v169 offset:3072
	ds_read_b128 v[208:211], v169 offset:4096
	ds_read_b128 v[212:215], v169 offset:5120
	ds_read_b128 v[216:219], v169 offset:6144
	ds_read_b128 v[220:223], v169 offset:7168
	global_load_lds_dwordx4 v[174:175], off
	v_lshl_add_u64 v[174:175], s[8:9], 0, v[146:147]
	s_add_i32 m0, s13, 0xe000
	s_nop 0
	global_load_lds_dwordx4 v[174:175], off
	s_waitcnt vmcnt(8)
	s_waitcnt lgkmcnt(0)
	s_barrier
	s_setprio 1
	s_waitcnt lgkmcnt(0)
	v_mfma_f32_16x16x32_bf16 v[124:127], v[128:131], v[192:195], v[124:127]
	v_mfma_f32_16x16x32_bf16 v[120:123], v[154:157], v[192:195], v[120:123]
	v_mfma_f32_16x16x32_bf16 v[104:107], v[128:131], v[200:203], v[104:107]
	v_mfma_f32_16x16x32_bf16 v[108:111], v[154:157], v[200:203], v[108:111]
	v_mfma_f32_16x16x32_bf16 v[88:91], v[128:131], v[208:211], v[88:91]
	v_mfma_f32_16x16x32_bf16 v[92:95], v[154:157], v[208:211], v[92:95]
	v_mfma_f32_16x16x32_bf16 v[72:75], v[128:131], v[216:219], v[72:75]
	v_mfma_f32_16x16x32_bf16 v[76:79], v[154:157], v[216:219], v[76:79]
	v_mfma_f32_16x16x32_bf16 v[124:127], v[132:135], v[196:199], v[124:127]
	v_mfma_f32_16x16x32_bf16 v[120:123], v[158:161], v[196:199], v[120:123]
	v_mfma_f32_16x16x32_bf16 v[104:107], v[132:135], v[204:207], v[104:107]
	v_mfma_f32_16x16x32_bf16 v[108:111], v[158:161], v[204:207], v[108:111]
	v_mfma_f32_16x16x32_bf16 v[88:91], v[132:135], v[212:215], v[88:91]
	v_mfma_f32_16x16x32_bf16 v[92:95], v[158:161], v[212:215], v[92:95]
	v_mfma_f32_16x16x32_bf16 v[72:75], v[132:135], v[220:223], v[72:75]
	v_mfma_f32_16x16x32_bf16 v[76:79], v[158:161], v[220:223], v[76:79]
	s_setprio 0
	s_setprio 1
	v_mfma_f32_16x16x32_bf16 v[116:119], v[162:165], v[192:195], v[116:119]
	v_mfma_f32_16x16x32_bf16 v[112:115], v[184:187], v[192:195], v[112:115]
	v_mfma_f32_16x16x32_bf16 v[100:103], v[162:165], v[200:203], v[100:103]
	v_mfma_f32_16x16x32_bf16 v[96:99], v[184:187], v[200:203], v[96:99]
	v_mfma_f32_16x16x32_bf16 v[84:87], v[162:165], v[208:211], v[84:87]
	v_mfma_f32_16x16x32_bf16 v[80:83], v[184:187], v[208:211], v[80:83]
	v_mfma_f32_16x16x32_bf16 v[68:71], v[162:165], v[216:219], v[68:71]
	v_mfma_f32_16x16x32_bf16 v[64:67], v[184:187], v[216:219], v[64:67]
	v_mfma_f32_16x16x32_bf16 v[116:119], v[180:183], v[196:199], v[116:119]
	v_mfma_f32_16x16x32_bf16 v[112:115], v[188:191], v[196:199], v[112:115]
	v_mfma_f32_16x16x32_bf16 v[100:103], v[180:183], v[204:207], v[100:103]
	v_mfma_f32_16x16x32_bf16 v[96:99], v[188:191], v[204:207], v[96:99]
	v_mfma_f32_16x16x32_bf16 v[84:87], v[180:183], v[212:215], v[84:87]
	v_mfma_f32_16x16x32_bf16 v[80:83], v[188:191], v[212:215], v[80:83]
	v_mfma_f32_16x16x32_bf16 v[68:71], v[180:183], v[220:223], v[68:71]
	v_mfma_f32_16x16x32_bf16 v[64:67], v[188:191], v[220:223], v[64:67]
	s_setprio 0
	s_barrier
	s_add_i32 s0, s73, s42
	v_lshl_add_u64 v[174:175], s[10:11], 0, v[138:139]
	s_mov_b32 m0, s0
	ds_read_b128 v[192:195], v169 offset:16384
	ds_read_b128 v[196:199], v169 offset:17408
	ds_read_b128 v[200:203], v169 offset:18432
	ds_read_b128 v[204:207], v169 offset:19456
	ds_read_b128 v[208:211], v169 offset:20480
	ds_read_b128 v[212:215], v169 offset:21504
	ds_read_b128 v[216:219], v169 offset:22528
	ds_read_b128 v[220:223], v169 offset:23552
	global_load_lds_dwordx4 v[174:175], off
	s_add_i32 m0, s0, 0x2000
	s_add_u32 s38, s10, 0x40000
	v_lshl_add_u64 v[226:227], s[10:11], 0, v[142:143]
	s_addc_u32 s39, s11, 0
	s_add_i32 s0, s74, s42
	global_load_lds_dwordx4 v[226:227], off
	v_lshl_add_u64 v[228:229], s[38:39], 0, v[138:139]
	s_mov_b32 m0, s0
	v_lshl_add_u64 v[230:231], s[60:61], 0, v[140:141]
	global_load_lds_dwordx4 v[228:229], off
	v_lshl_add_u64 v[228:229], s[38:39], 0, v[142:143]
	s_add_i32 m0, s0, 0x2000
	s_nop 0
	global_load_lds_dwordx4 v[228:229], off
	v_lshl_add_u64 v[228:229], s[60:61], 0, v[136:137]
	s_mov_b32 m0, s13
	s_nop 0
	global_load_lds_dwordx4 v[228:229], off
	s_mov_b32 m0, s63
	s_nop 0
	global_load_lds_dwordx4 v[230:231], off
	s_waitcnt vmcnt(8)
	s_waitcnt lgkmcnt(0)
	s_barrier
; #define PG8_STAGE(bufoff, gbase, voff) do { _Pragma("unroll") for (int _i = 0; _i < 2; ++_i) \
;         __builtin_amdgcn_global_load_lds((const unsigned*)((const char*)(gbase) + (voff)[_i]), (LAS unsigned*)(lds + (bufoff) + ldsw + _i * 8192), 16, 0, 0); } while (0)
; #define PG8_LDA(dst, b, h) do { _Pragma("unroll") for (int m = 0; m < 4; ++m) _Pragma("unroll") for (int k = 0; k < 2; ++k) dst[m][k] = *(const LAS bf16x8*)(lds + PG8_SA(b, h) + aoff + m * 2048 + k * 1024); } while (0)
; #define PG8_LDB(dst, b, h) do { _Pragma("unroll") for (int n = 0; n < 2; ++n) _Pragma("unroll") for (int k = 0; k < 2; ++k) dst[n][k] = *(const LAS bf16x8*)(lds + PG8_SB(b, h) + boff + n * 2048 + k * 1024); } while (0)
; #define PG8_MMA(ai, bj, At, Bt) do { __builtin_amdgcn_s_setprio(1); _Pragma("unroll") for (int m = 0; m < 4; ++m) _Pragma("unroll") for (int n = 0; n < 2; ++n) _Pragma("unroll") for (int k = 0; k < 2; ++k) \
;         acc[ai][bj][m][n] = __builtin_amdgcn_mfma_f32_16x16x32_bf16(Bt[n][k], At[m][k], acc[ai][bj][m][n], 0, 0, 0); __builtin_amdgcn_s_setprio(0); } while (0)
; #define PG8_WAIT_V(n) asm volatile("s_waitcnt vmcnt(" #n ")" ::: "memory")
; #define PG8_WAIT_L(n) asm volatile("s_waitcnt lgkmcnt(" #n ")" ::: "memory")
; #define PG8_BAR __builtin_amdgcn_s_barrier()
; #define PG8_SCHED __builtin_amdgcn_sched_barrier(0)
; template <class Epi, class Sched>
; DI void gemm_phase(LAS unsigned char* lds, const Gemm g, const Sched& S, const Epi& E) {
;     ...
;       PG8_WAIT_V(8); PG8_WAIT_L(0); PG8_BAR; PG8_MMA(1, 0, At, B0); PG8_MMA(1, 1, At, B1); PG8_BAR; PG8_SCHED;
;       PG8_LDB(B0, 1, 0); PG8_LDB(B1, 1, 1); PG8_SCHED; PG8_LDA(At, 1, 0); PG8_STAGE(PG8_SA(0, 1), a2 + hstepA, voffA);
;       PG8_WAIT_V(8); PG8_WAIT_L(0); PG8_BAR; PG8_MMA(0, 0, At, B0); PG8_MMA(0, 1, At, B1); PG8_BAR; PG8_SCHED;
	s_setprio 1
	s_waitcnt lgkmcnt(0)
	v_mfma_f32_16x16x32_bf16 v[56:59], v[128:131], v[192:195], v[56:59]
	v_mfma_f32_16x16x32_bf16 v[60:63], v[154:157], v[192:195], v[60:63]
	v_mfma_f32_16x16x32_bf16 v[40:43], v[128:131], v[200:203], v[40:43]
	v_mfma_f32_16x16x32_bf16 v[44:47], v[154:157], v[200:203], v[44:47]
	v_mfma_f32_16x16x32_bf16 v[24:27], v[128:131], v[208:211], v[24:27]
	v_mfma_f32_16x16x32_bf16 v[28:31], v[154:157], v[208:211], v[28:31]
	v_mfma_f32_16x16x32_bf16 v[8:11], v[128:131], v[216:219], v[8:11]
	v_mfma_f32_16x16x32_bf16 v[12:15], v[154:157], v[216:219], v[12:15]
	v_mfma_f32_16x16x32_bf16 v[56:59], v[132:135], v[196:199], v[56:59]
	v_mfma_f32_16x16x32_bf16 v[60:63], v[158:161], v[196:199], v[60:63]
	v_mfma_f32_16x16x32_bf16 v[40:43], v[132:135], v[204:207], v[40:43]
	v_mfma_f32_16x16x32_bf16 v[44:47], v[158:161], v[204:207], v[44:47]
	v_mfma_f32_16x16x32_bf16 v[24:27], v[132:135], v[212:215], v[24:27]
	v_mfma_f32_16x16x32_bf16 v[28:31], v[158:161], v[212:215], v[28:31]
	v_mfma_f32_16x16x32_bf16 v[8:11], v[132:135], v[220:223], v[8:11]
	v_mfma_f32_16x16x32_bf16 v[12:15], v[158:161], v[220:223], v[12:15]
	s_setprio 0
	s_setprio 1
	v_mfma_f32_16x16x32_bf16 v[52:55], v[162:165], v[192:195], v[52:55]
	v_mfma_f32_16x16x32_bf16 v[48:51], v[184:187], v[192:195], v[48:51]
	v_mfma_f32_16x16x32_bf16 v[36:39], v[162:165], v[200:203], v[36:39]
	v_mfma_f32_16x16x32_bf16 v[32:35], v[184:187], v[200:203], v[32:35]
	v_mfma_f32_16x16x32_bf16 v[20:23], v[162:165], v[208:211], v[20:23]
	v_mfma_f32_16x16x32_bf16 v[16:19], v[184:187], v[208:211], v[16:19]
	v_mfma_f32_16x16x32_bf16 v[4:7], v[162:165], v[216:219], v[4:7]
	v_mfma_f32_16x16x32_bf16 v[0:3], v[184:187], v[216:219], v[0:3]
	v_mfma_f32_16x16x32_bf16 v[52:55], v[180:183], v[196:199], v[52:55]
	v_mfma_f32_16x16x32_bf16 v[48:51], v[188:191], v[196:199], v[48:51]
	v_mfma_f32_16x16x32_bf16 v[36:39], v[180:183], v[204:207], v[36:39]
	v_mfma_f32_16x16x32_bf16 v[32:35], v[188:191], v[204:207], v[32:35]
	v_mfma_f32_16x16x32_bf16 v[20:23], v[180:183], v[212:215], v[20:23]
	v_mfma_f32_16x16x32_bf16 v[16:19], v[188:191], v[212:215], v[16:19]
	v_mfma_f32_16x16x32_bf16 v[4:7], v[180:183], v[220:223], v[4:7]
	v_mfma_f32_16x16x32_bf16 v[0:3], v[188:191], v[220:223], v[0:3]
	s_setprio 0
	s_barrier
	s_add_i32 s0, 0, 0x18000
	v_add_u32_e32 v144, s0, v166
	s_add_i32 s1, 0, 0x1c000
	ds_read_b128 v[128:131], v144
	ds_read_b128 v[132:135], v144 offset:1024
	ds_read_b128 v[154:157], v144 offset:2048
	ds_read_b128 v[158:161], v144 offset:3072
	v_add_u32_e32 v144, s1, v166
	ds_read_b128 v[162:165], v144
	ds_read_b128 v[180:183], v144 offset:1024
	ds_read_b128 v[184:187], v144 offset:2048
	ds_read_b128 v[188:191], v144 offset:3072
	s_add_u32 s38, s60, 0x40000
	s_addc_u32 s39, s61, 0
	s_mov_b32 m0, s64
	v_lshl_add_u64 v[232:233], s[38:39], 0, v[136:137]
	ds_read_b128 v[192:195], v169 offset:32768
	ds_read_b128 v[196:199], v169 offset:33792
	ds_read_b128 v[200:203], v169 offset:34816
	ds_read_b128 v[204:207], v169 offset:35840
	ds_read_b128 v[208:211], v169 offset:36864
	ds_read_b128 v[212:215], v169 offset:37888
	ds_read_b128 v[216:219], v169 offset:38912
	ds_read_b128 v[220:223], v169 offset:39936
	global_load_lds_dwordx4 v[232:233], off
	v_lshl_add_u64 v[232:233], s[38:39], 0, v[140:141]
	s_mov_b32 m0, s65
	s_nop 0
	global_load_lds_dwordx4 v[232:233], off
	s_waitcnt vmcnt(8)
	s_waitcnt lgkmcnt(0)
	s_barrier
	s_setprio 1
	s_waitcnt lgkmcnt(0)
	v_mfma_f32_16x16x32_bf16 v[124:127], v[128:131], v[192:195], v[124:127]
	v_mfma_f32_16x16x32_bf16 v[120:123], v[154:157], v[192:195], v[120:123]
	v_mfma_f32_16x16x32_bf16 v[104:107], v[128:131], v[200:203], v[104:107]
	v_mfma_f32_16x16x32_bf16 v[108:111], v[154:157], v[200:203], v[108:111]
	v_mfma_f32_16x16x32_bf16 v[88:91], v[128:131], v[208:211], v[88:91]
	v_mfma_f32_16x16x32_bf16 v[92:95], v[154:157], v[208:211], v[92:95]
	v_mfma_f32_16x16x32_bf16 v[72:75], v[128:131], v[216:219], v[72:75]
	v_mfma_f32_16x16x32_bf16 v[76:79], v[154:157], v[216:219], v[76:79]
	v_mfma_f32_16x16x32_bf16 v[124:127], v[132:135], v[196:199], v[124:127]
	v_mfma_f32_16x16x32_bf16 v[120:123], v[158:161], v[196:199], v[120:123]
	v_mfma_f32_16x16x32_bf16 v[104:107], v[132:135], v[204:207], v[104:107]
	v_mfma_f32_16x16x32_bf16 v[108:111], v[158:161], v[204:207], v[108:111]
	v_mfma_f32_16x16x32_bf16 v[88:91], v[132:135], v[212:215], v[88:91]
	v_mfma_f32_16x16x32_bf16 v[92:95], v[158:161], v[212:215], v[92:95]
	v_mfma_f32_16x16x32_bf16 v[72:75], v[132:135], v[220:223], v[72:75]
	v_mfma_f32_16x16x32_bf16 v[76:79], v[158:161], v[220:223], v[76:79]
	s_setprio 0
	s_setprio 1
	v_mfma_f32_16x16x32_bf16 v[116:119], v[162:165], v[192:195], v[116:119]
	v_mfma_f32_16x16x32_bf16 v[112:115], v[184:187], v[192:195], v[112:115]
	v_mfma_f32_16x16x32_bf16 v[100:103], v[162:165], v[200:203], v[100:103]
	v_mfma_f32_16x16x32_bf16 v[96:99], v[184:187], v[200:203], v[96:99]
	v_mfma_f32_16x16x32_bf16 v[84:87], v[162:165], v[208:211], v[84:87]
	v_mfma_f32_16x16x32_bf16 v[80:83], v[184:187], v[208:211], v[80:83]
	v_mfma_f32_16x16x32_bf16 v[68:71], v[162:165], v[216:219], v[68:71]
	v_mfma_f32_16x16x32_bf16 v[64:67], v[184:187], v[216:219], v[64:67]
	v_mfma_f32_16x16x32_bf16 v[116:119], v[180:183], v[196:199], v[116:119]
	v_mfma_f32_16x16x32_bf16 v[112:115], v[188:191], v[196:199], v[112:115]
	v_mfma_f32_16x16x32_bf16 v[100:103], v[180:183], v[204:207], v[100:103]
	v_mfma_f32_16x16x32_bf16 v[96:99], v[188:191], v[204:207], v[96:99]
	v_mfma_f32_16x16x32_bf16 v[84:87], v[180:183], v[212:215], v[84:87]
	v_mfma_f32_16x16x32_bf16 v[80:83], v[188:191], v[212:215], v[80:83]
	v_mfma_f32_16x16x32_bf16 v[68:71], v[180:183], v[220:223], v[68:71]
	v_mfma_f32_16x16x32_bf16 v[64:67], v[188:191], v[220:223], v[64:67]
	s_setprio 0
	s_barrier
; #define PG8_STAGE(bufoff, gbase, voff) do { _Pragma("unroll") for (int _i = 0; _i < 2; ++_i) \
;         __builtin_amdgcn_global_load_lds((const unsigned*)((const char*)(gbase) + (voff)[_i]), (LAS unsigned*)(lds + (bufoff) + ldsw + _i * 8192), 16, 0, 0); } while (0)
; #define PG8_LDA(dst, b, h) do { _Pragma("unroll") for (int m = 0; m < 4; ++m) _Pragma("unroll") for (int k = 0; k < 2; ++k) dst[m][k] = *(const LAS bf16x8*)(lds + PG8_SA(b, h) + aoff + m * 2048 + k * 1024); } while (0)
; #define PG8_MMA(ai, bj, At, Bt) do { __builtin_amdgcn_s_setprio(1); _Pragma("unroll") for (int m = 0; m < 4; ++m) _Pragma("unroll") for (int n = 0; n < 2; ++n) _Pragma("unroll") for (int k = 0; k < 2; ++k) \
;         acc[ai][bj][m][n] = __builtin_amdgcn_mfma_f32_16x16x32_bf16(Bt[n][k], At[m][k], acc[ai][bj][m][n], 0, 0, 0); __builtin_amdgcn_s_setprio(0); } while (0)
; #define PG8_WAIT_V(n) asm volatile("s_waitcnt vmcnt(" #n ")" ::: "memory")
; #define PG8_WAIT_L(n) asm volatile("s_waitcnt lgkmcnt(" #n ")" ::: "memory")
; #define PG8_BAR __builtin_amdgcn_s_barrier()
; #define PG8_SCHED __builtin_amdgcn_sched_barrier(0)
; template <class Epi, class Sched>
; DI void gemm_phase(LAS unsigned char* lds, const Gemm g, const Sched& S, const Epi& E) {
;     ...
;     for (int t = 0; t < nt; t += 2) {
;       const bool last = (t == nt - 2);
;       const char* a1 = cA + (size_t)(t + 1) * kstep;
;       const char* a2 = last ? nA : cA + (size_t)(t + 2) * kstep; const char* b2 = last ? nB : cB + (size_t)(t + 2) * kstep;
;     ...
;       PG8_LDA(At, 1, 1); PG8_STAGE(PG8_SB(1, 0), b3, voffB); PG8_STAGE(PG8_SB(1, 1), b3 + hstepB, voffB); PG8_STAGE(PG8_SA(1, 0), a3, voffA);
;       PG8_WAIT_V(8); PG8_WAIT_L(0); PG8_BAR; PG8_MMA(1, 0, At, B0); PG8_MMA(1, 1, At, B1); PG8_BAR; PG8_SCHED;
;     }
	s_add_i32 s0, s0, s42
	v_lshl_add_u64 v[174:175], v[174:175], 0, s[20:21]
	s_mov_b32 m0, s0
	ds_read_b128 v[192:195], v169 offset:49152
	ds_read_b128 v[196:199], v169 offset:50176
	ds_read_b128 v[200:203], v169 offset:51200
	ds_read_b128 v[204:207], v169 offset:52224
	ds_read_b128 v[208:211], v169 offset:53248
	ds_read_b128 v[212:215], v169 offset:54272
	ds_read_b128 v[216:219], v169 offset:55296
	ds_read_b128 v[220:223], v169 offset:56320
	global_load_lds_dwordx4 v[174:175], off
	s_add_i32 m0, s0, 0x2000
	s_add_u32 s10, s10, 0x40080
	v_lshl_add_u64 v[174:175], v[226:227], 0, s[20:21]
	s_addc_u32 s11, s11, 0
	s_add_i32 s0, s1, s42
	global_load_lds_dwordx4 v[174:175], off
	v_lshl_add_u64 v[174:175], s[10:11], 0, v[138:139]
	s_mov_b32 m0, s0
	s_nop 0
	global_load_lds_dwordx4 v[174:175], off
	v_lshl_add_u64 v[174:175], s[10:11], 0, v[142:143]
	s_add_i32 m0, s0, 0x2000
	s_nop 0
	global_load_lds_dwordx4 v[174:175], off
	v_lshl_add_u64 v[174:175], v[228:229], 0, s[20:21]
	s_mov_b32 m0, s69
	s_nop 0
	global_load_lds_dwordx4 v[174:175], off
	v_lshl_add_u64 v[174:175], v[230:231], 0, s[20:21]
	s_mov_b32 m0, s70
	s_nop 0
	global_load_lds_dwordx4 v[174:175], off
	s_waitcnt vmcnt(8)
	s_waitcnt lgkmcnt(0)
	s_barrier
	s_setprio 1
	s_waitcnt lgkmcnt(0)
	v_mfma_f32_16x16x32_bf16 v[56:59], v[128:131], v[192:195], v[56:59]
	v_mfma_f32_16x16x32_bf16 v[60:63], v[154:157], v[192:195], v[60:63]
	v_mfma_f32_16x16x32_bf16 v[40:43], v[128:131], v[200:203], v[40:43]
	v_mfma_f32_16x16x32_bf16 v[44:47], v[154:157], v[200:203], v[44:47]
	v_mfma_f32_16x16x32_bf16 v[24:27], v[128:131], v[208:211], v[24:27]
	v_mfma_f32_16x16x32_bf16 v[28:31], v[154:157], v[208:211], v[28:31]
	v_mfma_f32_16x16x32_bf16 v[8:11], v[128:131], v[216:219], v[8:11]
	v_mfma_f32_16x16x32_bf16 v[12:15], v[154:157], v[216:219], v[12:15]
	v_mfma_f32_16x16x32_bf16 v[56:59], v[132:135], v[196:199], v[56:59]
	v_mfma_f32_16x16x32_bf16 v[60:63], v[158:161], v[196:199], v[60:63]
	v_mfma_f32_16x16x32_bf16 v[40:43], v[132:135], v[204:207], v[40:43]
	v_mfma_f32_16x16x32_bf16 v[44:47], v[158:161], v[204:207], v[44:47]
	v_mfma_f32_16x16x32_bf16 v[24:27], v[132:135], v[212:215], v[24:27]
	v_mfma_f32_16x16x32_bf16 v[28:31], v[158:161], v[212:215], v[28:31]
	v_mfma_f32_16x16x32_bf16 v[8:11], v[132:135], v[220:223], v[8:11]
	v_mfma_f32_16x16x32_bf16 v[12:15], v[158:161], v[220:223], v[12:15]
	s_setprio 0
	s_setprio 1
	v_mfma_f32_16x16x32_bf16 v[52:55], v[162:165], v[192:195], v[52:55]
	v_mfma_f32_16x16x32_bf16 v[48:51], v[184:187], v[192:195], v[48:51]
	v_mfma_f32_16x16x32_bf16 v[36:39], v[162:165], v[200:203], v[36:39]
	v_mfma_f32_16x16x32_bf16 v[32:35], v[184:187], v[200:203], v[32:35]
	v_mfma_f32_16x16x32_bf16 v[20:23], v[162:165], v[208:211], v[20:23]
	v_mfma_f32_16x16x32_bf16 v[16:19], v[184:187], v[208:211], v[16:19]
	v_mfma_f32_16x16x32_bf16 v[4:7], v[162:165], v[216:219], v[4:7]
	v_mfma_f32_16x16x32_bf16 v[0:3], v[184:187], v[216:219], v[0:3]
	v_mfma_f32_16x16x32_bf16 v[52:55], v[180:183], v[196:199], v[52:55]
	v_mfma_f32_16x16x32_bf16 v[48:51], v[188:191], v[196:199], v[48:51]
	v_mfma_f32_16x16x32_bf16 v[36:39], v[180:183], v[204:207], v[36:39]
	v_mfma_f32_16x16x32_bf16 v[32:35], v[188:191], v[204:207], v[32:35]
	v_mfma_f32_16x16x32_bf16 v[20:23], v[180:183], v[212:215], v[20:23]
	v_mfma_f32_16x16x32_bf16 v[16:19], v[188:191], v[212:215], v[16:19]
	v_mfma_f32_16x16x32_bf16 v[4:7], v[180:183], v[220:223], v[4:7]
	v_mfma_f32_16x16x32_bf16 v[0:3], v[188:191], v[220:223], v[0:3]
	s_setprio 0
	s_add_i32 s92, s92, 2
	s_add_u32 s90, s90, 0x100
	s_addc_u32 s91, s91, 0
	s_add_u32 s8, s8, 0x100
	s_addc_u32 s9, s9, 0
	s_cmp_gt_u32 s92, 13
	s_barrier
	s_cbranch_scc0 .LBB0_2714
	s_and_b64 vcc, exec, s[22:23]
	s_cbranch_vccz .LBB0_2717
	s_barrier

; #define PG8_STAGE(bufoff, gbase, voff) do { _Pragma("unroll") for (int _i = 0; _i < 2; ++_i) \
;         __builtin_amdgcn_global_load_lds((const unsigned*)((const char*)(gbase) + (voff)[_i]), (LAS unsigned*)(lds + (bufoff) + ldsw + _i * 8192), 16, 0, 0); } while (0)
; #define PG8_LDA(dst, b, h) do { _Pragma("unroll") for (int m = 0; m < 4; ++m) _Pragma("unroll") for (int k = 0; k < 2; ++k) dst[m][k] = *(const LAS bf16x8*)(lds + PG8_SA(b, h) + aoff + m * 2048 + k * 1024); } while (0)
; #define PG8_LDB(dst, b, h) do { _Pragma("unroll") for (int n = 0; n < 2; ++n) _Pragma("unroll") for (int k = 0; k < 2; ++k) dst[n][k] = *(const LAS bf16x8*)(lds + PG8_SB(b, h) + boff + n * 2048 + k * 1024); } while (0)
; #define PG8_MMA(ai, bj, At, Bt) do { __builtin_amdgcn_s_setprio(1); _Pragma("unroll") for (int m = 0; m < 4; ++m) _Pragma("unroll") for (int n = 0; n < 2; ++n) _Pragma("unroll") for (int k = 0; k < 2; ++k) \
;         acc[ai][bj][m][n] = __builtin_amdgcn_mfma_f32_16x16x32_bf16(Bt[n][k], At[m][k], acc[ai][bj][m][n], 0, 0, 0); __builtin_amdgcn_s_setprio(0); } while (0)
; #define PG8_WAIT_V(n) asm volatile("s_waitcnt vmcnt(" #n ")" ::: "memory")
; #define PG8_WAIT_L(n) asm volatile("s_waitcnt lgkmcnt(" #n ")" ::: "memory")
; #define PG8_BAR __builtin_amdgcn_s_barrier()
; #define PG8_SCHED __builtin_amdgcn_sched_barrier(0)
; template <class Epi, class Sched>
; DI void gemm_phase(LAS unsigned char* lds, const Gemm g, const Sched& S, const Epi& E) {
;     ...
;     for (int t = 0; t < nt; t += 2) {
;       const bool last = (t == nt - 2);
;       const char* a1 = cA + (size_t)(t + 1) * kstep;
;       const char* a2 = last ? nA : cA + (size_t)(t + 2) * kstep; const char* b2 = last ? nB : cB + (size_t)(t + 2) * kstep;
;       const char* a3 = a2 + kstep; const char* b3 = b2 + kstep;
;       PG8_LDB(B0, 0, 0); PG8_LDB(B1, 0, 1); PG8_SCHED; PG8_LDA(At, 0, 0); PG8_STAGE(PG8_SA(1, 1), a1 + hstepA, voffA);
;       PG8_WAIT_V(8); PG8_WAIT_L(0); PG8_BAR; PG8_MMA(0, 0, At, B0); PG8_MMA(0, 1, At, B1); PG8_BAR; PG8_SCHED;
;       PG8_LDA(At, 0, 1); PG8_STAGE(PG8_SB(0, 0), b2, voffB); PG8_STAGE(PG8_SB(0, 1), b2 + hstepB, voffB); PG8_STAGE(PG8_SA(0, 0), a2, voffA);
;       PG8_WAIT_V(8); PG8_WAIT_L(0); PG8_BAR; PG8_MMA(1, 0, At, B0); PG8_MMA(1, 1, At, B1); PG8_BAR; PG8_SCHED;
.LBB0_3003:
	ds_read_b128 v[152:155], v147
	ds_read_b128 v[156:159], v147 offset:1024
	ds_read_b128 v[160:163], v147 offset:2048
	ds_read_b128 v[164:167], v147 offset:3072
	ds_read_b128 v[168:171], v148
	ds_read_b128 v[172:175], v148 offset:1024
	ds_read_b128 v[176:179], v148 offset:2048
	ds_read_b128 v[180:183], v148 offset:3072
	s_add_u32 s0, s26, 0xfffc0080
	s_addc_u32 s1, s27, -1
	s_cmp_eq_u32 s69, 12
	s_cselect_b32 s31, s19, s1
	s_cselect_b32 s30, s65, s0
	s_cselect_b32 s29, s15, s68
	s_cselect_b32 s28, s66, s67
	v_lshl_add_u64 v[144:145], s[26:27], 0, v[138:139]
	s_add_i32 m0, s25, 0xc000
	ds_read_b128 v[184:187], v149
	ds_read_b128 v[188:191], v149 offset:1024
	ds_read_b128 v[192:195], v149 offset:2048
	ds_read_b128 v[196:199], v149 offset:3072
	ds_read_b128 v[200:203], v149 offset:4096
	ds_read_b128 v[204:207], v149 offset:5120
	ds_read_b128 v[208:211], v149 offset:6144
	ds_read_b128 v[212:215], v149 offset:7168
	global_load_lds_dwordx4 v[144:145], off
	v_lshl_add_u64 v[144:145], s[26:27], 0, v[136:137]
	s_add_i32 m0, s25, 0xe000
	s_nop 0
	global_load_lds_dwordx4 v[144:145], off
	s_waitcnt vmcnt(8)
	s_waitcnt lgkmcnt(0)
	s_barrier
	s_setprio 1
	s_waitcnt lgkmcnt(0)
	v_mfma_f32_16x16x32_bf16 v[124:127], v[152:155], v[184:187], v[124:127]
	v_mfma_f32_16x16x32_bf16 v[120:123], v[160:163], v[184:187], v[120:123]
	v_mfma_f32_16x16x32_bf16 v[108:111], v[152:155], v[192:195], v[108:111]
	v_mfma_f32_16x16x32_bf16 v[104:107], v[160:163], v[192:195], v[104:107]
	v_mfma_f32_16x16x32_bf16 v[92:95], v[152:155], v[200:203], v[92:95]
	v_mfma_f32_16x16x32_bf16 v[88:91], v[160:163], v[200:203], v[88:91]
	v_mfma_f32_16x16x32_bf16 v[76:79], v[152:155], v[208:211], v[76:79]
	v_mfma_f32_16x16x32_bf16 v[72:75], v[160:163], v[208:211], v[72:75]
	v_mfma_f32_16x16x32_bf16 v[124:127], v[156:159], v[188:191], v[124:127]
	v_mfma_f32_16x16x32_bf16 v[120:123], v[164:167], v[188:191], v[120:123]
	v_mfma_f32_16x16x32_bf16 v[108:111], v[156:159], v[196:199], v[108:111]
	v_mfma_f32_16x16x32_bf16 v[104:107], v[164:167], v[196:199], v[104:107]
	v_mfma_f32_16x16x32_bf16 v[92:95], v[156:159], v[204:207], v[92:95]
	v_mfma_f32_16x16x32_bf16 v[88:91], v[164:167], v[204:207], v[88:91]
	v_mfma_f32_16x16x32_bf16 v[76:79], v[156:159], v[212:215], v[76:79]
	v_mfma_f32_16x16x32_bf16 v[72:75], v[164:167], v[212:215], v[72:75]
	s_setprio 0
	s_setprio 1
	v_mfma_f32_16x16x32_bf16 v[116:119], v[168:171], v[184:187], v[116:119]
	v_mfma_f32_16x16x32_bf16 v[112:115], v[176:179], v[184:187], v[112:115]
	v_mfma_f32_16x16x32_bf16 v[100:103], v[168:171], v[192:195], v[100:103]
	v_mfma_f32_16x16x32_bf16 v[96:99], v[176:179], v[192:195], v[96:99]
	v_mfma_f32_16x16x32_bf16 v[84:87], v[168:171], v[200:203], v[84:87]
	v_mfma_f32_16x16x32_bf16 v[80:83], v[176:179], v[200:203], v[80:83]
	v_mfma_f32_16x16x32_bf16 v[68:71], v[168:171], v[208:211], v[68:71]
	v_mfma_f32_16x16x32_bf16 v[64:67], v[176:179], v[208:211], v[64:67]
	v_mfma_f32_16x16x32_bf16 v[116:119], v[172:175], v[188:191], v[116:119]
	v_mfma_f32_16x16x32_bf16 v[112:115], v[180:183], v[188:191], v[112:115]
	v_mfma_f32_16x16x32_bf16 v[100:103], v[172:175], v[196:199], v[100:103]
	v_mfma_f32_16x16x32_bf16 v[96:99], v[180:183], v[196:199], v[96:99]
	v_mfma_f32_16x16x32_bf16 v[84:87], v[172:175], v[204:207], v[84:87]
	v_mfma_f32_16x16x32_bf16 v[80:83], v[180:183], v[204:207], v[80:83]
	v_mfma_f32_16x16x32_bf16 v[68:71], v[172:175], v[212:215], v[68:71]
	v_mfma_f32_16x16x32_bf16 v[64:67], v[180:183], v[212:215], v[64:67]
	s_setprio 0
	s_barrier
	s_add_i32 s0, s62, s17
	v_lshl_add_u64 v[144:145], s[28:29], 0, v[132:133]
	s_mov_b32 m0, s0
	ds_read_b128 v[184:187], v149 offset:16384
	ds_read_b128 v[188:191], v149 offset:17408
	ds_read_b128 v[192:195], v149 offset:18432
	ds_read_b128 v[196:199], v149 offset:19456
	ds_read_b128 v[200:203], v149 offset:20480
	ds_read_b128 v[204:207], v149 offset:21504
	ds_read_b128 v[208:211], v149 offset:22528
	ds_read_b128 v[212:215], v149 offset:23552
	global_load_lds_dwordx4 v[144:145], off
	s_add_i32 m0, s0, 0x2000
	s_add_u32 s38, s28, 0x40000
	v_lshl_add_u64 v[216:217], s[28:29], 0, v[128:129]
	s_addc_u32 s39, s29, 0
	s_add_i32 s0, s63, s17
	global_load_lds_dwordx4 v[216:217], off
	v_lshl_add_u64 v[218:219], s[38:39], 0, v[132:133]
	s_mov_b32 m0, s0
	v_lshl_add_u64 v[220:221], s[30:31], 0, v[130:131]
	global_load_lds_dwordx4 v[218:219], off
	v_lshl_add_u64 v[218:219], s[38:39], 0, v[128:129]
	s_add_i32 m0, s0, 0x2000
	s_nop 0
	global_load_lds_dwordx4 v[218:219], off
	v_lshl_add_u64 v[218:219], s[30:31], 0, v[134:135]
	s_mov_b32 m0, s25
	s_nop 0
	global_load_lds_dwordx4 v[218:219], off
	s_mov_b32 m0, s34
	s_nop 0
	global_load_lds_dwordx4 v[220:221], off
	s_waitcnt vmcnt(8)
	s_waitcnt lgkmcnt(0)
	s_barrier
; #define PG8_STAGE(bufoff, gbase, voff) do { _Pragma("unroll") for (int _i = 0; _i < 2; ++_i) \
;         __builtin_amdgcn_global_load_lds((const unsigned*)((const char*)(gbase) + (voff)[_i]), (LAS unsigned*)(lds + (bufoff) + ldsw + _i * 8192), 16, 0, 0); } while (0)
; #define PG8_LDA(dst, b, h) do { _Pragma("unroll") for (int m = 0; m < 4; ++m) _Pragma("unroll") for (int k = 0; k < 2; ++k) dst[m][k] = *(const LAS bf16x8*)(lds + PG8_SA(b, h) + aoff + m * 2048 + k * 1024); } while (0)
; #define PG8_LDB(dst, b, h) do { _Pragma("unroll") for (int n = 0; n < 2; ++n) _Pragma("unroll") for (int k = 0; k < 2; ++k) dst[n][k] = *(const LAS bf16x8*)(lds + PG8_SB(b, h) + boff + n * 2048 + k * 1024); } while (0)
; #define PG8_MMA(ai, bj, At, Bt) do { __builtin_amdgcn_s_setprio(1); _Pragma("unroll") for (int m = 0; m < 4; ++m) _Pragma("unroll") for (int n = 0; n < 2; ++n) _Pragma("unroll") for (int k = 0; k < 2; ++k) \
;         acc[ai][bj][m][n] = __builtin_amdgcn_mfma_f32_16x16x32_bf16(Bt[n][k], At[m][k], acc[ai][bj][m][n], 0, 0, 0); __builtin_amdgcn_s_setprio(0); } while (0)
; #define PG8_WAIT_V(n) asm volatile("s_waitcnt vmcnt(" #n ")" ::: "memory")
; #define PG8_WAIT_L(n) asm volatile("s_waitcnt lgkmcnt(" #n ")" ::: "memory")
; #define PG8_BAR __builtin_amdgcn_s_barrier()
; #define PG8_SCHED __builtin_amdgcn_sched_barrier(0)
; template <class Epi, class Sched>
; DI void gemm_phase(LAS unsigned char* lds, const Gemm g, const Sched& S, const Epi& E) {
;     ...
;       PG8_WAIT_V(8); PG8_WAIT_L(0); PG8_BAR; PG8_MMA(1, 0, At, B0); PG8_MMA(1, 1, At, B1); PG8_BAR; PG8_SCHED;
;       PG8_LDB(B0, 1, 0); PG8_LDB(B1, 1, 1); PG8_SCHED; PG8_LDA(At, 1, 0); PG8_STAGE(PG8_SA(0, 1), a2 + hstepA, voffA);
;       PG8_WAIT_V(8); PG8_WAIT_L(0); PG8_BAR; PG8_MMA(0, 0, At, B0); PG8_MMA(0, 1, At, B1); PG8_BAR; PG8_SCHED;
	s_setprio 1
	s_waitcnt lgkmcnt(0)
	v_mfma_f32_16x16x32_bf16 v[60:63], v[152:155], v[184:187], v[60:63]
	v_mfma_f32_16x16x32_bf16 v[56:59], v[160:163], v[184:187], v[56:59]
	v_mfma_f32_16x16x32_bf16 v[44:47], v[152:155], v[192:195], v[44:47]
	v_mfma_f32_16x16x32_bf16 v[40:43], v[160:163], v[192:195], v[40:43]
	v_mfma_f32_16x16x32_bf16 v[28:31], v[152:155], v[200:203], v[28:31]
	v_mfma_f32_16x16x32_bf16 v[24:27], v[160:163], v[200:203], v[24:27]
	v_mfma_f32_16x16x32_bf16 v[12:15], v[152:155], v[208:211], v[12:15]
	v_mfma_f32_16x16x32_bf16 v[8:11], v[160:163], v[208:211], v[8:11]
	v_mfma_f32_16x16x32_bf16 v[60:63], v[156:159], v[188:191], v[60:63]
	v_mfma_f32_16x16x32_bf16 v[56:59], v[164:167], v[188:191], v[56:59]
	v_mfma_f32_16x16x32_bf16 v[44:47], v[156:159], v[196:199], v[44:47]
	v_mfma_f32_16x16x32_bf16 v[40:43], v[164:167], v[196:199], v[40:43]
	v_mfma_f32_16x16x32_bf16 v[28:31], v[156:159], v[204:207], v[28:31]
	v_mfma_f32_16x16x32_bf16 v[24:27], v[164:167], v[204:207], v[24:27]
	v_mfma_f32_16x16x32_bf16 v[12:15], v[156:159], v[212:215], v[12:15]
	v_mfma_f32_16x16x32_bf16 v[8:11], v[164:167], v[212:215], v[8:11]
	s_setprio 0
	s_setprio 1
	v_mfma_f32_16x16x32_bf16 v[52:55], v[168:171], v[184:187], v[52:55]
	v_mfma_f32_16x16x32_bf16 v[48:51], v[176:179], v[184:187], v[48:51]
	v_mfma_f32_16x16x32_bf16 v[36:39], v[168:171], v[192:195], v[36:39]
	v_mfma_f32_16x16x32_bf16 v[32:35], v[176:179], v[192:195], v[32:35]
	v_mfma_f32_16x16x32_bf16 v[20:23], v[168:171], v[200:203], v[20:23]
	v_mfma_f32_16x16x32_bf16 v[16:19], v[176:179], v[200:203], v[16:19]
	v_mfma_f32_16x16x32_bf16 v[4:7], v[168:171], v[208:211], v[4:7]
	v_mfma_f32_16x16x32_bf16 v[0:3], v[176:179], v[208:211], v[0:3]
	v_mfma_f32_16x16x32_bf16 v[52:55], v[172:175], v[188:191], v[52:55]
	v_mfma_f32_16x16x32_bf16 v[48:51], v[180:183], v[188:191], v[48:51]
	v_mfma_f32_16x16x32_bf16 v[36:39], v[172:175], v[196:199], v[36:39]
	v_mfma_f32_16x16x32_bf16 v[32:35], v[180:183], v[196:199], v[32:35]
	v_mfma_f32_16x16x32_bf16 v[20:23], v[172:175], v[204:207], v[20:23]
	v_mfma_f32_16x16x32_bf16 v[16:19], v[180:183], v[204:207], v[16:19]
	v_mfma_f32_16x16x32_bf16 v[4:7], v[172:175], v[212:215], v[4:7]
	v_mfma_f32_16x16x32_bf16 v[0:3], v[180:183], v[212:215], v[0:3]
	s_setprio 0
	s_barrier
	s_add_i32 s0, 0, 0x18000
	v_add_u32_e32 v151, s0, v146
	s_add_i32 s1, 0, 0x1c000
	ds_read_b128 v[152:155], v151
	ds_read_b128 v[156:159], v151 offset:1024
	ds_read_b128 v[160:163], v151 offset:2048
	ds_read_b128 v[164:167], v151 offset:3072
	v_add_u32_e32 v151, s1, v146
	ds_read_b128 v[168:171], v151
	ds_read_b128 v[172:175], v151 offset:1024
	ds_read_b128 v[176:179], v151 offset:2048
	ds_read_b128 v[180:183], v151 offset:3072
	s_add_u32 s30, s30, 0x40000
	s_addc_u32 s31, s31, 0
	s_mov_b32 m0, s35
	v_lshl_add_u64 v[222:223], s[30:31], 0, v[134:135]
	ds_read_b128 v[184:187], v149 offset:32768
	ds_read_b128 v[188:191], v149 offset:33792
	ds_read_b128 v[192:195], v149 offset:34816
	ds_read_b128 v[196:199], v149 offset:35840
	ds_read_b128 v[200:203], v149 offset:36864
	ds_read_b128 v[204:207], v149 offset:37888
	ds_read_b128 v[208:211], v149 offset:38912
	ds_read_b128 v[212:215], v149 offset:39936
	global_load_lds_dwordx4 v[222:223], off
	v_lshl_add_u64 v[222:223], s[30:31], 0, v[130:131]
	s_mov_b32 m0, s36
	s_nop 0
	global_load_lds_dwordx4 v[222:223], off
	s_waitcnt vmcnt(8)
	s_waitcnt lgkmcnt(0)
	s_barrier
	s_setprio 1
	s_waitcnt lgkmcnt(0)
	v_mfma_f32_16x16x32_bf16 v[124:127], v[152:155], v[184:187], v[124:127]
	v_mfma_f32_16x16x32_bf16 v[120:123], v[160:163], v[184:187], v[120:123]
	v_mfma_f32_16x16x32_bf16 v[108:111], v[152:155], v[192:195], v[108:111]
	v_mfma_f32_16x16x32_bf16 v[104:107], v[160:163], v[192:195], v[104:107]
	v_mfma_f32_16x16x32_bf16 v[92:95], v[152:155], v[200:203], v[92:95]
	v_mfma_f32_16x16x32_bf16 v[88:91], v[160:163], v[200:203], v[88:91]
	v_mfma_f32_16x16x32_bf16 v[76:79], v[152:155], v[208:211], v[76:79]
	v_mfma_f32_16x16x32_bf16 v[72:75], v[160:163], v[208:211], v[72:75]
	v_mfma_f32_16x16x32_bf16 v[124:127], v[156:159], v[188:191], v[124:127]
	v_mfma_f32_16x16x32_bf16 v[120:123], v[164:167], v[188:191], v[120:123]
	v_mfma_f32_16x16x32_bf16 v[108:111], v[156:159], v[196:199], v[108:111]
	v_mfma_f32_16x16x32_bf16 v[104:107], v[164:167], v[196:199], v[104:107]
	v_mfma_f32_16x16x32_bf16 v[92:95], v[156:159], v[204:207], v[92:95]
	v_mfma_f32_16x16x32_bf16 v[88:91], v[164:167], v[204:207], v[88:91]
	v_mfma_f32_16x16x32_bf16 v[76:79], v[156:159], v[212:215], v[76:79]
	v_mfma_f32_16x16x32_bf16 v[72:75], v[164:167], v[212:215], v[72:75]
	s_setprio 0
	s_setprio 1
	v_mfma_f32_16x16x32_bf16 v[116:119], v[168:171], v[184:187], v[116:119]
	v_mfma_f32_16x16x32_bf16 v[112:115], v[176:179], v[184:187], v[112:115]
	v_mfma_f32_16x16x32_bf16 v[100:103], v[168:171], v[192:195], v[100:103]
	v_mfma_f32_16x16x32_bf16 v[96:99], v[176:179], v[192:195], v[96:99]
	v_mfma_f32_16x16x32_bf16 v[84:87], v[168:171], v[200:203], v[84:87]
	v_mfma_f32_16x16x32_bf16 v[80:83], v[176:179], v[200:203], v[80:83]
	v_mfma_f32_16x16x32_bf16 v[68:71], v[168:171], v[208:211], v[68:71]
	v_mfma_f32_16x16x32_bf16 v[64:67], v[176:179], v[208:211], v[64:67]
	v_mfma_f32_16x16x32_bf16 v[116:119], v[172:175], v[188:191], v[116:119]
	v_mfma_f32_16x16x32_bf16 v[112:115], v[180:183], v[188:191], v[112:115]
	v_mfma_f32_16x16x32_bf16 v[100:103], v[172:175], v[196:199], v[100:103]
	v_mfma_f32_16x16x32_bf16 v[96:99], v[180:183], v[196:199], v[96:99]
	v_mfma_f32_16x16x32_bf16 v[84:87], v[172:175], v[204:207], v[84:87]
	v_mfma_f32_16x16x32_bf16 v[80:83], v[180:183], v[204:207], v[80:83]
	v_mfma_f32_16x16x32_bf16 v[68:71], v[172:175], v[212:215], v[68:71]
	v_mfma_f32_16x16x32_bf16 v[64:67], v[180:183], v[212:215], v[64:67]
	s_setprio 0
	s_barrier
; #define PG8_STAGE(bufoff, gbase, voff) do { _Pragma("unroll") for (int _i = 0; _i < 2; ++_i) \
;         __builtin_amdgcn_global_load_lds((const unsigned*)((const char*)(gbase) + (voff)[_i]), (LAS unsigned*)(lds + (bufoff) + ldsw + _i * 8192), 16, 0, 0); } while (0)
; #define PG8_LDA(dst, b, h) do { _Pragma("unroll") for (int m = 0; m < 4; ++m) _Pragma("unroll") for (int k = 0; k < 2; ++k) dst[m][k] = *(const LAS bf16x8*)(lds + PG8_SA(b, h) + aoff + m * 2048 + k * 1024); } while (0)
; #define PG8_MMA(ai, bj, At, Bt) do { __builtin_amdgcn_s_setprio(1); _Pragma("unroll") for (int m = 0; m < 4; ++m) _Pragma("unroll") for (int n = 0; n < 2; ++n) _Pragma("unroll") for (int k = 0; k < 2; ++k) \
;         acc[ai][bj][m][n] = __builtin_amdgcn_mfma_f32_16x16x32_bf16(Bt[n][k], At[m][k], acc[ai][bj][m][n], 0, 0, 0); __builtin_amdgcn_s_setprio(0); } while (0)
; #define PG8_WAIT_V(n) asm volatile("s_waitcnt vmcnt(" #n ")" ::: "memory")
; #define PG8_WAIT_L(n) asm volatile("s_waitcnt lgkmcnt(" #n ")" ::: "memory")
; #define PG8_BAR __builtin_amdgcn_s_barrier()
; #define PG8_SCHED __builtin_amdgcn_sched_barrier(0)
; template <class Epi, class Sched>
; DI void gemm_phase(LAS unsigned char* lds, const Gemm g, const Sched& S, const Epi& E) {
;     ...
;     for (int t = 0; t < nt; t += 2) {
;       const bool last = (t == nt - 2);
;       const char* a1 = cA + (size_t)(t + 1) * kstep;
;       const char* a2 = last ? nA : cA + (size_t)(t + 2) * kstep; const char* b2 = last ? nB : cB + (size_t)(t + 2) * kstep;
;     ...
;       PG8_LDA(At, 1, 1); PG8_STAGE(PG8_SB(1, 0), b3, voffB); PG8_STAGE(PG8_SB(1, 1), b3 + hstepB, voffB); PG8_STAGE(PG8_SA(1, 0), a3, voffA);
;       PG8_WAIT_V(8); PG8_WAIT_L(0); PG8_BAR; PG8_MMA(1, 0, At, B0); PG8_MMA(1, 1, At, B1); PG8_BAR; PG8_SCHED;
;     }
	s_add_i32 s0, s0, s17
	v_lshl_add_u64 v[144:145], v[144:145], 0, s[8:9]
	s_mov_b32 m0, s0
	ds_read_b128 v[184:187], v149 offset:49152
	ds_read_b128 v[188:191], v149 offset:50176
	ds_read_b128 v[192:195], v149 offset:51200
	ds_read_b128 v[196:199], v149 offset:52224
	ds_read_b128 v[200:203], v149 offset:53248
	ds_read_b128 v[204:207], v149 offset:54272
	ds_read_b128 v[208:211], v149 offset:55296
	ds_read_b128 v[212:215], v149 offset:56320
	global_load_lds_dwordx4 v[144:145], off
	s_add_i32 m0, s0, 0x2000
	s_add_u32 s28, s28, 0x40080
	v_lshl_add_u64 v[144:145], v[216:217], 0, s[8:9]
	s_addc_u32 s29, s29, 0
	s_add_i32 s0, s1, s17
	global_load_lds_dwordx4 v[144:145], off
	v_lshl_add_u64 v[144:145], s[28:29], 0, v[132:133]
	s_mov_b32 m0, s0
	s_nop 0
	global_load_lds_dwordx4 v[144:145], off
	v_lshl_add_u64 v[144:145], s[28:29], 0, v[128:129]
	s_add_i32 m0, s0, 0x2000
	s_nop 0
	global_load_lds_dwordx4 v[144:145], off
	v_lshl_add_u64 v[144:145], v[218:219], 0, s[8:9]
	s_mov_b32 m0, s60
	s_nop 0
	global_load_lds_dwordx4 v[144:145], off
	v_lshl_add_u64 v[144:145], v[220:221], 0, s[8:9]
	s_mov_b32 m0, s61
	s_nop 0
	global_load_lds_dwordx4 v[144:145], off
	s_waitcnt vmcnt(8)
	s_waitcnt lgkmcnt(0)
	s_barrier
	s_setprio 1
	s_waitcnt lgkmcnt(0)
	v_mfma_f32_16x16x32_bf16 v[60:63], v[152:155], v[184:187], v[60:63]
	v_mfma_f32_16x16x32_bf16 v[56:59], v[160:163], v[184:187], v[56:59]
	v_mfma_f32_16x16x32_bf16 v[44:47], v[152:155], v[192:195], v[44:47]
	v_mfma_f32_16x16x32_bf16 v[40:43], v[160:163], v[192:195], v[40:43]
	v_mfma_f32_16x16x32_bf16 v[28:31], v[152:155], v[200:203], v[28:31]
	v_mfma_f32_16x16x32_bf16 v[24:27], v[160:163], v[200:203], v[24:27]
	v_mfma_f32_16x16x32_bf16 v[12:15], v[152:155], v[208:211], v[12:15]
	v_mfma_f32_16x16x32_bf16 v[8:11], v[160:163], v[208:211], v[8:11]
	v_mfma_f32_16x16x32_bf16 v[60:63], v[156:159], v[188:191], v[60:63]
	v_mfma_f32_16x16x32_bf16 v[56:59], v[164:167], v[188:191], v[56:59]
	v_mfma_f32_16x16x32_bf16 v[44:47], v[156:159], v[196:199], v[44:47]
	v_mfma_f32_16x16x32_bf16 v[40:43], v[164:167], v[196:199], v[40:43]
	v_mfma_f32_16x16x32_bf16 v[28:31], v[156:159], v[204:207], v[28:31]
	v_mfma_f32_16x16x32_bf16 v[24:27], v[164:167], v[204:207], v[24:27]
	v_mfma_f32_16x16x32_bf16 v[12:15], v[156:159], v[212:215], v[12:15]
	v_mfma_f32_16x16x32_bf16 v[8:11], v[164:167], v[212:215], v[8:11]
	s_setprio 0
	s_setprio 1
	v_mfma_f32_16x16x32_bf16 v[52:55], v[168:171], v[184:187], v[52:55]
	v_mfma_f32_16x16x32_bf16 v[48:51], v[176:179], v[184:187], v[48:51]
	v_mfma_f32_16x16x32_bf16 v[36:39], v[168:171], v[192:195], v[36:39]
	v_mfma_f32_16x16x32_bf16 v[32:35], v[176:179], v[192:195], v[32:35]
	v_mfma_f32_16x16x32_bf16 v[20:23], v[168:171], v[200:203], v[20:23]
	v_mfma_f32_16x16x32_bf16 v[16:19], v[176:179], v[200:203], v[16:19]
	v_mfma_f32_16x16x32_bf16 v[4:7], v[168:171], v[208:211], v[4:7]
	v_mfma_f32_16x16x32_bf16 v[0:3], v[176:179], v[208:211], v[0:3]
	v_mfma_f32_16x16x32_bf16 v[52:55], v[172:175], v[188:191], v[52:55]
	v_mfma_f32_16x16x32_bf16 v[48:51], v[180:183], v[188:191], v[48:51]
	v_mfma_f32_16x16x32_bf16 v[36:39], v[172:175], v[196:199], v[36:39]
	v_mfma_f32_16x16x32_bf16 v[32:35], v[180:183], v[196:199], v[32:35]
	v_mfma_f32_16x16x32_bf16 v[20:23], v[172:175], v[204:207], v[20:23]
	v_mfma_f32_16x16x32_bf16 v[16:19], v[180:183], v[204:207], v[16:19]
	v_mfma_f32_16x16x32_bf16 v[4:7], v[172:175], v[212:215], v[4:7]
	v_mfma_f32_16x16x32_bf16 v[0:3], v[180:183], v[212:215], v[0:3]
	s_setprio 0
	s_add_i32 s69, s69, 2
	s_add_u32 s67, s67, 0x100
	s_addc_u32 s68, s68, 0
	s_add_u32 s26, s26, 0x100
	s_addc_u32 s27, s27, 0
	s_cmp_gt_u32 s69, 13
	s_barrier
	s_cbranch_scc0 .LBB0_3003
	s_and_b64 vcc, exec, s[10:11]
	s_cbranch_vccz .LBB0_3006
	s_barrier

; #define PG8_STAGE(bufoff, gbase, voff) do { _Pragma("unroll") for (int _i = 0; _i < 2; ++_i) \
;         __builtin_amdgcn_global_load_lds((const unsigned*)((const char*)(gbase) + (voff)[_i]), (LAS unsigned*)(lds + (bufoff) + ldsw + _i * 8192), 16, 0, 0); } while (0)
; #define PG8_LDA(dst, b, h) do { _Pragma("unroll") for (int m = 0; m < 4; ++m) _Pragma("unroll") for (int k = 0; k < 2; ++k) dst[m][k] = *(const LAS bf16x8*)(lds + PG8_SA(b, h) + aoff + m * 2048 + k * 1024); } while (0)
; #define PG8_LDB(dst, b, h) do { _Pragma("unroll") for (int n = 0; n < 2; ++n) _Pragma("unroll") for (int k = 0; k < 2; ++k) dst[n][k] = *(const LAS bf16x8*)(lds + PG8_SB(b, h) + boff + n * 2048 + k * 1024); } while (0)
; #define PG8_MMA(ai, bj, At, Bt) do { __builtin_amdgcn_s_setprio(1); _Pragma("unroll") for (int m = 0; m < 4; ++m) _Pragma("unroll") for (int n = 0; n < 2; ++n) _Pragma("unroll") for (int k = 0; k < 2; ++k) \
;         acc[ai][bj][m][n] = __builtin_amdgcn_mfma_f32_16x16x32_bf16(Bt[n][k], At[m][k], acc[ai][bj][m][n], 0, 0, 0); __builtin_amdgcn_s_setprio(0); } while (0)
; #define PG8_WAIT_V(n) asm volatile("s_waitcnt vmcnt(" #n ")" ::: "memory")
; #define PG8_WAIT_L(n) asm volatile("s_waitcnt lgkmcnt(" #n ")" ::: "memory")
; #define PG8_BAR __builtin_amdgcn_s_barrier()
; #define PG8_SCHED __builtin_amdgcn_sched_barrier(0)
; template <class Epi, class Sched>
; DI void gemm_phase(LAS unsigned char* lds, const Gemm g, const Sched& S, const Epi& E) {
;     ...
;     for (int t = 0; t < nt; t += 2) {
;       const bool last = (t == nt - 2);
;       const char* a1 = cA + (size_t)(t + 1) * kstep;
;       const char* a2 = last ? nA : cA + (size_t)(t + 2) * kstep; const char* b2 = last ? nB : cB + (size_t)(t + 2) * kstep;
;       const char* a3 = a2 + kstep; const char* b3 = b2 + kstep;
;       PG8_LDB(B0, 0, 0); PG8_LDB(B1, 0, 1); PG8_SCHED; PG8_LDA(At, 0, 0); PG8_STAGE(PG8_SA(1, 1), a1 + hstepA, voffA);
;       PG8_WAIT_V(8); PG8_WAIT_L(0); PG8_BAR; PG8_MMA(0, 0, At, B0); PG8_MMA(0, 1, At, B1); PG8_BAR; PG8_SCHED;
;       PG8_LDA(At, 0, 1); PG8_STAGE(PG8_SB(0, 0), b2, voffB); PG8_STAGE(PG8_SB(0, 1), b2 + hstepB, voffB); PG8_STAGE(PG8_SA(0, 0), a2, voffA);
;       PG8_WAIT_V(8); PG8_WAIT_L(0); PG8_BAR; PG8_MMA(1, 0, At, B0); PG8_MMA(1, 1, At, B1); PG8_BAR; PG8_SCHED;
.LBB0_3087:
	ds_read_b128 v[146:149], v159
	ds_read_b128 v[150:153], v159 offset:1024
	ds_read_b128 v[154:157], v159 offset:2048
	ds_read_b128 v[166:169], v159 offset:3072
	ds_read_b128 v[170:173], v160
	ds_read_b128 v[174:177], v160 offset:1024
	ds_read_b128 v[178:181], v160 offset:2048
	ds_read_b128 v[182:185], v160 offset:3072
	s_add_u32 s0, s30, 0xfff00080
	s_addc_u32 s1, s31, -1
	s_cmp_eq_u32 s89, 60
	s_cselect_b32 s37, s7, s1
	s_cselect_b32 s36, s9, s0
	s_cselect_b32 s35, s23, s88
	s_cselect_b32 s34, s25, s87
	v_lshl_add_u64 v[218:219], s[30:31], 0, v[140:141]
	s_add_i32 m0, s43, 0xc000
	ds_read_b128 v[186:189], v161
	ds_read_b128 v[190:193], v161 offset:1024
	ds_read_b128 v[194:197], v161 offset:2048
	ds_read_b128 v[198:201], v161 offset:3072
	ds_read_b128 v[202:205], v161 offset:4096
	ds_read_b128 v[206:209], v161 offset:5120
	ds_read_b128 v[210:213], v161 offset:6144
	ds_read_b128 v[214:217], v161 offset:7168
	global_load_lds_dwordx4 v[218:219], off
	v_lshl_add_u64 v[218:219], s[30:31], 0, v[138:139]
	s_add_i32 m0, s43, 0xe000
	s_nop 0
	global_load_lds_dwordx4 v[218:219], off
	s_waitcnt vmcnt(8)
	s_waitcnt lgkmcnt(0)
	s_barrier
	s_setprio 1
	s_waitcnt lgkmcnt(0)
	v_mfma_f32_16x16x32_bf16 v[124:127], v[146:149], v[186:189], v[124:127]
	v_mfma_f32_16x16x32_bf16 v[120:123], v[154:157], v[186:189], v[120:123]
	v_mfma_f32_16x16x32_bf16 v[108:111], v[146:149], v[194:197], v[108:111]
	v_mfma_f32_16x16x32_bf16 v[104:107], v[154:157], v[194:197], v[104:107]
	v_mfma_f32_16x16x32_bf16 v[92:95], v[146:149], v[202:205], v[92:95]
	v_mfma_f32_16x16x32_bf16 v[88:91], v[154:157], v[202:205], v[88:91]
	v_mfma_f32_16x16x32_bf16 v[76:79], v[146:149], v[210:213], v[76:79]
	v_mfma_f32_16x16x32_bf16 v[72:75], v[154:157], v[210:213], v[72:75]
	v_mfma_f32_16x16x32_bf16 v[124:127], v[150:153], v[190:193], v[124:127]
	v_mfma_f32_16x16x32_bf16 v[120:123], v[166:169], v[190:193], v[120:123]
	v_mfma_f32_16x16x32_bf16 v[108:111], v[150:153], v[198:201], v[108:111]
	v_mfma_f32_16x16x32_bf16 v[104:107], v[166:169], v[198:201], v[104:107]
	v_mfma_f32_16x16x32_bf16 v[92:95], v[150:153], v[206:209], v[92:95]
	v_mfma_f32_16x16x32_bf16 v[88:91], v[166:169], v[206:209], v[88:91]
	v_mfma_f32_16x16x32_bf16 v[76:79], v[150:153], v[214:217], v[76:79]
	v_mfma_f32_16x16x32_bf16 v[72:75], v[166:169], v[214:217], v[72:75]
	s_setprio 0
	s_setprio 1
	v_mfma_f32_16x16x32_bf16 v[116:119], v[170:173], v[186:189], v[116:119]
	v_mfma_f32_16x16x32_bf16 v[112:115], v[178:181], v[186:189], v[112:115]
	v_mfma_f32_16x16x32_bf16 v[100:103], v[170:173], v[194:197], v[100:103]
	v_mfma_f32_16x16x32_bf16 v[96:99], v[178:181], v[194:197], v[96:99]
	v_mfma_f32_16x16x32_bf16 v[84:87], v[170:173], v[202:205], v[84:87]
	v_mfma_f32_16x16x32_bf16 v[80:83], v[178:181], v[202:205], v[80:83]
	v_mfma_f32_16x16x32_bf16 v[68:71], v[170:173], v[210:213], v[68:71]
	v_mfma_f32_16x16x32_bf16 v[64:67], v[178:181], v[210:213], v[64:67]
	v_mfma_f32_16x16x32_bf16 v[116:119], v[174:177], v[190:193], v[116:119]
	v_mfma_f32_16x16x32_bf16 v[112:115], v[182:185], v[190:193], v[112:115]
	v_mfma_f32_16x16x32_bf16 v[100:103], v[174:177], v[198:201], v[100:103]
	v_mfma_f32_16x16x32_bf16 v[96:99], v[182:185], v[198:201], v[96:99]
	v_mfma_f32_16x16x32_bf16 v[84:87], v[174:177], v[206:209], v[84:87]
	v_mfma_f32_16x16x32_bf16 v[80:83], v[182:185], v[206:209], v[80:83]
	v_mfma_f32_16x16x32_bf16 v[68:71], v[174:177], v[214:217], v[68:71]
	v_mfma_f32_16x16x32_bf16 v[64:67], v[182:185], v[214:217], v[64:67]
	s_setprio 0
	s_barrier
	s_add_i32 s0, s69, s42
	v_lshl_add_u64 v[218:219], s[34:35], 0, v[130:131]
	s_mov_b32 m0, s0
	ds_read_b128 v[186:189], v161 offset:16384
	ds_read_b128 v[190:193], v161 offset:17408
	ds_read_b128 v[194:197], v161 offset:18432
	ds_read_b128 v[198:201], v161 offset:19456
	ds_read_b128 v[202:205], v161 offset:20480
	ds_read_b128 v[206:209], v161 offset:21504
	ds_read_b128 v[210:213], v161 offset:22528
	ds_read_b128 v[214:217], v161 offset:23552
	global_load_lds_dwordx4 v[218:219], off
	s_add_i32 m0, s0, 0x2000
	s_add_u32 s38, s34, 0x100000
	v_lshl_add_u64 v[220:221], s[34:35], 0, v[134:135]
	s_addc_u32 s39, s35, 0
	s_add_i32 s0, s70, s42
	global_load_lds_dwordx4 v[220:221], off
	v_lshl_add_u64 v[222:223], s[38:39], 0, v[130:131]
	s_mov_b32 m0, s0
	v_lshl_add_u64 v[226:227], s[36:37], 0, v[132:133]
	global_load_lds_dwordx4 v[222:223], off
	v_lshl_add_u64 v[222:223], s[38:39], 0, v[134:135]
	s_add_i32 m0, s0, 0x2000
	s_nop 0
	global_load_lds_dwordx4 v[222:223], off
	v_lshl_add_u64 v[222:223], s[36:37], 0, v[128:129]
	s_mov_b32 m0, s43
	s_nop 0
	global_load_lds_dwordx4 v[222:223], off
	s_mov_b32 m0, s56
	s_nop 0
	global_load_lds_dwordx4 v[226:227], off
	s_waitcnt vmcnt(8)
	s_waitcnt lgkmcnt(0)
	s_barrier
; #define PG8_STAGE(bufoff, gbase, voff) do { _Pragma("unroll") for (int _i = 0; _i < 2; ++_i) \
;         __builtin_amdgcn_global_load_lds((const unsigned*)((const char*)(gbase) + (voff)[_i]), (LAS unsigned*)(lds + (bufoff) + ldsw + _i * 8192), 16, 0, 0); } while (0)
; #define PG8_LDA(dst, b, h) do { _Pragma("unroll") for (int m = 0; m < 4; ++m) _Pragma("unroll") for (int k = 0; k < 2; ++k) dst[m][k] = *(const LAS bf16x8*)(lds + PG8_SA(b, h) + aoff + m * 2048 + k * 1024); } while (0)
; #define PG8_LDB(dst, b, h) do { _Pragma("unroll") for (int n = 0; n < 2; ++n) _Pragma("unroll") for (int k = 0; k < 2; ++k) dst[n][k] = *(const LAS bf16x8*)(lds + PG8_SB(b, h) + boff + n * 2048 + k * 1024); } while (0)
; #define PG8_MMA(ai, bj, At, Bt) do { __builtin_amdgcn_s_setprio(1); _Pragma("unroll") for (int m = 0; m < 4; ++m) _Pragma("unroll") for (int n = 0; n < 2; ++n) _Pragma("unroll") for (int k = 0; k < 2; ++k) \
;         acc[ai][bj][m][n] = __builtin_amdgcn_mfma_f32_16x16x32_bf16(Bt[n][k], At[m][k], acc[ai][bj][m][n], 0, 0, 0); __builtin_amdgcn_s_setprio(0); } while (0)
; #define PG8_WAIT_V(n) asm volatile("s_waitcnt vmcnt(" #n ")" ::: "memory")
; #define PG8_WAIT_L(n) asm volatile("s_waitcnt lgkmcnt(" #n ")" ::: "memory")
; #define PG8_BAR __builtin_amdgcn_s_barrier()
; #define PG8_SCHED __builtin_amdgcn_sched_barrier(0)
; template <class Epi, class Sched>
; DI void gemm_phase(LAS unsigned char* lds, const Gemm g, const Sched& S, const Epi& E) {
;     ...
;       PG8_WAIT_V(8); PG8_WAIT_L(0); PG8_BAR; PG8_MMA(1, 0, At, B0); PG8_MMA(1, 1, At, B1); PG8_BAR; PG8_SCHED;
;       PG8_LDB(B0, 1, 0); PG8_LDB(B1, 1, 1); PG8_SCHED; PG8_LDA(At, 1, 0); PG8_STAGE(PG8_SA(0, 1), a2 + hstepA, voffA);
;       PG8_WAIT_V(8); PG8_WAIT_L(0); PG8_BAR; PG8_MMA(0, 0, At, B0); PG8_MMA(0, 1, At, B1); PG8_BAR; PG8_SCHED;
	s_setprio 1
	s_waitcnt lgkmcnt(0)
	v_mfma_f32_16x16x32_bf16 v[60:63], v[146:149], v[186:189], v[60:63]
	v_mfma_f32_16x16x32_bf16 v[56:59], v[154:157], v[186:189], v[56:59]
	v_mfma_f32_16x16x32_bf16 v[44:47], v[146:149], v[194:197], v[44:47]
	v_mfma_f32_16x16x32_bf16 v[40:43], v[154:157], v[194:197], v[40:43]
	v_mfma_f32_16x16x32_bf16 v[28:31], v[146:149], v[202:205], v[28:31]
	v_mfma_f32_16x16x32_bf16 v[24:27], v[154:157], v[202:205], v[24:27]
	v_mfma_f32_16x16x32_bf16 v[12:15], v[146:149], v[210:213], v[12:15]
	v_mfma_f32_16x16x32_bf16 v[8:11], v[154:157], v[210:213], v[8:11]
	v_mfma_f32_16x16x32_bf16 v[60:63], v[150:153], v[190:193], v[60:63]
	v_mfma_f32_16x16x32_bf16 v[56:59], v[166:169], v[190:193], v[56:59]
	v_mfma_f32_16x16x32_bf16 v[44:47], v[150:153], v[198:201], v[44:47]
	v_mfma_f32_16x16x32_bf16 v[40:43], v[166:169], v[198:201], v[40:43]
	v_mfma_f32_16x16x32_bf16 v[28:31], v[150:153], v[206:209], v[28:31]
	v_mfma_f32_16x16x32_bf16 v[24:27], v[166:169], v[206:209], v[24:27]
	v_mfma_f32_16x16x32_bf16 v[12:15], v[150:153], v[214:217], v[12:15]
	v_mfma_f32_16x16x32_bf16 v[8:11], v[166:169], v[214:217], v[8:11]
	s_setprio 0
	s_setprio 1
	v_mfma_f32_16x16x32_bf16 v[52:55], v[170:173], v[186:189], v[52:55]
	v_mfma_f32_16x16x32_bf16 v[48:51], v[178:181], v[186:189], v[48:51]
	v_mfma_f32_16x16x32_bf16 v[36:39], v[170:173], v[194:197], v[36:39]
	v_mfma_f32_16x16x32_bf16 v[32:35], v[178:181], v[194:197], v[32:35]
	v_mfma_f32_16x16x32_bf16 v[20:23], v[170:173], v[202:205], v[20:23]
	v_mfma_f32_16x16x32_bf16 v[16:19], v[178:181], v[202:205], v[16:19]
	v_mfma_f32_16x16x32_bf16 v[4:7], v[170:173], v[210:213], v[4:7]
	v_mfma_f32_16x16x32_bf16 v[0:3], v[178:181], v[210:213], v[0:3]
	v_mfma_f32_16x16x32_bf16 v[52:55], v[174:177], v[190:193], v[52:55]
	v_mfma_f32_16x16x32_bf16 v[48:51], v[182:185], v[190:193], v[48:51]
	v_mfma_f32_16x16x32_bf16 v[36:39], v[174:177], v[198:201], v[36:39]
	v_mfma_f32_16x16x32_bf16 v[32:35], v[182:185], v[198:201], v[32:35]
	v_mfma_f32_16x16x32_bf16 v[20:23], v[174:177], v[206:209], v[20:23]
	v_mfma_f32_16x16x32_bf16 v[16:19], v[182:185], v[206:209], v[16:19]
	v_mfma_f32_16x16x32_bf16 v[4:7], v[174:177], v[214:217], v[4:7]
	v_mfma_f32_16x16x32_bf16 v[0:3], v[182:185], v[214:217], v[0:3]
	s_setprio 0
	s_barrier
	s_add_i32 s0, 0, 0x18000
	v_add_u32_e32 v136, s0, v158
	s_add_i32 s1, 0, 0x1c000
	ds_read_b128 v[146:149], v136
	ds_read_b128 v[150:153], v136 offset:1024
	ds_read_b128 v[154:157], v136 offset:2048
	ds_read_b128 v[166:169], v136 offset:3072
	v_add_u32_e32 v136, s1, v158
	ds_read_b128 v[170:173], v136
	ds_read_b128 v[174:177], v136 offset:1024
	ds_read_b128 v[178:181], v136 offset:2048
	ds_read_b128 v[182:185], v136 offset:3072
	s_add_u32 s36, s36, 0x100000
	s_addc_u32 s37, s37, 0
	s_mov_b32 m0, s57
	v_lshl_add_u64 v[228:229], s[36:37], 0, v[128:129]
	ds_read_b128 v[186:189], v161 offset:32768
	ds_read_b128 v[190:193], v161 offset:33792
	ds_read_b128 v[194:197], v161 offset:34816
	ds_read_b128 v[198:201], v161 offset:35840
	ds_read_b128 v[202:205], v161 offset:36864
	ds_read_b128 v[206:209], v161 offset:37888
	ds_read_b128 v[210:213], v161 offset:38912
	ds_read_b128 v[214:217], v161 offset:39936
	global_load_lds_dwordx4 v[228:229], off
	v_lshl_add_u64 v[228:229], s[36:37], 0, v[132:133]
	s_mov_b32 m0, s60
	s_nop 0
	global_load_lds_dwordx4 v[228:229], off
	s_waitcnt vmcnt(8)
	s_waitcnt lgkmcnt(0)
	s_barrier
	s_setprio 1
	s_waitcnt lgkmcnt(0)
	v_mfma_f32_16x16x32_bf16 v[124:127], v[146:149], v[186:189], v[124:127]
	v_mfma_f32_16x16x32_bf16 v[120:123], v[154:157], v[186:189], v[120:123]
	v_mfma_f32_16x16x32_bf16 v[108:111], v[146:149], v[194:197], v[108:111]
	v_mfma_f32_16x16x32_bf16 v[104:107], v[154:157], v[194:197], v[104:107]
	v_mfma_f32_16x16x32_bf16 v[92:95], v[146:149], v[202:205], v[92:95]
	v_mfma_f32_16x16x32_bf16 v[88:91], v[154:157], v[202:205], v[88:91]
	v_mfma_f32_16x16x32_bf16 v[76:79], v[146:149], v[210:213], v[76:79]
	v_mfma_f32_16x16x32_bf16 v[72:75], v[154:157], v[210:213], v[72:75]
	v_mfma_f32_16x16x32_bf16 v[124:127], v[150:153], v[190:193], v[124:127]
	v_mfma_f32_16x16x32_bf16 v[120:123], v[166:169], v[190:193], v[120:123]
	v_mfma_f32_16x16x32_bf16 v[108:111], v[150:153], v[198:201], v[108:111]
	v_mfma_f32_16x16x32_bf16 v[104:107], v[166:169], v[198:201], v[104:107]
	v_mfma_f32_16x16x32_bf16 v[92:95], v[150:153], v[206:209], v[92:95]
	v_mfma_f32_16x16x32_bf16 v[88:91], v[166:169], v[206:209], v[88:91]
	v_mfma_f32_16x16x32_bf16 v[76:79], v[150:153], v[214:217], v[76:79]
	v_mfma_f32_16x16x32_bf16 v[72:75], v[166:169], v[214:217], v[72:75]
	s_setprio 0
	s_setprio 1
	v_mfma_f32_16x16x32_bf16 v[116:119], v[170:173], v[186:189], v[116:119]
	v_mfma_f32_16x16x32_bf16 v[112:115], v[178:181], v[186:189], v[112:115]
	v_mfma_f32_16x16x32_bf16 v[100:103], v[170:173], v[194:197], v[100:103]
	v_mfma_f32_16x16x32_bf16 v[96:99], v[178:181], v[194:197], v[96:99]
	v_mfma_f32_16x16x32_bf16 v[84:87], v[170:173], v[202:205], v[84:87]
	v_mfma_f32_16x16x32_bf16 v[80:83], v[178:181], v[202:205], v[80:83]
	v_mfma_f32_16x16x32_bf16 v[68:71], v[170:173], v[210:213], v[68:71]
	v_mfma_f32_16x16x32_bf16 v[64:67], v[178:181], v[210:213], v[64:67]
	v_mfma_f32_16x16x32_bf16 v[116:119], v[174:177], v[190:193], v[116:119]
	v_mfma_f32_16x16x32_bf16 v[112:115], v[182:185], v[190:193], v[112:115]
	v_mfma_f32_16x16x32_bf16 v[100:103], v[174:177], v[198:201], v[100:103]
	v_mfma_f32_16x16x32_bf16 v[96:99], v[182:185], v[198:201], v[96:99]
	v_mfma_f32_16x16x32_bf16 v[84:87], v[174:177], v[206:209], v[84:87]
	v_mfma_f32_16x16x32_bf16 v[80:83], v[182:185], v[206:209], v[80:83]
	v_mfma_f32_16x16x32_bf16 v[68:71], v[174:177], v[214:217], v[68:71]
	v_mfma_f32_16x16x32_bf16 v[64:67], v[182:185], v[214:217], v[64:67]
	s_setprio 0
	s_barrier
; #define PG8_STAGE(bufoff, gbase, voff) do { _Pragma("unroll") for (int _i = 0; _i < 2; ++_i) \
;         __builtin_amdgcn_global_load_lds((const unsigned*)((const char*)(gbase) + (voff)[_i]), (LAS unsigned*)(lds + (bufoff) + ldsw + _i * 8192), 16, 0, 0); } while (0)
; #define PG8_LDA(dst, b, h) do { _Pragma("unroll") for (int m = 0; m < 4; ++m) _Pragma("unroll") for (int k = 0; k < 2; ++k) dst[m][k] = *(const LAS bf16x8*)(lds + PG8_SA(b, h) + aoff + m * 2048 + k * 1024); } while (0)
; #define PG8_MMA(ai, bj, At, Bt) do { __builtin_amdgcn_s_setprio(1); _Pragma("unroll") for (int m = 0; m < 4; ++m) _Pragma("unroll") for (int n = 0; n < 2; ++n) _Pragma("unroll") for (int k = 0; k < 2; ++k) \
;         acc[ai][bj][m][n] = __builtin_amdgcn_mfma_f32_16x16x32_bf16(Bt[n][k], At[m][k], acc[ai][bj][m][n], 0, 0, 0); __builtin_amdgcn_s_setprio(0); } while (0)
; #define PG8_WAIT_V(n) asm volatile("s_waitcnt vmcnt(" #n ")" ::: "memory")
; #define PG8_WAIT_L(n) asm volatile("s_waitcnt lgkmcnt(" #n ")" ::: "memory")
; #define PG8_BAR __builtin_amdgcn_s_barrier()
; #define PG8_SCHED __builtin_amdgcn_sched_barrier(0)
; template <class Epi, class Sched>
; DI void gemm_phase(LAS unsigned char* lds, const Gemm g, const Sched& S, const Epi& E) {
;     ...
;     for (int t = 0; t < nt; t += 2) {
;       const bool last = (t == nt - 2);
;       const char* a1 = cA + (size_t)(t + 1) * kstep;
;       const char* a2 = last ? nA : cA + (size_t)(t + 2) * kstep; const char* b2 = last ? nB : cB + (size_t)(t + 2) * kstep;
;     ...
;       PG8_LDA(At, 1, 1); PG8_STAGE(PG8_SB(1, 0), b3, voffB); PG8_STAGE(PG8_SB(1, 1), b3 + hstepB, voffB); PG8_STAGE(PG8_SA(1, 0), a3, voffA);
;       PG8_WAIT_V(8); PG8_WAIT_L(0); PG8_BAR; PG8_MMA(1, 0, At, B0); PG8_MMA(1, 1, At, B1); PG8_BAR; PG8_SCHED;
;     }
	s_add_i32 s0, s0, s42
	v_lshl_add_u64 v[218:219], v[218:219], 0, s[12:13]
	s_mov_b32 m0, s0
	ds_read_b128 v[186:189], v161 offset:49152
	ds_read_b128 v[190:193], v161 offset:50176
	ds_read_b128 v[194:197], v161 offset:51200
	ds_read_b128 v[198:201], v161 offset:52224
	ds_read_b128 v[202:205], v161 offset:53248
	ds_read_b128 v[206:209], v161 offset:54272
	ds_read_b128 v[210:213], v161 offset:55296
	ds_read_b128 v[214:217], v161 offset:56320
	global_load_lds_dwordx4 v[218:219], off
	s_add_i32 m0, s0, 0x2000
	s_add_u32 s34, s34, 0x100080
	v_lshl_add_u64 v[218:219], v[220:221], 0, s[12:13]
	s_addc_u32 s35, s35, 0
	s_add_i32 s0, s1, s42
	global_load_lds_dwordx4 v[218:219], off
	v_lshl_add_u64 v[218:219], s[34:35], 0, v[130:131]
	s_mov_b32 m0, s0
	s_nop 0
	global_load_lds_dwordx4 v[218:219], off
	v_lshl_add_u64 v[218:219], s[34:35], 0, v[134:135]
	s_add_i32 m0, s0, 0x2000
	s_nop 0
	global_load_lds_dwordx4 v[218:219], off
	v_lshl_add_u64 v[218:219], v[222:223], 0, s[12:13]
	s_mov_b32 m0, s64
	s_nop 0
	global_load_lds_dwordx4 v[218:219], off
	v_lshl_add_u64 v[218:219], v[226:227], 0, s[12:13]
	s_mov_b32 m0, s65
	s_nop 0
	global_load_lds_dwordx4 v[218:219], off
	s_waitcnt vmcnt(8)
	s_waitcnt lgkmcnt(0)
	s_barrier
	s_setprio 1
	s_waitcnt lgkmcnt(0)
	v_mfma_f32_16x16x32_bf16 v[60:63], v[146:149], v[186:189], v[60:63]
	v_mfma_f32_16x16x32_bf16 v[56:59], v[154:157], v[186:189], v[56:59]
	v_mfma_f32_16x16x32_bf16 v[44:47], v[146:149], v[194:197], v[44:47]
	v_mfma_f32_16x16x32_bf16 v[40:43], v[154:157], v[194:197], v[40:43]
	v_mfma_f32_16x16x32_bf16 v[28:31], v[146:149], v[202:205], v[28:31]
	v_mfma_f32_16x16x32_bf16 v[24:27], v[154:157], v[202:205], v[24:27]
	v_mfma_f32_16x16x32_bf16 v[12:15], v[146:149], v[210:213], v[12:15]
	v_mfma_f32_16x16x32_bf16 v[8:11], v[154:157], v[210:213], v[8:11]
	v_mfma_f32_16x16x32_bf16 v[60:63], v[150:153], v[190:193], v[60:63]
	v_mfma_f32_16x16x32_bf16 v[56:59], v[166:169], v[190:193], v[56:59]
	v_mfma_f32_16x16x32_bf16 v[44:47], v[150:153], v[198:201], v[44:47]
	v_mfma_f32_16x16x32_bf16 v[40:43], v[166:169], v[198:201], v[40:43]
	v_mfma_f32_16x16x32_bf16 v[28:31], v[150:153], v[206:209], v[28:31]
	v_mfma_f32_16x16x32_bf16 v[24:27], v[166:169], v[206:209], v[24:27]
	v_mfma_f32_16x16x32_bf16 v[12:15], v[150:153], v[214:217], v[12:15]
	v_mfma_f32_16x16x32_bf16 v[8:11], v[166:169], v[214:217], v[8:11]
	s_setprio 0
	s_setprio 1
	v_mfma_f32_16x16x32_bf16 v[52:55], v[170:173], v[186:189], v[52:55]
	v_mfma_f32_16x16x32_bf16 v[48:51], v[178:181], v[186:189], v[48:51]
	v_mfma_f32_16x16x32_bf16 v[36:39], v[170:173], v[194:197], v[36:39]
	v_mfma_f32_16x16x32_bf16 v[32:35], v[178:181], v[194:197], v[32:35]
	v_mfma_f32_16x16x32_bf16 v[20:23], v[170:173], v[202:205], v[20:23]
	v_mfma_f32_16x16x32_bf16 v[16:19], v[178:181], v[202:205], v[16:19]
	v_mfma_f32_16x16x32_bf16 v[4:7], v[170:173], v[210:213], v[4:7]
	v_mfma_f32_16x16x32_bf16 v[0:3], v[178:181], v[210:213], v[0:3]
	v_mfma_f32_16x16x32_bf16 v[52:55], v[174:177], v[190:193], v[52:55]
	v_mfma_f32_16x16x32_bf16 v[48:51], v[182:185], v[190:193], v[48:51]
	v_mfma_f32_16x16x32_bf16 v[36:39], v[174:177], v[198:201], v[36:39]
	v_mfma_f32_16x16x32_bf16 v[32:35], v[182:185], v[198:201], v[32:35]
	v_mfma_f32_16x16x32_bf16 v[20:23], v[174:177], v[206:209], v[20:23]
	v_mfma_f32_16x16x32_bf16 v[16:19], v[182:185], v[206:209], v[16:19]
	v_mfma_f32_16x16x32_bf16 v[4:7], v[174:177], v[214:217], v[4:7]
	v_mfma_f32_16x16x32_bf16 v[0:3], v[182:185], v[214:217], v[0:3]
	s_setprio 0
	s_add_i32 s89, s89, 2
	s_add_u32 s87, s87, 0x100
	s_addc_u32 s88, s88, 0
	s_add_u32 s30, s30, 0x100
	s_addc_u32 s31, s31, 0
	s_cmp_gt_u32 s89, 61
	s_barrier
	s_cbranch_scc0 .LBB0_3087
	s_and_b64 vcc, exec, s[14:15]
	s_cbranch_vccz .LBB0_3090
	s_barrier

; #define PG8_STAGE(bufoff, gbase, voff) do { _Pragma("unroll") for (int _i = 0; _i < 2; ++_i) \
;         __builtin_amdgcn_global_load_lds((const unsigned*)((const char*)(gbase) + (voff)[_i]), (LAS unsigned*)(lds + (bufoff) + ldsw + _i * 8192), 16, 0, 0); } while (0)
; #define PG8_LDA(dst, b, h) do { _Pragma("unroll") for (int m = 0; m < 4; ++m) _Pragma("unroll") for (int k = 0; k < 2; ++k) dst[m][k] = *(const LAS bf16x8*)(lds + PG8_SA(b, h) + aoff + m * 2048 + k * 1024); } while (0)
; #define PG8_LDB(dst, b, h) do { _Pragma("unroll") for (int n = 0; n < 2; ++n) _Pragma("unroll") for (int k = 0; k < 2; ++k) dst[n][k] = *(const LAS bf16x8*)(lds + PG8_SB(b, h) + boff + n * 2048 + k * 1024); } while (0)
; #define PG8_MMA(ai, bj, At, Bt) do { __builtin_amdgcn_s_setprio(1); _Pragma("unroll") for (int m = 0; m < 4; ++m) _Pragma("unroll") for (int n = 0; n < 2; ++n) _Pragma("unroll") for (int k = 0; k < 2; ++k) \
;         acc[ai][bj][m][n] = __builtin_amdgcn_mfma_f32_16x16x32_bf16(Bt[n][k], At[m][k], acc[ai][bj][m][n], 0, 0, 0); __builtin_amdgcn_s_setprio(0); } while (0)
; #define PG8_WAIT_V(n) asm volatile("s_waitcnt vmcnt(" #n ")" ::: "memory")
; #define PG8_WAIT_L(n) asm volatile("s_waitcnt lgkmcnt(" #n ")" ::: "memory")
; #define PG8_BAR __builtin_amdgcn_s_barrier()
; #define PG8_SCHED __builtin_amdgcn_sched_barrier(0)
; template <class Epi, class Sched>
; DI void gemm_phase(LAS unsigned char* lds, const Gemm g, const Sched& S, const Epi& E) {
;     ...
;     for (int t = 0; t < nt; t += 2) {
;       const bool last = (t == nt - 2);
;       const char* a1 = cA + (size_t)(t + 1) * kstep;
;       const char* a2 = last ? nA : cA + (size_t)(t + 2) * kstep; const char* b2 = last ? nB : cB + (size_t)(t + 2) * kstep;
;       const char* a3 = a2 + kstep; const char* b3 = b2 + kstep;
;       PG8_LDB(B0, 0, 0); PG8_LDB(B1, 0, 1); PG8_SCHED; PG8_LDA(At, 0, 0); PG8_STAGE(PG8_SA(1, 1), a1 + hstepA, voffA);
;       PG8_WAIT_V(8); PG8_WAIT_L(0); PG8_BAR; PG8_MMA(0, 0, At, B0); PG8_MMA(0, 1, At, B1); PG8_BAR; PG8_SCHED;
;       PG8_LDA(At, 0, 1); PG8_STAGE(PG8_SB(0, 0), b2, voffB); PG8_STAGE(PG8_SB(0, 1), b2 + hstepB, voffB); PG8_STAGE(PG8_SA(0, 0), a2, voffA);
;       PG8_WAIT_V(8); PG8_WAIT_L(0); PG8_BAR; PG8_MMA(1, 0, At, B0); PG8_MMA(1, 1, At, B1); PG8_BAR; PG8_SCHED;
.LBB0_3779:
	ds_read_b128 v[152:155], v147
	ds_read_b128 v[156:159], v147 offset:1024
	ds_read_b128 v[160:163], v147 offset:2048
	ds_read_b128 v[164:167], v147 offset:3072
	ds_read_b128 v[168:171], v148
	ds_read_b128 v[172:175], v148 offset:1024
	ds_read_b128 v[176:179], v148 offset:2048
	ds_read_b128 v[180:183], v148 offset:3072
	s_add_u32 s0, s24, 0xfffc0080
	s_addc_u32 s1, s25, -1
	s_cmp_eq_u32 s64, 12
	s_cselect_b32 s29, s15, s1
	s_cselect_b32 s28, s60, s0
	s_cselect_b32 s27, s13, s63
	s_cselect_b32 s26, s61, s62
	v_lshl_add_u64 v[144:145], s[24:25], 0, v[138:139]
	s_add_i32 m0, s23, 0xc000
	ds_read_b128 v[184:187], v149
	ds_read_b128 v[188:191], v149 offset:1024
	ds_read_b128 v[192:195], v149 offset:2048
	ds_read_b128 v[196:199], v149 offset:3072
	ds_read_b128 v[200:203], v149 offset:4096
	ds_read_b128 v[204:207], v149 offset:5120
	ds_read_b128 v[208:211], v149 offset:6144
	ds_read_b128 v[212:215], v149 offset:7168
	global_load_lds_dwordx4 v[144:145], off
	v_lshl_add_u64 v[144:145], s[24:25], 0, v[136:137]
	s_add_i32 m0, s23, 0xe000
	s_nop 0
	global_load_lds_dwordx4 v[144:145], off
	s_waitcnt vmcnt(8)
	s_waitcnt lgkmcnt(0)
	s_barrier
	s_setprio 1
	s_waitcnt lgkmcnt(0)
	v_mfma_f32_16x16x32_bf16 v[124:127], v[152:155], v[184:187], v[124:127]
	v_mfma_f32_16x16x32_bf16 v[120:123], v[160:163], v[184:187], v[120:123]
	v_mfma_f32_16x16x32_bf16 v[108:111], v[152:155], v[192:195], v[108:111]
	v_mfma_f32_16x16x32_bf16 v[104:107], v[160:163], v[192:195], v[104:107]
	v_mfma_f32_16x16x32_bf16 v[92:95], v[152:155], v[200:203], v[92:95]
	v_mfma_f32_16x16x32_bf16 v[88:91], v[160:163], v[200:203], v[88:91]
	v_mfma_f32_16x16x32_bf16 v[76:79], v[152:155], v[208:211], v[76:79]
	v_mfma_f32_16x16x32_bf16 v[72:75], v[160:163], v[208:211], v[72:75]
	v_mfma_f32_16x16x32_bf16 v[124:127], v[156:159], v[188:191], v[124:127]
	v_mfma_f32_16x16x32_bf16 v[120:123], v[164:167], v[188:191], v[120:123]
	v_mfma_f32_16x16x32_bf16 v[108:111], v[156:159], v[196:199], v[108:111]
	v_mfma_f32_16x16x32_bf16 v[104:107], v[164:167], v[196:199], v[104:107]
	v_mfma_f32_16x16x32_bf16 v[92:95], v[156:159], v[204:207], v[92:95]
	v_mfma_f32_16x16x32_bf16 v[88:91], v[164:167], v[204:207], v[88:91]
	v_mfma_f32_16x16x32_bf16 v[76:79], v[156:159], v[212:215], v[76:79]
	v_mfma_f32_16x16x32_bf16 v[72:75], v[164:167], v[212:215], v[72:75]
	s_setprio 0
	s_setprio 1
	v_mfma_f32_16x16x32_bf16 v[116:119], v[168:171], v[184:187], v[116:119]
	v_mfma_f32_16x16x32_bf16 v[112:115], v[176:179], v[184:187], v[112:115]
	v_mfma_f32_16x16x32_bf16 v[100:103], v[168:171], v[192:195], v[100:103]
	v_mfma_f32_16x16x32_bf16 v[96:99], v[176:179], v[192:195], v[96:99]
	v_mfma_f32_16x16x32_bf16 v[84:87], v[168:171], v[200:203], v[84:87]
	v_mfma_f32_16x16x32_bf16 v[80:83], v[176:179], v[200:203], v[80:83]
	v_mfma_f32_16x16x32_bf16 v[68:71], v[168:171], v[208:211], v[68:71]
	v_mfma_f32_16x16x32_bf16 v[64:67], v[176:179], v[208:211], v[64:67]
	v_mfma_f32_16x16x32_bf16 v[116:119], v[172:175], v[188:191], v[116:119]
	v_mfma_f32_16x16x32_bf16 v[112:115], v[180:183], v[188:191], v[112:115]
	v_mfma_f32_16x16x32_bf16 v[100:103], v[172:175], v[196:199], v[100:103]
	v_mfma_f32_16x16x32_bf16 v[96:99], v[180:183], v[196:199], v[96:99]
	v_mfma_f32_16x16x32_bf16 v[84:87], v[172:175], v[204:207], v[84:87]
	v_mfma_f32_16x16x32_bf16 v[80:83], v[180:183], v[204:207], v[80:83]
	v_mfma_f32_16x16x32_bf16 v[68:71], v[172:175], v[212:215], v[68:71]
	v_mfma_f32_16x16x32_bf16 v[64:67], v[180:183], v[212:215], v[64:67]
	s_setprio 0
	s_barrier
	s_add_i32 s0, s55, s17
	v_lshl_add_u64 v[144:145], s[26:27], 0, v[132:133]
	s_mov_b32 m0, s0
	ds_read_b128 v[184:187], v149 offset:16384
	ds_read_b128 v[188:191], v149 offset:17408
	ds_read_b128 v[192:195], v149 offset:18432
	ds_read_b128 v[196:199], v149 offset:19456
	ds_read_b128 v[200:203], v149 offset:20480
	ds_read_b128 v[204:207], v149 offset:21504
	ds_read_b128 v[208:211], v149 offset:22528
	ds_read_b128 v[212:215], v149 offset:23552
	global_load_lds_dwordx4 v[144:145], off
	s_add_i32 m0, s0, 0x2000
	s_add_u32 s66, s26, 0x40000
	v_lshl_add_u64 v[216:217], s[26:27], 0, v[128:129]
	s_addc_u32 s67, s27, 0
	s_add_i32 s0, s56, s17
	global_load_lds_dwordx4 v[216:217], off
	v_lshl_add_u64 v[218:219], s[66:67], 0, v[132:133]
	s_mov_b32 m0, s0
	v_lshl_add_u64 v[220:221], s[28:29], 0, v[130:131]
	global_load_lds_dwordx4 v[218:219], off
	v_lshl_add_u64 v[218:219], s[66:67], 0, v[128:129]
	s_add_i32 m0, s0, 0x2000
	s_nop 0
	global_load_lds_dwordx4 v[218:219], off
	v_lshl_add_u64 v[218:219], s[28:29], 0, v[134:135]
	s_mov_b32 m0, s23
	s_nop 0
	global_load_lds_dwordx4 v[218:219], off
	s_mov_b32 m0, s33
	s_nop 0
	global_load_lds_dwordx4 v[220:221], off
	s_waitcnt vmcnt(8)
	s_waitcnt lgkmcnt(0)
	s_barrier
; #define PG8_STAGE(bufoff, gbase, voff) do { _Pragma("unroll") for (int _i = 0; _i < 2; ++_i) \
;         __builtin_amdgcn_global_load_lds((const unsigned*)((const char*)(gbase) + (voff)[_i]), (LAS unsigned*)(lds + (bufoff) + ldsw + _i * 8192), 16, 0, 0); } while (0)
; #define PG8_LDA(dst, b, h) do { _Pragma("unroll") for (int m = 0; m < 4; ++m) _Pragma("unroll") for (int k = 0; k < 2; ++k) dst[m][k] = *(const LAS bf16x8*)(lds + PG8_SA(b, h) + aoff + m * 2048 + k * 1024); } while (0)
; #define PG8_LDB(dst, b, h) do { _Pragma("unroll") for (int n = 0; n < 2; ++n) _Pragma("unroll") for (int k = 0; k < 2; ++k) dst[n][k] = *(const LAS bf16x8*)(lds + PG8_SB(b, h) + boff + n * 2048 + k * 1024); } while (0)
; #define PG8_MMA(ai, bj, At, Bt) do { __builtin_amdgcn_s_setprio(1); _Pragma("unroll") for (int m = 0; m < 4; ++m) _Pragma("unroll") for (int n = 0; n < 2; ++n) _Pragma("unroll") for (int k = 0; k < 2; ++k) \
;         acc[ai][bj][m][n] = __builtin_amdgcn_mfma_f32_16x16x32_bf16(Bt[n][k], At[m][k], acc[ai][bj][m][n], 0, 0, 0); __builtin_amdgcn_s_setprio(0); } while (0)
; #define PG8_WAIT_V(n) asm volatile("s_waitcnt vmcnt(" #n ")" ::: "memory")
; #define PG8_WAIT_L(n) asm volatile("s_waitcnt lgkmcnt(" #n ")" ::: "memory")
; #define PG8_BAR __builtin_amdgcn_s_barrier()
; #define PG8_SCHED __builtin_amdgcn_sched_barrier(0)
; template <class Epi, class Sched>
; DI void gemm_phase(LAS unsigned char* lds, const Gemm g, const Sched& S, const Epi& E) {
;     ...
;       PG8_WAIT_V(8); PG8_WAIT_L(0); PG8_BAR; PG8_MMA(1, 0, At, B0); PG8_MMA(1, 1, At, B1); PG8_BAR; PG8_SCHED;
;       PG8_LDB(B0, 1, 0); PG8_LDB(B1, 1, 1); PG8_SCHED; PG8_LDA(At, 1, 0); PG8_STAGE(PG8_SA(0, 1), a2 + hstepA, voffA);
;       PG8_WAIT_V(8); PG8_WAIT_L(0); PG8_BAR; PG8_MMA(0, 0, At, B0); PG8_MMA(0, 1, At, B1); PG8_BAR; PG8_SCHED;
	s_setprio 1
	s_waitcnt lgkmcnt(0)
	v_mfma_f32_16x16x32_bf16 v[60:63], v[152:155], v[184:187], v[60:63]
	v_mfma_f32_16x16x32_bf16 v[56:59], v[160:163], v[184:187], v[56:59]
	v_mfma_f32_16x16x32_bf16 v[44:47], v[152:155], v[192:195], v[44:47]
	v_mfma_f32_16x16x32_bf16 v[40:43], v[160:163], v[192:195], v[40:43]
	v_mfma_f32_16x16x32_bf16 v[28:31], v[152:155], v[200:203], v[28:31]
	v_mfma_f32_16x16x32_bf16 v[24:27], v[160:163], v[200:203], v[24:27]
	v_mfma_f32_16x16x32_bf16 v[12:15], v[152:155], v[208:211], v[12:15]
	v_mfma_f32_16x16x32_bf16 v[8:11], v[160:163], v[208:211], v[8:11]
	v_mfma_f32_16x16x32_bf16 v[60:63], v[156:159], v[188:191], v[60:63]
	v_mfma_f32_16x16x32_bf16 v[56:59], v[164:167], v[188:191], v[56:59]
	v_mfma_f32_16x16x32_bf16 v[44:47], v[156:159], v[196:199], v[44:47]
	v_mfma_f32_16x16x32_bf16 v[40:43], v[164:167], v[196:199], v[40:43]
	v_mfma_f32_16x16x32_bf16 v[28:31], v[156:159], v[204:207], v[28:31]
	v_mfma_f32_16x16x32_bf16 v[24:27], v[164:167], v[204:207], v[24:27]
	v_mfma_f32_16x16x32_bf16 v[12:15], v[156:159], v[212:215], v[12:15]
	v_mfma_f32_16x16x32_bf16 v[8:11], v[164:167], v[212:215], v[8:11]
	s_setprio 0
	s_setprio 1
	v_mfma_f32_16x16x32_bf16 v[52:55], v[168:171], v[184:187], v[52:55]
	v_mfma_f32_16x16x32_bf16 v[48:51], v[176:179], v[184:187], v[48:51]
	v_mfma_f32_16x16x32_bf16 v[36:39], v[168:171], v[192:195], v[36:39]
	v_mfma_f32_16x16x32_bf16 v[32:35], v[176:179], v[192:195], v[32:35]
	v_mfma_f32_16x16x32_bf16 v[20:23], v[168:171], v[200:203], v[20:23]
	v_mfma_f32_16x16x32_bf16 v[16:19], v[176:179], v[200:203], v[16:19]
	v_mfma_f32_16x16x32_bf16 v[4:7], v[168:171], v[208:211], v[4:7]
	v_mfma_f32_16x16x32_bf16 v[0:3], v[176:179], v[208:211], v[0:3]
	v_mfma_f32_16x16x32_bf16 v[52:55], v[172:175], v[188:191], v[52:55]
	v_mfma_f32_16x16x32_bf16 v[48:51], v[180:183], v[188:191], v[48:51]
	v_mfma_f32_16x16x32_bf16 v[36:39], v[172:175], v[196:199], v[36:39]
	v_mfma_f32_16x16x32_bf16 v[32:35], v[180:183], v[196:199], v[32:35]
	v_mfma_f32_16x16x32_bf16 v[20:23], v[172:175], v[204:207], v[20:23]
	v_mfma_f32_16x16x32_bf16 v[16:19], v[180:183], v[204:207], v[16:19]
	v_mfma_f32_16x16x32_bf16 v[4:7], v[172:175], v[212:215], v[4:7]
	v_mfma_f32_16x16x32_bf16 v[0:3], v[180:183], v[212:215], v[0:3]
	s_setprio 0
	s_barrier
	s_add_i32 s0, 0, 0x18000
	v_add_u32_e32 v151, s0, v146
	s_add_i32 s1, 0, 0x1c000
	ds_read_b128 v[152:155], v151
	ds_read_b128 v[156:159], v151 offset:1024
	ds_read_b128 v[160:163], v151 offset:2048
	ds_read_b128 v[164:167], v151 offset:3072
	v_add_u32_e32 v151, s1, v146
	ds_read_b128 v[168:171], v151
	ds_read_b128 v[172:175], v151 offset:1024
	ds_read_b128 v[176:179], v151 offset:2048
	ds_read_b128 v[180:183], v151 offset:3072
	s_add_u32 s28, s28, 0x40000
	s_addc_u32 s29, s29, 0
	s_mov_b32 m0, s34
	v_lshl_add_u64 v[222:223], s[28:29], 0, v[134:135]
	ds_read_b128 v[184:187], v149 offset:32768
	ds_read_b128 v[188:191], v149 offset:33792
	ds_read_b128 v[192:195], v149 offset:34816
	ds_read_b128 v[196:199], v149 offset:35840
	ds_read_b128 v[200:203], v149 offset:36864
	ds_read_b128 v[204:207], v149 offset:37888
	ds_read_b128 v[208:211], v149 offset:38912
	ds_read_b128 v[212:215], v149 offset:39936
	global_load_lds_dwordx4 v[222:223], off
	v_lshl_add_u64 v[222:223], s[28:29], 0, v[130:131]
	s_mov_b32 m0, s35
	s_nop 0
	global_load_lds_dwordx4 v[222:223], off
	s_waitcnt vmcnt(8)
	s_waitcnt lgkmcnt(0)
	s_barrier
	s_setprio 1
	s_waitcnt lgkmcnt(0)
	v_mfma_f32_16x16x32_bf16 v[124:127], v[152:155], v[184:187], v[124:127]
	v_mfma_f32_16x16x32_bf16 v[120:123], v[160:163], v[184:187], v[120:123]
	v_mfma_f32_16x16x32_bf16 v[108:111], v[152:155], v[192:195], v[108:111]
	v_mfma_f32_16x16x32_bf16 v[104:107], v[160:163], v[192:195], v[104:107]
	v_mfma_f32_16x16x32_bf16 v[92:95], v[152:155], v[200:203], v[92:95]
	v_mfma_f32_16x16x32_bf16 v[88:91], v[160:163], v[200:203], v[88:91]
	v_mfma_f32_16x16x32_bf16 v[76:79], v[152:155], v[208:211], v[76:79]
	v_mfma_f32_16x16x32_bf16 v[72:75], v[160:163], v[208:211], v[72:75]
	v_mfma_f32_16x16x32_bf16 v[124:127], v[156:159], v[188:191], v[124:127]
	v_mfma_f32_16x16x32_bf16 v[120:123], v[164:167], v[188:191], v[120:123]
	v_mfma_f32_16x16x32_bf16 v[108:111], v[156:159], v[196:199], v[108:111]
	v_mfma_f32_16x16x32_bf16 v[104:107], v[164:167], v[196:199], v[104:107]
	v_mfma_f32_16x16x32_bf16 v[92:95], v[156:159], v[204:207], v[92:95]
	v_mfma_f32_16x16x32_bf16 v[88:91], v[164:167], v[204:207], v[88:91]
	v_mfma_f32_16x16x32_bf16 v[76:79], v[156:159], v[212:215], v[76:79]
	v_mfma_f32_16x16x32_bf16 v[72:75], v[164:167], v[212:215], v[72:75]
	s_setprio 0
	s_setprio 1
	v_mfma_f32_16x16x32_bf16 v[116:119], v[168:171], v[184:187], v[116:119]
	v_mfma_f32_16x16x32_bf16 v[112:115], v[176:179], v[184:187], v[112:115]
	v_mfma_f32_16x16x32_bf16 v[100:103], v[168:171], v[192:195], v[100:103]
	v_mfma_f32_16x16x32_bf16 v[96:99], v[176:179], v[192:195], v[96:99]
	v_mfma_f32_16x16x32_bf16 v[84:87], v[168:171], v[200:203], v[84:87]
	v_mfma_f32_16x16x32_bf16 v[80:83], v[176:179], v[200:203], v[80:83]
	v_mfma_f32_16x16x32_bf16 v[68:71], v[168:171], v[208:211], v[68:71]
	v_mfma_f32_16x16x32_bf16 v[64:67], v[176:179], v[208:211], v[64:67]
	v_mfma_f32_16x16x32_bf16 v[116:119], v[172:175], v[188:191], v[116:119]
	v_mfma_f32_16x16x32_bf16 v[112:115], v[180:183], v[188:191], v[112:115]
	v_mfma_f32_16x16x32_bf16 v[100:103], v[172:175], v[196:199], v[100:103]
	v_mfma_f32_16x16x32_bf16 v[96:99], v[180:183], v[196:199], v[96:99]
	v_mfma_f32_16x16x32_bf16 v[84:87], v[172:175], v[204:207], v[84:87]
	v_mfma_f32_16x16x32_bf16 v[80:83], v[180:183], v[204:207], v[80:83]
	v_mfma_f32_16x16x32_bf16 v[68:71], v[172:175], v[212:215], v[68:71]
	v_mfma_f32_16x16x32_bf16 v[64:67], v[180:183], v[212:215], v[64:67]
	s_setprio 0
	s_barrier
; #define PG8_STAGE(bufoff, gbase, voff) do { _Pragma("unroll") for (int _i = 0; _i < 2; ++_i) \
;         __builtin_amdgcn_global_load_lds((const unsigned*)((const char*)(gbase) + (voff)[_i]), (LAS unsigned*)(lds + (bufoff) + ldsw + _i * 8192), 16, 0, 0); } while (0)
; #define PG8_LDA(dst, b, h) do { _Pragma("unroll") for (int m = 0; m < 4; ++m) _Pragma("unroll") for (int k = 0; k < 2; ++k) dst[m][k] = *(const LAS bf16x8*)(lds + PG8_SA(b, h) + aoff + m * 2048 + k * 1024); } while (0)
; #define PG8_MMA(ai, bj, At, Bt) do { __builtin_amdgcn_s_setprio(1); _Pragma("unroll") for (int m = 0; m < 4; ++m) _Pragma("unroll") for (int n = 0; n < 2; ++n) _Pragma("unroll") for (int k = 0; k < 2; ++k) \
;         acc[ai][bj][m][n] = __builtin_amdgcn_mfma_f32_16x16x32_bf16(Bt[n][k], At[m][k], acc[ai][bj][m][n], 0, 0, 0); __builtin_amdgcn_s_setprio(0); } while (0)
; #define PG8_WAIT_V(n) asm volatile("s_waitcnt vmcnt(" #n ")" ::: "memory")
; #define PG8_WAIT_L(n) asm volatile("s_waitcnt lgkmcnt(" #n ")" ::: "memory")
; #define PG8_BAR __builtin_amdgcn_s_barrier()
; #define PG8_SCHED __builtin_amdgcn_sched_barrier(0)
; template <class Epi, class Sched>
; DI void gemm_phase(LAS unsigned char* lds, const Gemm g, const Sched& S, const Epi& E) {
;     ...
;     for (int t = 0; t < nt; t += 2) {
;       const bool last = (t == nt - 2);
;       const char* a1 = cA + (size_t)(t + 1) * kstep;
;       const char* a2 = last ? nA : cA + (size_t)(t + 2) * kstep; const char* b2 = last ? nB : cB + (size_t)(t + 2) * kstep;
;     ...
;       PG8_LDA(At, 1, 1); PG8_STAGE(PG8_SB(1, 0), b3, voffB); PG8_STAGE(PG8_SB(1, 1), b3 + hstepB, voffB); PG8_STAGE(PG8_SA(1, 0), a3, voffA);
;       PG8_WAIT_V(8); PG8_WAIT_L(0); PG8_BAR; PG8_MMA(1, 0, At, B0); PG8_MMA(1, 1, At, B1); PG8_BAR; PG8_SCHED;
;     }
	s_add_i32 s0, s0, s17
	v_lshl_add_u64 v[144:145], v[144:145], 0, s[8:9]
	s_mov_b32 m0, s0
	ds_read_b128 v[184:187], v149 offset:49152
	ds_read_b128 v[188:191], v149 offset:50176
	ds_read_b128 v[192:195], v149 offset:51200
	ds_read_b128 v[196:199], v149 offset:52224
	ds_read_b128 v[200:203], v149 offset:53248
	ds_read_b128 v[204:207], v149 offset:54272
	ds_read_b128 v[208:211], v149 offset:55296
	ds_read_b128 v[212:215], v149 offset:56320
	global_load_lds_dwordx4 v[144:145], off
	s_add_i32 m0, s0, 0x2000
	s_add_u32 s26, s26, 0x40080
	v_lshl_add_u64 v[144:145], v[216:217], 0, s[8:9]
	s_addc_u32 s27, s27, 0
	s_add_i32 s0, s1, s17
	global_load_lds_dwordx4 v[144:145], off
	v_lshl_add_u64 v[144:145], s[26:27], 0, v[132:133]
	s_mov_b32 m0, s0
	s_nop 0
	global_load_lds_dwordx4 v[144:145], off
	v_lshl_add_u64 v[144:145], s[26:27], 0, v[128:129]
	s_add_i32 m0, s0, 0x2000
	s_nop 0
	global_load_lds_dwordx4 v[144:145], off
	v_lshl_add_u64 v[144:145], v[218:219], 0, s[8:9]
	s_mov_b32 m0, s38
	s_nop 0
	global_load_lds_dwordx4 v[144:145], off
	v_lshl_add_u64 v[144:145], v[220:221], 0, s[8:9]
	s_mov_b32 m0, s42
	s_nop 0
	global_load_lds_dwordx4 v[144:145], off
	s_waitcnt vmcnt(8)
	s_waitcnt lgkmcnt(0)
	s_barrier
	s_setprio 1
	s_waitcnt lgkmcnt(0)
	v_mfma_f32_16x16x32_bf16 v[60:63], v[152:155], v[184:187], v[60:63]
	v_mfma_f32_16x16x32_bf16 v[56:59], v[160:163], v[184:187], v[56:59]
	v_mfma_f32_16x16x32_bf16 v[44:47], v[152:155], v[192:195], v[44:47]
	v_mfma_f32_16x16x32_bf16 v[40:43], v[160:163], v[192:195], v[40:43]
	v_mfma_f32_16x16x32_bf16 v[28:31], v[152:155], v[200:203], v[28:31]
	v_mfma_f32_16x16x32_bf16 v[24:27], v[160:163], v[200:203], v[24:27]
	v_mfma_f32_16x16x32_bf16 v[12:15], v[152:155], v[208:211], v[12:15]
	v_mfma_f32_16x16x32_bf16 v[8:11], v[160:163], v[208:211], v[8:11]
	v_mfma_f32_16x16x32_bf16 v[60:63], v[156:159], v[188:191], v[60:63]
	v_mfma_f32_16x16x32_bf16 v[56:59], v[164:167], v[188:191], v[56:59]
	v_mfma_f32_16x16x32_bf16 v[44:47], v[156:159], v[196:199], v[44:47]
	v_mfma_f32_16x16x32_bf16 v[40:43], v[164:167], v[196:199], v[40:43]
	v_mfma_f32_16x16x32_bf16 v[28:31], v[156:159], v[204:207], v[28:31]
	v_mfma_f32_16x16x32_bf16 v[24:27], v[164:167], v[204:207], v[24:27]
	v_mfma_f32_16x16x32_bf16 v[12:15], v[156:159], v[212:215], v[12:15]
	v_mfma_f32_16x16x32_bf16 v[8:11], v[164:167], v[212:215], v[8:11]
	s_setprio 0
	s_setprio 1
	v_mfma_f32_16x16x32_bf16 v[52:55], v[168:171], v[184:187], v[52:55]
	v_mfma_f32_16x16x32_bf16 v[48:51], v[176:179], v[184:187], v[48:51]
	v_mfma_f32_16x16x32_bf16 v[36:39], v[168:171], v[192:195], v[36:39]
	v_mfma_f32_16x16x32_bf16 v[32:35], v[176:179], v[192:195], v[32:35]
	v_mfma_f32_16x16x32_bf16 v[20:23], v[168:171], v[200:203], v[20:23]
	v_mfma_f32_16x16x32_bf16 v[16:19], v[176:179], v[200:203], v[16:19]
	v_mfma_f32_16x16x32_bf16 v[4:7], v[168:171], v[208:211], v[4:7]
	v_mfma_f32_16x16x32_bf16 v[0:3], v[176:179], v[208:211], v[0:3]
	v_mfma_f32_16x16x32_bf16 v[52:55], v[172:175], v[188:191], v[52:55]
	v_mfma_f32_16x16x32_bf16 v[48:51], v[180:183], v[188:191], v[48:51]
	v_mfma_f32_16x16x32_bf16 v[36:39], v[172:175], v[196:199], v[36:39]
	v_mfma_f32_16x16x32_bf16 v[32:35], v[180:183], v[196:199], v[32:35]
	v_mfma_f32_16x16x32_bf16 v[20:23], v[172:175], v[204:207], v[20:23]
	v_mfma_f32_16x16x32_bf16 v[16:19], v[180:183], v[204:207], v[16:19]
	v_mfma_f32_16x16x32_bf16 v[4:7], v[172:175], v[212:215], v[4:7]
	v_mfma_f32_16x16x32_bf16 v[0:3], v[180:183], v[212:215], v[0:3]
	s_setprio 0
	s_add_i32 s64, s64, 2
	s_add_u32 s62, s62, 0x100
	s_addc_u32 s63, s63, 0
	s_add_u32 s24, s24, 0x100
	s_addc_u32 s25, s25, 0
	s_cmp_gt_u32 s64, 13
	s_barrier
	s_cbranch_scc0 .LBB0_3779
	s_and_b64 vcc, exec, s[10:11]
	s_cbranch_vccz .LBB0_3782
	s_barrier

; #define PG8_STAGE(bufoff, gbase, voff) do { _Pragma("unroll") for (int _i = 0; _i < 2; ++_i) \
;         __builtin_amdgcn_global_load_lds((const unsigned*)((const char*)(gbase) + (voff)[_i]), (LAS unsigned*)(lds + (bufoff) + ldsw + _i * 8192), 16, 0, 0); } while (0)
; #define PG8_LDA(dst, b, h) do { _Pragma("unroll") for (int m = 0; m < 4; ++m) _Pragma("unroll") for (int k = 0; k < 2; ++k) dst[m][k] = *(const LAS bf16x8*)(lds + PG8_SA(b, h) + aoff + m * 2048 + k * 1024); } while (0)
; #define PG8_LDB(dst, b, h) do { _Pragma("unroll") for (int n = 0; n < 2; ++n) _Pragma("unroll") for (int k = 0; k < 2; ++k) dst[n][k] = *(const LAS bf16x8*)(lds + PG8_SB(b, h) + boff + n * 2048 + k * 1024); } while (0)
; #define PG8_MMA(ai, bj, At, Bt) do { __builtin_amdgcn_s_setprio(1); _Pragma("unroll") for (int m = 0; m < 4; ++m) _Pragma("unroll") for (int n = 0; n < 2; ++n) _Pragma("unroll") for (int k = 0; k < 2; ++k) \
;         acc[ai][bj][m][n] = __builtin_amdgcn_mfma_f32_16x16x32_bf16(Bt[n][k], At[m][k], acc[ai][bj][m][n], 0, 0, 0); __builtin_amdgcn_s_setprio(0); } while (0)
; #define PG8_WAIT_V(n) asm volatile("s_waitcnt vmcnt(" #n ")" ::: "memory")
; #define PG8_WAIT_L(n) asm volatile("s_waitcnt lgkmcnt(" #n ")" ::: "memory")
; #define PG8_BAR __builtin_amdgcn_s_barrier()
; #define PG8_SCHED __builtin_amdgcn_sched_barrier(0)
; template <class Epi, class Sched>
; DI void gemm_phase(LAS unsigned char* lds, const Gemm g, const Sched& S, const Epi& E) {
;     ...
;     for (int t = 0; t < nt; t += 2) {
;       const bool last = (t == nt - 2);
;       const char* a1 = cA + (size_t)(t + 1) * kstep;
;       const char* a2 = last ? nA : cA + (size_t)(t + 2) * kstep; const char* b2 = last ? nB : cB + (size_t)(t + 2) * kstep;
;       const char* a3 = a2 + kstep; const char* b3 = b2 + kstep;
;       PG8_LDB(B0, 0, 0); PG8_LDB(B1, 0, 1); PG8_SCHED; PG8_LDA(At, 0, 0); PG8_STAGE(PG8_SA(1, 1), a1 + hstepA, voffA);
;       PG8_WAIT_V(8); PG8_WAIT_L(0); PG8_BAR; PG8_MMA(0, 0, At, B0); PG8_MMA(0, 1, At, B1); PG8_BAR; PG8_SCHED;
;       PG8_LDA(At, 0, 1); PG8_STAGE(PG8_SB(0, 0), b2, voffB); PG8_STAGE(PG8_SB(0, 1), b2 + hstepB, voffB); PG8_STAGE(PG8_SA(0, 0), a2, voffA);
;       PG8_WAIT_V(8); PG8_WAIT_L(0); PG8_BAR; PG8_MMA(1, 0, At, B0); PG8_MMA(1, 1, At, B1); PG8_BAR; PG8_SCHED;
.LBB0_3856:
	ds_read_b128 v[146:149], v155
	ds_read_b128 v[150:153], v155 offset:1024
	ds_read_b128 v[162:165], v155 offset:2048
	ds_read_b128 v[166:169], v155 offset:3072
	ds_read_b128 v[170:173], v156
	ds_read_b128 v[174:177], v156 offset:1024
	ds_read_b128 v[178:181], v156 offset:2048
	ds_read_b128 v[182:185], v156 offset:3072
	s_add_u32 s26, s24, 0xfff00080
	s_addc_u32 s27, s25, -1
	s_cmp_eq_u32 s70, 60
	s_cselect_b32 s29, s5, s27
	s_cselect_b32 s28, s7, s26
	s_cselect_b32 s27, s17, s69
	s_cselect_b32 s26, s19, s68
	v_lshl_add_u64 v[218:219], s[24:25], 0, v[140:141]
	s_add_i32 m0, s35, 0xc000
	ds_read_b128 v[186:189], v157
	ds_read_b128 v[190:193], v157 offset:1024
	ds_read_b128 v[194:197], v157 offset:2048
	ds_read_b128 v[198:201], v157 offset:3072
	ds_read_b128 v[202:205], v157 offset:4096
	ds_read_b128 v[206:209], v157 offset:5120
	ds_read_b128 v[210:213], v157 offset:6144
	ds_read_b128 v[214:217], v157 offset:7168
	global_load_lds_dwordx4 v[218:219], off
	v_lshl_add_u64 v[218:219], s[24:25], 0, v[138:139]
	s_add_i32 m0, s35, 0xe000
	s_nop 0
	global_load_lds_dwordx4 v[218:219], off
	s_waitcnt vmcnt(8)
	s_waitcnt lgkmcnt(0)
	s_barrier
	s_setprio 1
	s_waitcnt lgkmcnt(0)
	v_mfma_f32_16x16x32_bf16 v[124:127], v[146:149], v[186:189], v[124:127]
	v_mfma_f32_16x16x32_bf16 v[120:123], v[162:165], v[186:189], v[120:123]
	v_mfma_f32_16x16x32_bf16 v[108:111], v[146:149], v[194:197], v[108:111]
	v_mfma_f32_16x16x32_bf16 v[104:107], v[162:165], v[194:197], v[104:107]
	v_mfma_f32_16x16x32_bf16 v[92:95], v[146:149], v[202:205], v[92:95]
	v_mfma_f32_16x16x32_bf16 v[88:91], v[162:165], v[202:205], v[88:91]
	v_mfma_f32_16x16x32_bf16 v[76:79], v[146:149], v[210:213], v[76:79]
	v_mfma_f32_16x16x32_bf16 v[72:75], v[162:165], v[210:213], v[72:75]
	v_mfma_f32_16x16x32_bf16 v[124:127], v[150:153], v[190:193], v[124:127]
	v_mfma_f32_16x16x32_bf16 v[120:123], v[166:169], v[190:193], v[120:123]
	v_mfma_f32_16x16x32_bf16 v[108:111], v[150:153], v[198:201], v[108:111]
	v_mfma_f32_16x16x32_bf16 v[104:107], v[166:169], v[198:201], v[104:107]
	v_mfma_f32_16x16x32_bf16 v[92:95], v[150:153], v[206:209], v[92:95]
	v_mfma_f32_16x16x32_bf16 v[88:91], v[166:169], v[206:209], v[88:91]
	v_mfma_f32_16x16x32_bf16 v[76:79], v[150:153], v[214:217], v[76:79]
	v_mfma_f32_16x16x32_bf16 v[72:75], v[166:169], v[214:217], v[72:75]
	s_setprio 0
	s_setprio 1
	v_mfma_f32_16x16x32_bf16 v[116:119], v[170:173], v[186:189], v[116:119]
	v_mfma_f32_16x16x32_bf16 v[112:115], v[178:181], v[186:189], v[112:115]
	v_mfma_f32_16x16x32_bf16 v[100:103], v[170:173], v[194:197], v[100:103]
	v_mfma_f32_16x16x32_bf16 v[96:99], v[178:181], v[194:197], v[96:99]
	v_mfma_f32_16x16x32_bf16 v[84:87], v[170:173], v[202:205], v[84:87]
	v_mfma_f32_16x16x32_bf16 v[80:83], v[178:181], v[202:205], v[80:83]
	v_mfma_f32_16x16x32_bf16 v[68:71], v[170:173], v[210:213], v[68:71]
	v_mfma_f32_16x16x32_bf16 v[64:67], v[178:181], v[210:213], v[64:67]
	v_mfma_f32_16x16x32_bf16 v[116:119], v[174:177], v[190:193], v[116:119]
	v_mfma_f32_16x16x32_bf16 v[112:115], v[182:185], v[190:193], v[112:115]
	v_mfma_f32_16x16x32_bf16 v[100:103], v[174:177], v[198:201], v[100:103]
	v_mfma_f32_16x16x32_bf16 v[96:99], v[182:185], v[198:201], v[96:99]
	v_mfma_f32_16x16x32_bf16 v[84:87], v[174:177], v[206:209], v[84:87]
	v_mfma_f32_16x16x32_bf16 v[80:83], v[182:185], v[206:209], v[80:83]
	v_mfma_f32_16x16x32_bf16 v[68:71], v[174:177], v[214:217], v[68:71]
	v_mfma_f32_16x16x32_bf16 v[64:67], v[182:185], v[214:217], v[64:67]
	s_setprio 0
	s_barrier
	s_add_i32 s71, s57, s31
	v_lshl_add_u64 v[218:219], s[26:27], 0, v[130:131]
	s_mov_b32 m0, s71
	ds_read_b128 v[186:189], v157 offset:16384
	ds_read_b128 v[190:193], v157 offset:17408
	ds_read_b128 v[194:197], v157 offset:18432
	ds_read_b128 v[198:201], v157 offset:19456
	ds_read_b128 v[202:205], v157 offset:20480
	ds_read_b128 v[206:209], v157 offset:21504
	ds_read_b128 v[210:213], v157 offset:22528
	ds_read_b128 v[214:217], v157 offset:23552
	global_load_lds_dwordx4 v[218:219], off
	s_add_i32 m0, s71, 0x2000
	s_add_u32 s72, s26, 0x100000
	v_lshl_add_u64 v[220:221], s[26:27], 0, v[134:135]
	s_addc_u32 s73, s27, 0
	s_add_i32 s71, s58, s31
	global_load_lds_dwordx4 v[220:221], off
	v_lshl_add_u64 v[222:223], s[72:73], 0, v[130:131]
	s_mov_b32 m0, s71
	v_lshl_add_u64 v[226:227], s[28:29], 0, v[132:133]
	global_load_lds_dwordx4 v[222:223], off
	v_lshl_add_u64 v[222:223], s[72:73], 0, v[134:135]
	s_add_i32 m0, s71, 0x2000
	s_nop 0
	global_load_lds_dwordx4 v[222:223], off
	v_lshl_add_u64 v[222:223], s[28:29], 0, v[128:129]
	s_mov_b32 m0, s35
	s_nop 0
	global_load_lds_dwordx4 v[222:223], off
	s_mov_b32 m0, s36
	s_nop 0
	global_load_lds_dwordx4 v[226:227], off
	s_waitcnt vmcnt(8)
	s_waitcnt lgkmcnt(0)
	s_barrier
; #define PG8_STAGE(bufoff, gbase, voff) do { _Pragma("unroll") for (int _i = 0; _i < 2; ++_i) \
;         __builtin_amdgcn_global_load_lds((const unsigned*)((const char*)(gbase) + (voff)[_i]), (LAS unsigned*)(lds + (bufoff) + ldsw + _i * 8192), 16, 0, 0); } while (0)
; #define PG8_LDA(dst, b, h) do { _Pragma("unroll") for (int m = 0; m < 4; ++m) _Pragma("unroll") for (int k = 0; k < 2; ++k) dst[m][k] = *(const LAS bf16x8*)(lds + PG8_SA(b, h) + aoff + m * 2048 + k * 1024); } while (0)
; #define PG8_LDB(dst, b, h) do { _Pragma("unroll") for (int n = 0; n < 2; ++n) _Pragma("unroll") for (int k = 0; k < 2; ++k) dst[n][k] = *(const LAS bf16x8*)(lds + PG8_SB(b, h) + boff + n * 2048 + k * 1024); } while (0)
; #define PG8_MMA(ai, bj, At, Bt) do { __builtin_amdgcn_s_setprio(1); _Pragma("unroll") for (int m = 0; m < 4; ++m) _Pragma("unroll") for (int n = 0; n < 2; ++n) _Pragma("unroll") for (int k = 0; k < 2; ++k) \
;         acc[ai][bj][m][n] = __builtin_amdgcn_mfma_f32_16x16x32_bf16(Bt[n][k], At[m][k], acc[ai][bj][m][n], 0, 0, 0); __builtin_amdgcn_s_setprio(0); } while (0)
; #define PG8_WAIT_V(n) asm volatile("s_waitcnt vmcnt(" #n ")" ::: "memory")
; #define PG8_WAIT_L(n) asm volatile("s_waitcnt lgkmcnt(" #n ")" ::: "memory")
; #define PG8_BAR __builtin_amdgcn_s_barrier()
; #define PG8_SCHED __builtin_amdgcn_sched_barrier(0)
; template <class Epi, class Sched>
; DI void gemm_phase(LAS unsigned char* lds, const Gemm g, const Sched& S, const Epi& E) {
;     ...
;       PG8_WAIT_V(8); PG8_WAIT_L(0); PG8_BAR; PG8_MMA(1, 0, At, B0); PG8_MMA(1, 1, At, B1); PG8_BAR; PG8_SCHED;
;       PG8_LDB(B0, 1, 0); PG8_LDB(B1, 1, 1); PG8_SCHED; PG8_LDA(At, 1, 0); PG8_STAGE(PG8_SA(0, 1), a2 + hstepA, voffA);
;       PG8_WAIT_V(8); PG8_WAIT_L(0); PG8_BAR; PG8_MMA(0, 0, At, B0); PG8_MMA(0, 1, At, B1); PG8_BAR; PG8_SCHED;
	s_setprio 1
	s_waitcnt lgkmcnt(0)
	v_mfma_f32_16x16x32_bf16 v[60:63], v[146:149], v[186:189], v[60:63]
	v_mfma_f32_16x16x32_bf16 v[56:59], v[162:165], v[186:189], v[56:59]
	v_mfma_f32_16x16x32_bf16 v[44:47], v[146:149], v[194:197], v[44:47]
	v_mfma_f32_16x16x32_bf16 v[40:43], v[162:165], v[194:197], v[40:43]
	v_mfma_f32_16x16x32_bf16 v[28:31], v[146:149], v[202:205], v[28:31]
	v_mfma_f32_16x16x32_bf16 v[24:27], v[162:165], v[202:205], v[24:27]
	v_mfma_f32_16x16x32_bf16 v[12:15], v[146:149], v[210:213], v[12:15]
	v_mfma_f32_16x16x32_bf16 v[8:11], v[162:165], v[210:213], v[8:11]
	v_mfma_f32_16x16x32_bf16 v[60:63], v[150:153], v[190:193], v[60:63]
	v_mfma_f32_16x16x32_bf16 v[56:59], v[166:169], v[190:193], v[56:59]
	v_mfma_f32_16x16x32_bf16 v[44:47], v[150:153], v[198:201], v[44:47]
	v_mfma_f32_16x16x32_bf16 v[40:43], v[166:169], v[198:201], v[40:43]
	v_mfma_f32_16x16x32_bf16 v[28:31], v[150:153], v[206:209], v[28:31]
	v_mfma_f32_16x16x32_bf16 v[24:27], v[166:169], v[206:209], v[24:27]
	v_mfma_f32_16x16x32_bf16 v[12:15], v[150:153], v[214:217], v[12:15]
	v_mfma_f32_16x16x32_bf16 v[8:11], v[166:169], v[214:217], v[8:11]
	s_setprio 0
	s_setprio 1
	v_mfma_f32_16x16x32_bf16 v[52:55], v[170:173], v[186:189], v[52:55]
	v_mfma_f32_16x16x32_bf16 v[48:51], v[178:181], v[186:189], v[48:51]
	v_mfma_f32_16x16x32_bf16 v[36:39], v[170:173], v[194:197], v[36:39]
	v_mfma_f32_16x16x32_bf16 v[32:35], v[178:181], v[194:197], v[32:35]
	v_mfma_f32_16x16x32_bf16 v[20:23], v[170:173], v[202:205], v[20:23]
	v_mfma_f32_16x16x32_bf16 v[16:19], v[178:181], v[202:205], v[16:19]
	v_mfma_f32_16x16x32_bf16 v[4:7], v[170:173], v[210:213], v[4:7]
	v_mfma_f32_16x16x32_bf16 v[0:3], v[178:181], v[210:213], v[0:3]
	v_mfma_f32_16x16x32_bf16 v[52:55], v[174:177], v[190:193], v[52:55]
	v_mfma_f32_16x16x32_bf16 v[48:51], v[182:185], v[190:193], v[48:51]
	v_mfma_f32_16x16x32_bf16 v[36:39], v[174:177], v[198:201], v[36:39]
	v_mfma_f32_16x16x32_bf16 v[32:35], v[182:185], v[198:201], v[32:35]
	v_mfma_f32_16x16x32_bf16 v[20:23], v[174:177], v[206:209], v[20:23]
	v_mfma_f32_16x16x32_bf16 v[16:19], v[182:185], v[206:209], v[16:19]
	v_mfma_f32_16x16x32_bf16 v[4:7], v[174:177], v[214:217], v[4:7]
	v_mfma_f32_16x16x32_bf16 v[0:3], v[182:185], v[214:217], v[0:3]
	s_setprio 0
	s_barrier
	s_add_i32 s71, 0, 0x18000
	v_add_u32_e32 v136, s71, v154
	s_add_i32 s72, 0, 0x1c000
	ds_read_b128 v[146:149], v136
	ds_read_b128 v[150:153], v136 offset:1024
	ds_read_b128 v[162:165], v136 offset:2048
	ds_read_b128 v[166:169], v136 offset:3072
	v_add_u32_e32 v136, s72, v154
	ds_read_b128 v[170:173], v136
	ds_read_b128 v[174:177], v136 offset:1024
	ds_read_b128 v[178:181], v136 offset:2048
	ds_read_b128 v[182:185], v136 offset:3072
	s_add_u32 s28, s28, 0x100000
	s_addc_u32 s29, s29, 0
	s_mov_b32 m0, s37
	v_lshl_add_u64 v[228:229], s[28:29], 0, v[128:129]
	ds_read_b128 v[186:189], v157 offset:32768
	ds_read_b128 v[190:193], v157 offset:33792
	ds_read_b128 v[194:197], v157 offset:34816
	ds_read_b128 v[198:201], v157 offset:35840
	ds_read_b128 v[202:205], v157 offset:36864
	ds_read_b128 v[206:209], v157 offset:37888
	ds_read_b128 v[210:213], v157 offset:38912
	ds_read_b128 v[214:217], v157 offset:39936
	global_load_lds_dwordx4 v[228:229], off
	v_lshl_add_u64 v[228:229], s[28:29], 0, v[132:133]
	s_mov_b32 m0, s38
	s_nop 0
	global_load_lds_dwordx4 v[228:229], off
	s_waitcnt vmcnt(8)
	s_waitcnt lgkmcnt(0)
	s_barrier
	s_setprio 1
	s_waitcnt lgkmcnt(0)
	v_mfma_f32_16x16x32_bf16 v[124:127], v[146:149], v[186:189], v[124:127]
	v_mfma_f32_16x16x32_bf16 v[120:123], v[162:165], v[186:189], v[120:123]
	v_mfma_f32_16x16x32_bf16 v[108:111], v[146:149], v[194:197], v[108:111]
	v_mfma_f32_16x16x32_bf16 v[104:107], v[162:165], v[194:197], v[104:107]
	v_mfma_f32_16x16x32_bf16 v[92:95], v[146:149], v[202:205], v[92:95]
	v_mfma_f32_16x16x32_bf16 v[88:91], v[162:165], v[202:205], v[88:91]
	v_mfma_f32_16x16x32_bf16 v[76:79], v[146:149], v[210:213], v[76:79]
	v_mfma_f32_16x16x32_bf16 v[72:75], v[162:165], v[210:213], v[72:75]
	v_mfma_f32_16x16x32_bf16 v[124:127], v[150:153], v[190:193], v[124:127]
	v_mfma_f32_16x16x32_bf16 v[120:123], v[166:169], v[190:193], v[120:123]
	v_mfma_f32_16x16x32_bf16 v[108:111], v[150:153], v[198:201], v[108:111]
	v_mfma_f32_16x16x32_bf16 v[104:107], v[166:169], v[198:201], v[104:107]
	v_mfma_f32_16x16x32_bf16 v[92:95], v[150:153], v[206:209], v[92:95]
	v_mfma_f32_16x16x32_bf16 v[88:91], v[166:169], v[206:209], v[88:91]
	v_mfma_f32_16x16x32_bf16 v[76:79], v[150:153], v[214:217], v[76:79]
	v_mfma_f32_16x16x32_bf16 v[72:75], v[166:169], v[214:217], v[72:75]
	s_setprio 0
	s_setprio 1
	v_mfma_f32_16x16x32_bf16 v[116:119], v[170:173], v[186:189], v[116:119]
	v_mfma_f32_16x16x32_bf16 v[112:115], v[178:181], v[186:189], v[112:115]
	v_mfma_f32_16x16x32_bf16 v[100:103], v[170:173], v[194:197], v[100:103]
	v_mfma_f32_16x16x32_bf16 v[96:99], v[178:181], v[194:197], v[96:99]
	v_mfma_f32_16x16x32_bf16 v[84:87], v[170:173], v[202:205], v[84:87]
	v_mfma_f32_16x16x32_bf16 v[80:83], v[178:181], v[202:205], v[80:83]
	v_mfma_f32_16x16x32_bf16 v[68:71], v[170:173], v[210:213], v[68:71]
	v_mfma_f32_16x16x32_bf16 v[64:67], v[178:181], v[210:213], v[64:67]
	v_mfma_f32_16x16x32_bf16 v[116:119], v[174:177], v[190:193], v[116:119]
	v_mfma_f32_16x16x32_bf16 v[112:115], v[182:185], v[190:193], v[112:115]
	v_mfma_f32_16x16x32_bf16 v[100:103], v[174:177], v[198:201], v[100:103]
	v_mfma_f32_16x16x32_bf16 v[96:99], v[182:185], v[198:201], v[96:99]
	v_mfma_f32_16x16x32_bf16 v[84:87], v[174:177], v[206:209], v[84:87]
	v_mfma_f32_16x16x32_bf16 v[80:83], v[182:185], v[206:209], v[80:83]
	v_mfma_f32_16x16x32_bf16 v[68:71], v[174:177], v[214:217], v[68:71]
	v_mfma_f32_16x16x32_bf16 v[64:67], v[182:185], v[214:217], v[64:67]
	s_setprio 0
	s_barrier
; #define PG8_STAGE(bufoff, gbase, voff) do { _Pragma("unroll") for (int _i = 0; _i < 2; ++_i) \
;         __builtin_amdgcn_global_load_lds((const unsigned*)((const char*)(gbase) + (voff)[_i]), (LAS unsigned*)(lds + (bufoff) + ldsw + _i * 8192), 16, 0, 0); } while (0)
; #define PG8_LDA(dst, b, h) do { _Pragma("unroll") for (int m = 0; m < 4; ++m) _Pragma("unroll") for (int k = 0; k < 2; ++k) dst[m][k] = *(const LAS bf16x8*)(lds + PG8_SA(b, h) + aoff + m * 2048 + k * 1024); } while (0)
; #define PG8_MMA(ai, bj, At, Bt) do { __builtin_amdgcn_s_setprio(1); _Pragma("unroll") for (int m = 0; m < 4; ++m) _Pragma("unroll") for (int n = 0; n < 2; ++n) _Pragma("unroll") for (int k = 0; k < 2; ++k) \
;         acc[ai][bj][m][n] = __builtin_amdgcn_mfma_f32_16x16x32_bf16(Bt[n][k], At[m][k], acc[ai][bj][m][n], 0, 0, 0); __builtin_amdgcn_s_setprio(0); } while (0)
; #define PG8_WAIT_V(n) asm volatile("s_waitcnt vmcnt(" #n ")" ::: "memory")
; #define PG8_WAIT_L(n) asm volatile("s_waitcnt lgkmcnt(" #n ")" ::: "memory")
; #define PG8_BAR __builtin_amdgcn_s_barrier()
; #define PG8_SCHED __builtin_amdgcn_sched_barrier(0)
; template <class Epi, class Sched>
; DI void gemm_phase(LAS unsigned char* lds, const Gemm g, const Sched& S, const Epi& E) {
;     ...
;     for (int t = 0; t < nt; t += 2) {
;       const bool last = (t == nt - 2);
;       const char* a1 = cA + (size_t)(t + 1) * kstep;
;       const char* a2 = last ? nA : cA + (size_t)(t + 2) * kstep; const char* b2 = last ? nB : cB + (size_t)(t + 2) * kstep;
;     ...
;       PG8_LDA(At, 1, 1); PG8_STAGE(PG8_SB(1, 0), b3, voffB); PG8_STAGE(PG8_SB(1, 1), b3 + hstepB, voffB); PG8_STAGE(PG8_SA(1, 0), a3, voffA);
;       PG8_WAIT_V(8); PG8_WAIT_L(0); PG8_BAR; PG8_MMA(1, 0, At, B0); PG8_MMA(1, 1, At, B1); PG8_BAR; PG8_SCHED;
;     }
	s_add_i32 s28, s71, s31
	v_lshl_add_u64 v[218:219], v[218:219], 0, s[10:11]
	s_mov_b32 m0, s28
	ds_read_b128 v[186:189], v157 offset:49152
	ds_read_b128 v[190:193], v157 offset:50176
	ds_read_b128 v[194:197], v157 offset:51200
	ds_read_b128 v[198:201], v157 offset:52224
	ds_read_b128 v[202:205], v157 offset:53248
	ds_read_b128 v[206:209], v157 offset:54272
	ds_read_b128 v[210:213], v157 offset:55296
	ds_read_b128 v[214:217], v157 offset:56320
	global_load_lds_dwordx4 v[218:219], off
	s_add_i32 m0, s28, 0x2000
	s_add_u32 s26, s26, 0x100080
	v_lshl_add_u64 v[218:219], v[220:221], 0, s[10:11]
	s_addc_u32 s27, s27, 0
	s_add_i32 s28, s72, s31
	global_load_lds_dwordx4 v[218:219], off
	v_lshl_add_u64 v[218:219], s[26:27], 0, v[130:131]
	s_mov_b32 m0, s28
	s_nop 0
	global_load_lds_dwordx4 v[218:219], off
	v_lshl_add_u64 v[218:219], s[26:27], 0, v[134:135]
	s_add_i32 m0, s28, 0x2000
	s_nop 0
	global_load_lds_dwordx4 v[218:219], off
	v_lshl_add_u64 v[218:219], v[222:223], 0, s[10:11]
	s_mov_b32 m0, s42
	s_nop 0
	global_load_lds_dwordx4 v[218:219], off
	v_lshl_add_u64 v[218:219], v[226:227], 0, s[10:11]
	s_mov_b32 m0, s43
	s_nop 0
	global_load_lds_dwordx4 v[218:219], off
	s_waitcnt vmcnt(8)
	s_waitcnt lgkmcnt(0)
	s_barrier
	s_setprio 1
	s_waitcnt lgkmcnt(0)
	v_mfma_f32_16x16x32_bf16 v[60:63], v[146:149], v[186:189], v[60:63]
	v_mfma_f32_16x16x32_bf16 v[56:59], v[162:165], v[186:189], v[56:59]
	v_mfma_f32_16x16x32_bf16 v[44:47], v[146:149], v[194:197], v[44:47]
	v_mfma_f32_16x16x32_bf16 v[40:43], v[162:165], v[194:197], v[40:43]
	v_mfma_f32_16x16x32_bf16 v[28:31], v[146:149], v[202:205], v[28:31]
	v_mfma_f32_16x16x32_bf16 v[24:27], v[162:165], v[202:205], v[24:27]
	v_mfma_f32_16x16x32_bf16 v[12:15], v[146:149], v[210:213], v[12:15]
	v_mfma_f32_16x16x32_bf16 v[8:11], v[162:165], v[210:213], v[8:11]
	v_mfma_f32_16x16x32_bf16 v[60:63], v[150:153], v[190:193], v[60:63]
	v_mfma_f32_16x16x32_bf16 v[56:59], v[166:169], v[190:193], v[56:59]
	v_mfma_f32_16x16x32_bf16 v[44:47], v[150:153], v[198:201], v[44:47]
	v_mfma_f32_16x16x32_bf16 v[40:43], v[166:169], v[198:201], v[40:43]
	v_mfma_f32_16x16x32_bf16 v[28:31], v[150:153], v[206:209], v[28:31]
	v_mfma_f32_16x16x32_bf16 v[24:27], v[166:169], v[206:209], v[24:27]
	v_mfma_f32_16x16x32_bf16 v[12:15], v[150:153], v[214:217], v[12:15]
	v_mfma_f32_16x16x32_bf16 v[8:11], v[166:169], v[214:217], v[8:11]
	s_setprio 0
	s_setprio 1
	v_mfma_f32_16x16x32_bf16 v[52:55], v[170:173], v[186:189], v[52:55]
	v_mfma_f32_16x16x32_bf16 v[48:51], v[178:181], v[186:189], v[48:51]
	v_mfma_f32_16x16x32_bf16 v[36:39], v[170:173], v[194:197], v[36:39]
	v_mfma_f32_16x16x32_bf16 v[32:35], v[178:181], v[194:197], v[32:35]
	v_mfma_f32_16x16x32_bf16 v[20:23], v[170:173], v[202:205], v[20:23]
	v_mfma_f32_16x16x32_bf16 v[16:19], v[178:181], v[202:205], v[16:19]
	v_mfma_f32_16x16x32_bf16 v[4:7], v[170:173], v[210:213], v[4:7]
	v_mfma_f32_16x16x32_bf16 v[0:3], v[178:181], v[210:213], v[0:3]
	v_mfma_f32_16x16x32_bf16 v[52:55], v[174:177], v[190:193], v[52:55]
	v_mfma_f32_16x16x32_bf16 v[48:51], v[182:185], v[190:193], v[48:51]
	v_mfma_f32_16x16x32_bf16 v[36:39], v[174:177], v[198:201], v[36:39]
	v_mfma_f32_16x16x32_bf16 v[32:35], v[182:185], v[198:201], v[32:35]
	v_mfma_f32_16x16x32_bf16 v[20:23], v[174:177], v[206:209], v[20:23]
	v_mfma_f32_16x16x32_bf16 v[16:19], v[182:185], v[206:209], v[16:19]
	v_mfma_f32_16x16x32_bf16 v[4:7], v[174:177], v[214:217], v[4:7]
	v_mfma_f32_16x16x32_bf16 v[0:3], v[182:185], v[214:217], v[0:3]
	s_setprio 0
	s_add_i32 s70, s70, 2
	s_add_u32 s68, s68, 0x100
	s_addc_u32 s69, s69, 0
	s_add_u32 s24, s24, 0x100
	s_addc_u32 s25, s25, 0
	s_cmp_gt_u32 s70, 61
	s_barrier
	s_cbranch_scc0 .LBB0_3856
	s_and_b64 vcc, exec, s[12:13]
	s_cbranch_vccz .LBB0_3859
	s_barrier
